# v3
# speedup vs baseline: 1.0115x; 1.0115x over previous
; #define STAGE(P, BASE, LD, br, kt) do { const char* _g = (const char*)((BASE) + (size_t)(br) * (LD) + (size_t)(kt) * 64); \
;     for (int _i = 0; _i < 2; ++_i) { int _b = tidx * 16 + _i * 8192; int _r, _c; stage_rc(_b, _r, _c); \
;       __builtin_amdgcn_global_load_lds((const unsigned*)(_g + (unsigned)((_r * (LD) + _c) * 2)), (unsigned*)((char*)(P) + _b), 16, 0, 0); } } while (0)
; #define LDA(dst, b, h) for (int m = 0; m < 4; ++m) for (int k = 0; k < 2; ++k) \
;     dst[m][k] = *reinterpret_cast<const bf16x8*>((char*)SA(b, h) + lds_byte(wr * 64 + m * 16 + fr, k * 32 + fq * 8))
; #define LDB(dst, b, h) for (int n = 0; n < 2; ++n) for (int k = 0; k < 2; ++k) \
;     dst[n][k] = *reinterpret_cast<const bf16x8*>((char*)SB(b, h) + lds_byte(wc * 32 + n * 16 + fr, k * 32 + fq * 8))
; #define MMA(ai, bj, At_, Bt_) do { __builtin_amdgcn_s_setprio(1); \
;     for (int k = 0; k < 2; ++k) for (int m = 0; m < 4; ++m) for (int n = 0; n < 2; ++n) \
;       acc[ai][bj][m][n] = __builtin_amdgcn_mfma_f32_16x16x32_bf16(At_[m][k], Bt_[n][k], acc[ai][bj][m][n], 0, 0, 0); \
;     __builtin_amdgcn_s_setprio(0); } while (0)
; #define WAIT_V(n) asm volatile("s_waitcnt vmcnt(" #n ")" ::: "memory")
; #define WAIT_L(n) asm volatile("s_waitcnt lgkmcnt(" #n ")" ::: "memory")
; #define BAR __builtin_amdgcn_s_barrier()
; #define SCHED __builtin_amdgcn_sched_barrier(0)
; template <int EPI, int lda, int ldb, int N, int K>
; __device__ __forceinline__ void gemm_phase(const u16* __restrict__ A, const u16* __restrict__ Bt, const GemmEpi ep, int wv) {
;     ...
;     for (int t = 0; t < nt - 2; t += 2) {
;       LDB(B0, 0, 0); SCHED; LDA(At, 0, 0); STAGE(SA(1, 1), Ab, lda, brow + HALF, t + 1);
;       WAIT_L(8); BAR; WAIT_L(0); MMA(0, 0, At, B0); BAR; SCHED;
;       LDB(B1, 0, 1); STAGE(SB(0, 0), Bt, ldb, bcol, t + 2);
;       BAR; WAIT_L(0); MMA(0, 1, At, B1); BAR;
;       LDA(At, 0, 1); STAGE(SA(0, 0), Ab, lda, brow, t + 2);
;       BAR; WAIT_L(0); MMA(1, 0, At, B0); BAR; SCHED;
;       STAGE(SB(0, 1), Bt, ldb, bcol + HALF, t + 2);
;       WAIT_V(6); BAR; MMA(1, 1, At, B1); BAR;
;       LDB(B0, 1, 0); SCHED; LDA(At, 1, 0); STAGE(SA(0, 1), Ab, lda, brow + HALF, t + 2);
;       WAIT_L(8); BAR; WAIT_L(0); MMA(0, 0, At, B0); BAR; SCHED;
.LBB0_53:
	ds_read_b128 v[172:175], v161
	ds_read_b128 v[176:179], v161 offset:1024
	ds_read_b128 v[180:183], v161 offset:2048
	ds_read_b128 v[184:187], v161 offset:3072
	v_add_u32_e32 v169, 0xc000, v148
	v_lshl_add_u64 v[236:237], v[136:137], 0, s[42:43]
	v_readfirstlane_b32 s45, v169
	v_add_u32_e32 v170, 0xe000, v148
	v_lshl_add_u64 v[162:163], v[236:237], 0, s[14:15]
	s_mov_b32 m0, s45
	v_lshl_add_u64 v[238:239], v[134:135], 0, s[42:43]
	v_readfirstlane_b32 s45, v170
	ds_read_b128 v[164:167], v152
	ds_read_b128 v[188:191], v152 offset:1024
	ds_read_b128 v[192:195], v151
	ds_read_b128 v[196:199], v151 offset:1024
	ds_read_b128 v[200:203], v150
	ds_read_b128 v[204:207], v150 offset:1024
	ds_read_b128 v[208:211], v149
	ds_read_b128 v[212:215], v149 offset:1024
	global_load_lds_dwordx4 v[162:163], off
	v_lshl_add_u64 v[162:163], v[238:239], 0, s[14:15]
	s_mov_b32 m0, s45
	s_nop 0
	global_load_lds_dwordx4 v[162:163], off
	s_waitcnt lgkmcnt(8)
	s_barrier
	s_waitcnt lgkmcnt(0)
	s_setprio 1
	s_waitcnt lgkmcnt(0)
	v_mfma_f32_16x16x32_bf16 v[124:127], v[172:175], v[164:167], v[124:127]
	v_mfma_f32_16x16x32_bf16 v[120:123], v[180:183], v[164:167], v[120:123]
	v_mfma_f32_16x16x32_bf16 v[116:119], v[172:175], v[192:195], v[116:119]
	v_mfma_f32_16x16x32_bf16 v[112:115], v[180:183], v[192:195], v[112:115]
	v_mfma_f32_16x16x32_bf16 v[108:111], v[172:175], v[200:203], v[108:111]
	v_mfma_f32_16x16x32_bf16 v[104:107], v[180:183], v[200:203], v[104:107]
	v_mfma_f32_16x16x32_bf16 v[100:103], v[172:175], v[208:211], v[100:103]
	v_mfma_f32_16x16x32_bf16 v[96:99], v[180:183], v[208:211], v[96:99]
	v_mfma_f32_16x16x32_bf16 v[124:127], v[176:179], v[188:191], v[124:127]
	v_mfma_f32_16x16x32_bf16 v[120:123], v[184:187], v[188:191], v[120:123]
	v_mfma_f32_16x16x32_bf16 v[116:119], v[176:179], v[196:199], v[116:119]
	v_mfma_f32_16x16x32_bf16 v[112:115], v[184:187], v[196:199], v[112:115]
	v_mfma_f32_16x16x32_bf16 v[108:111], v[176:179], v[204:207], v[108:111]
	v_mfma_f32_16x16x32_bf16 v[104:107], v[184:187], v[204:207], v[104:107]
	v_mfma_f32_16x16x32_bf16 v[100:103], v[176:179], v[212:215], v[100:103]
	v_mfma_f32_16x16x32_bf16 v[96:99], v[184:187], v[212:215], v[96:99]
	s_setprio 0
	s_barrier
	v_add_u32_e32 v162, s54, v153
	v_lshl_add_u64 v[240:241], v[140:141], 0, s[42:43]
	v_readfirstlane_b32 s45, v162
	v_add_u32_e32 v163, 0x2000, v162
	v_lshl_add_u64 v[232:233], v[240:241], 0, s[16:17]
	s_mov_b32 m0, s45
	v_lshl_add_u64 v[242:243], v[138:139], 0, s[42:43]
	v_readfirstlane_b32 s45, v163
	ds_read_b128 v[216:219], v160
	ds_read_b128 v[220:223], v160 offset:1024
	ds_read_b128 v[224:227], v160 offset:2048
	ds_read_b128 v[228:231], v160 offset:3072
	global_load_lds_dwordx4 v[232:233], off
	v_lshl_add_u64 v[232:233], v[242:243], 0, s[16:17]
	s_mov_b32 m0, s45
	s_nop 0
	global_load_lds_dwordx4 v[232:233], off
	s_barrier
	s_waitcnt lgkmcnt(0)
	s_setprio 1
	s_waitcnt lgkmcnt(0)
	v_mfma_f32_16x16x32_bf16 v[92:95], v[216:219], v[164:167], v[92:95]
	v_mfma_f32_16x16x32_bf16 v[88:91], v[224:227], v[164:167], v[88:91]
	v_mfma_f32_16x16x32_bf16 v[84:87], v[216:219], v[192:195], v[84:87]
	v_mfma_f32_16x16x32_bf16 v[80:83], v[224:227], v[192:195], v[80:83]
	v_mfma_f32_16x16x32_bf16 v[76:79], v[216:219], v[200:203], v[76:79]
	v_mfma_f32_16x16x32_bf16 v[72:75], v[224:227], v[200:203], v[72:75]
	v_mfma_f32_16x16x32_bf16 v[68:71], v[216:219], v[208:211], v[68:71]
	v_mfma_f32_16x16x32_bf16 v[64:67], v[224:227], v[208:211], v[64:67]
	v_mfma_f32_16x16x32_bf16 v[92:95], v[220:223], v[188:191], v[92:95]
	v_mfma_f32_16x16x32_bf16 v[88:91], v[228:231], v[188:191], v[88:91]
	v_mfma_f32_16x16x32_bf16 v[84:87], v[220:223], v[196:199], v[84:87]
	v_mfma_f32_16x16x32_bf16 v[80:83], v[228:231], v[196:199], v[80:83]
	v_mfma_f32_16x16x32_bf16 v[76:79], v[220:223], v[204:207], v[76:79]
	v_mfma_f32_16x16x32_bf16 v[72:75], v[228:231], v[204:207], v[72:75]
	v_mfma_f32_16x16x32_bf16 v[68:71], v[220:223], v[212:215], v[68:71]
	v_mfma_f32_16x16x32_bf16 v[64:67], v[228:231], v[212:215], v[64:67]
	s_setprio 0
	v_readfirstlane_b32 s45, v148
	v_lshl_add_u64 v[164:165], v[236:237], 0, s[18:19]
	s_mov_b32 m0, s45
	s_barrier
	ds_read_b128 v[188:191], v152 offset:16384
	ds_read_b128 v[192:195], v152 offset:17408
	ds_read_b128 v[196:199], v151 offset:16384
	ds_read_b128 v[200:203], v151 offset:17408
	ds_read_b128 v[204:207], v150 offset:16384
	ds_read_b128 v[208:211], v150 offset:17408
	ds_read_b128 v[212:215], v149 offset:16384
	ds_read_b128 v[232:235], v149 offset:17408
	global_load_lds_dwordx4 v[164:165], off
	v_add_u32_e32 v164, 0x2000, v148
	v_lshl_add_u64 v[166:167], v[238:239], 0, s[18:19]
	v_readfirstlane_b32 s45, v164
	s_mov_b32 m0, s45
	s_nop 0
	global_load_lds_dwordx4 v[166:167], off
	s_barrier
	s_waitcnt lgkmcnt(0)
	s_setprio 1
	s_waitcnt lgkmcnt(0)
	v_mfma_f32_16x16x32_bf16 v[60:63], v[172:175], v[188:191], v[60:63]
	v_mfma_f32_16x16x32_bf16 v[56:59], v[180:183], v[188:191], v[56:59]
	v_mfma_f32_16x16x32_bf16 v[52:55], v[172:175], v[196:199], v[52:55]
	v_mfma_f32_16x16x32_bf16 v[48:51], v[180:183], v[196:199], v[48:51]
	v_mfma_f32_16x16x32_bf16 v[44:47], v[172:175], v[204:207], v[44:47]
	v_mfma_f32_16x16x32_bf16 v[40:43], v[180:183], v[204:207], v[40:43]
	v_mfma_f32_16x16x32_bf16 v[36:39], v[172:175], v[212:215], v[36:39]
	v_mfma_f32_16x16x32_bf16 v[32:35], v[180:183], v[212:215], v[32:35]
	v_mfma_f32_16x16x32_bf16 v[60:63], v[176:179], v[192:195], v[60:63]
	v_mfma_f32_16x16x32_bf16 v[56:59], v[184:187], v[192:195], v[56:59]
	v_mfma_f32_16x16x32_bf16 v[52:55], v[176:179], v[200:203], v[52:55]
	v_mfma_f32_16x16x32_bf16 v[48:51], v[184:187], v[200:203], v[48:51]
	v_mfma_f32_16x16x32_bf16 v[44:47], v[176:179], v[208:211], v[44:47]
	v_mfma_f32_16x16x32_bf16 v[40:43], v[184:187], v[208:211], v[40:43]
	v_mfma_f32_16x16x32_bf16 v[36:39], v[176:179], v[232:235], v[36:39]
	v_mfma_f32_16x16x32_bf16 v[32:35], v[184:187], v[232:235], v[32:35]
	s_setprio 0
	s_barrier
; #define STAGE(P, BASE, LD, br, kt) do { const char* _g = (const char*)((BASE) + (size_t)(br) * (LD) + (size_t)(kt) * 64); \
;     for (int _i = 0; _i < 2; ++_i) { int _b = tidx * 16 + _i * 8192; int _r, _c; stage_rc(_b, _r, _c); \
;       __builtin_amdgcn_global_load_lds((const unsigned*)(_g + (unsigned)((_r * (LD) + _c) * 2)), (unsigned*)((char*)(P) + _b), 16, 0, 0); } } while (0)
; #define LDA(dst, b, h) for (int m = 0; m < 4; ++m) for (int k = 0; k < 2; ++k) \
;     dst[m][k] = *reinterpret_cast<const bf16x8*>((char*)SA(b, h) + lds_byte(wr * 64 + m * 16 + fr, k * 32 + fq * 8))
; #define LDB(dst, b, h) for (int n = 0; n < 2; ++n) for (int k = 0; k < 2; ++k) \
;     dst[n][k] = *reinterpret_cast<const bf16x8*>((char*)SB(b, h) + lds_byte(wc * 32 + n * 16 + fr, k * 32 + fq * 8))
; #define MMA(ai, bj, At_, Bt_) do { __builtin_amdgcn_s_setprio(1); \
;     for (int k = 0; k < 2; ++k) for (int m = 0; m < 4; ++m) for (int n = 0; n < 2; ++n) \
;       acc[ai][bj][m][n] = __builtin_amdgcn_mfma_f32_16x16x32_bf16(At_[m][k], Bt_[n][k], acc[ai][bj][m][n], 0, 0, 0); \
;     __builtin_amdgcn_s_setprio(0); } while (0)
; #define WAIT_V(n) asm volatile("s_waitcnt vmcnt(" #n ")" ::: "memory")
; #define WAIT_L(n) asm volatile("s_waitcnt lgkmcnt(" #n ")" ::: "memory")
; #define BAR __builtin_amdgcn_s_barrier()
; #define SCHED __builtin_amdgcn_sched_barrier(0)
; template <int EPI, int lda, int ldb, int N, int K>
; __device__ __forceinline__ void gemm_phase(const u16* __restrict__ A, const u16* __restrict__ Bt, const GemmEpi ep, int wv) {
;     ...
;       STAGE(SB(0, 1), Bt, ldb, bcol + HALF, t + 2);
;       WAIT_V(6); BAR; MMA(1, 1, At, B1); BAR;
;       LDB(B0, 1, 0); SCHED; LDA(At, 1, 0); STAGE(SA(0, 1), Ab, lda, brow + HALF, t + 2);
;       WAIT_L(8); BAR; WAIT_L(0); MMA(0, 0, At, B0); BAR; SCHED;
;       LDB(B1, 1, 1); STAGE(SB(1, 0), Bt, ldb, bcol, t + 3);
;       BAR; WAIT_L(0); MMA(0, 1, At, B1); BAR;
;       LDA(At, 1, 1); STAGE(SA(1, 0), Ab, lda, brow, t + 3);
;       BAR; WAIT_L(0); MMA(1, 0, At, B0); BAR; SCHED;
	v_add_u32_e32 v165, s55, v153
	v_lshl_add_u64 v[166:167], v[240:241], 0, s[20:21]
	v_readfirstlane_b32 s45, v165
	s_mov_b32 m0, s45
	v_lshl_add_u64 v[172:173], v[242:243], 0, s[20:21]
	global_load_lds_dwordx4 v[166:167], off
	v_add_u32_e32 v166, 0x2000, v165
	s_nop 0
	v_readfirstlane_b32 s45, v166
	s_mov_b32 m0, s45
	s_nop 0
	global_load_lds_dwordx4 v[172:173], off
	s_waitcnt vmcnt(6)
	s_barrier
	s_setprio 1
	v_mfma_f32_16x16x32_bf16 v[28:31], v[216:219], v[188:191], v[28:31]
	v_mfma_f32_16x16x32_bf16 v[24:27], v[224:227], v[188:191], v[24:27]
	v_mfma_f32_16x16x32_bf16 v[20:23], v[216:219], v[196:199], v[20:23]
	v_mfma_f32_16x16x32_bf16 v[16:19], v[224:227], v[196:199], v[16:19]
	v_mfma_f32_16x16x32_bf16 v[12:15], v[216:219], v[204:207], v[12:15]
	v_mfma_f32_16x16x32_bf16 v[8:11], v[224:227], v[204:207], v[8:11]
	v_mfma_f32_16x16x32_bf16 v[4:7], v[216:219], v[212:215], v[4:7]
	v_mfma_f32_16x16x32_bf16 v[0:3], v[224:227], v[212:215], v[0:3]
	v_mfma_f32_16x16x32_bf16 v[28:31], v[220:223], v[192:195], v[28:31]
	v_mfma_f32_16x16x32_bf16 v[24:27], v[228:231], v[192:195], v[24:27]
	v_mfma_f32_16x16x32_bf16 v[20:23], v[220:223], v[200:203], v[20:23]
	v_mfma_f32_16x16x32_bf16 v[16:19], v[228:231], v[200:203], v[16:19]
	v_mfma_f32_16x16x32_bf16 v[12:15], v[220:223], v[208:211], v[12:15]
	v_mfma_f32_16x16x32_bf16 v[8:11], v[228:231], v[208:211], v[8:11]
	v_mfma_f32_16x16x32_bf16 v[4:7], v[220:223], v[232:235], v[4:7]
	v_mfma_f32_16x16x32_bf16 v[0:3], v[228:231], v[232:235], v[0:3]
	s_setprio 0
	s_barrier
	ds_read_b128 v[172:175], v156
	ds_read_b128 v[176:179], v156 offset:1024
	ds_read_b128 v[180:183], v156 offset:2048
	ds_read_b128 v[184:187], v156 offset:3072
	v_add_u32_e32 v167, 0x4000, v148
	v_add_u32_e32 v168, 0x6000, v148
	v_readfirstlane_b32 s45, v167
	v_lshl_add_u64 v[220:221], v[236:237], 0, s[22:23]
	s_mov_b32 m0, s45
	v_readfirstlane_b32 s45, v168
	ds_read_b128 v[188:191], v152 offset:32768
	ds_read_b128 v[192:195], v152 offset:33792
	ds_read_b128 v[196:199], v151 offset:32768
	ds_read_b128 v[200:203], v151 offset:33792
	ds_read_b128 v[204:207], v150 offset:32768
	ds_read_b128 v[208:211], v150 offset:33792
	ds_read_b128 v[212:215], v149 offset:32768
	ds_read_b128 v[216:219], v149 offset:33792
	global_load_lds_dwordx4 v[220:221], off
	v_lshl_add_u64 v[220:221], v[238:239], 0, s[22:23]
	s_mov_b32 m0, s45
	s_nop 0
	global_load_lds_dwordx4 v[220:221], off
	s_waitcnt lgkmcnt(8)
	s_barrier
	s_waitcnt lgkmcnt(0)
	s_setprio 1
	s_waitcnt lgkmcnt(0)
	v_mfma_f32_16x16x32_bf16 v[124:127], v[172:175], v[188:191], v[124:127]
	v_mfma_f32_16x16x32_bf16 v[120:123], v[180:183], v[188:191], v[120:123]
	v_mfma_f32_16x16x32_bf16 v[116:119], v[172:175], v[196:199], v[116:119]
	v_mfma_f32_16x16x32_bf16 v[112:115], v[180:183], v[196:199], v[112:115]
	v_mfma_f32_16x16x32_bf16 v[108:111], v[172:175], v[204:207], v[108:111]
	v_mfma_f32_16x16x32_bf16 v[104:107], v[180:183], v[204:207], v[104:107]
	v_mfma_f32_16x16x32_bf16 v[100:103], v[172:175], v[212:215], v[100:103]
	v_mfma_f32_16x16x32_bf16 v[96:99], v[180:183], v[212:215], v[96:99]
	v_mfma_f32_16x16x32_bf16 v[124:127], v[176:179], v[192:195], v[124:127]
	v_mfma_f32_16x16x32_bf16 v[120:123], v[184:187], v[192:195], v[120:123]
	v_mfma_f32_16x16x32_bf16 v[116:119], v[176:179], v[200:203], v[116:119]
	v_mfma_f32_16x16x32_bf16 v[112:115], v[184:187], v[200:203], v[112:115]
	v_mfma_f32_16x16x32_bf16 v[108:111], v[176:179], v[208:211], v[108:111]
	v_mfma_f32_16x16x32_bf16 v[104:107], v[184:187], v[208:211], v[104:107]
	v_mfma_f32_16x16x32_bf16 v[100:103], v[176:179], v[216:219], v[100:103]
	v_mfma_f32_16x16x32_bf16 v[96:99], v[184:187], v[216:219], v[96:99]
	s_setprio 0
	s_barrier
	v_readfirstlane_b32 s45, v155
	v_add_u32_e32 v171, 0x2000, v155
	v_lshl_add_u64 v[244:245], v[240:241], 0, s[24:25]
	s_mov_b32 m0, s45
	v_readfirstlane_b32 s45, v171
	ds_read_b128 v[220:223], v154
	ds_read_b128 v[224:227], v154 offset:1024
	ds_read_b128 v[228:231], v154 offset:2048
	ds_read_b128 v[232:235], v154 offset:3072
	global_load_lds_dwordx4 v[244:245], off
	v_lshl_add_u64 v[244:245], v[242:243], 0, s[24:25]
	s_mov_b32 m0, s45
	s_nop 0
	global_load_lds_dwordx4 v[244:245], off
	s_barrier
	s_waitcnt lgkmcnt(0)
	s_setprio 1
	s_waitcnt lgkmcnt(0)
	v_mfma_f32_16x16x32_bf16 v[92:95], v[220:223], v[188:191], v[92:95]
	v_mfma_f32_16x16x32_bf16 v[88:91], v[228:231], v[188:191], v[88:91]
	v_mfma_f32_16x16x32_bf16 v[84:87], v[220:223], v[196:199], v[84:87]
	v_mfma_f32_16x16x32_bf16 v[80:83], v[228:231], v[196:199], v[80:83]
	v_mfma_f32_16x16x32_bf16 v[76:79], v[220:223], v[204:207], v[76:79]
	v_mfma_f32_16x16x32_bf16 v[72:75], v[228:231], v[204:207], v[72:75]
	v_mfma_f32_16x16x32_bf16 v[68:71], v[220:223], v[212:215], v[68:71]
	v_mfma_f32_16x16x32_bf16 v[64:67], v[228:231], v[212:215], v[64:67]
	v_mfma_f32_16x16x32_bf16 v[92:95], v[224:227], v[192:195], v[92:95]
	v_mfma_f32_16x16x32_bf16 v[88:91], v[232:235], v[192:195], v[88:91]
	v_mfma_f32_16x16x32_bf16 v[84:87], v[224:227], v[200:203], v[84:87]
	v_mfma_f32_16x16x32_bf16 v[80:83], v[232:235], v[200:203], v[80:83]
	v_mfma_f32_16x16x32_bf16 v[76:79], v[224:227], v[208:211], v[76:79]
	v_mfma_f32_16x16x32_bf16 v[72:75], v[232:235], v[208:211], v[72:75]
	v_mfma_f32_16x16x32_bf16 v[68:71], v[224:227], v[216:219], v[68:71]
	v_mfma_f32_16x16x32_bf16 v[64:67], v[232:235], v[216:219], v[64:67]
	s_setprio 0
	v_readfirstlane_b32 s45, v157
	v_lshl_add_u64 v[236:237], v[236:237], 0, s[26:27]
	s_mov_b32 m0, s45
	v_readfirstlane_b32 s45, v158
	s_barrier
; #define STAGE(P, BASE, LD, br, kt) do { const char* _g = (const char*)((BASE) + (size_t)(br) * (LD) + (size_t)(kt) * 64); \
;     for (int _i = 0; _i < 2; ++_i) { int _b = tidx * 16 + _i * 8192; int _r, _c; stage_rc(_b, _r, _c); \
;       __builtin_amdgcn_global_load_lds((const unsigned*)(_g + (unsigned)((_r * (LD) + _c) * 2)), (unsigned*)((char*)(P) + _b), 16, 0, 0); } } while (0)
; #define LDA(dst, b, h) for (int m = 0; m < 4; ++m) for (int k = 0; k < 2; ++k) \
;     dst[m][k] = *reinterpret_cast<const bf16x8*>((char*)SA(b, h) + lds_byte(wr * 64 + m * 16 + fr, k * 32 + fq * 8))
; #define LDB(dst, b, h) for (int n = 0; n < 2; ++n) for (int k = 0; k < 2; ++k) \
;     dst[n][k] = *reinterpret_cast<const bf16x8*>((char*)SB(b, h) + lds_byte(wc * 32 + n * 16 + fr, k * 32 + fq * 8))
; #define MMA(ai, bj, At_, Bt_) do { __builtin_amdgcn_s_setprio(1); \
;     for (int k = 0; k < 2; ++k) for (int m = 0; m < 4; ++m) for (int n = 0; n < 2; ++n) \
;       acc[ai][bj][m][n] = __builtin_amdgcn_mfma_f32_16x16x32_bf16(At_[m][k], Bt_[n][k], acc[ai][bj][m][n], 0, 0, 0); \
;     __builtin_amdgcn_s_setprio(0); } while (0)
; #define WAIT_V(n) asm volatile("s_waitcnt vmcnt(" #n ")" ::: "memory")
; #define WAIT_L(n) asm volatile("s_waitcnt lgkmcnt(" #n ")" ::: "memory")
; #define BAR __builtin_amdgcn_s_barrier()
; #define SCHED __builtin_amdgcn_sched_barrier(0)
; template <int EPI, int lda, int ldb, int N, int K>
; __device__ __forceinline__ void gemm_phase(const u16* __restrict__ A, const u16* __restrict__ Bt, const GemmEpi ep, int wv) {
;     ...
;       LDA(At, 1, 1); STAGE(SA(1, 0), Ab, lda, brow, t + 3);
;       BAR; WAIT_L(0); MMA(1, 0, At, B0); BAR; SCHED;
;       STAGE(SB(1, 1), Bt, ldb, bcol + HALF, t + 3);
;       WAIT_V(6); BAR; MMA(1, 1, At, B1); BAR;
;     }
;     { LDB(B0, 0, 0); LDA(At, 0, 0); STAGE(SA(1, 1), Ab, lda, brow + HALF, nt - 1);
;       BAR; WAIT_L(0); MMA(0, 0, At, B0); BAR;
	ds_read_b128 v[188:191], v152 offset:49152
	ds_read_b128 v[192:195], v152 offset:50176
	ds_read_b128 v[196:199], v151 offset:49152
	ds_read_b128 v[200:203], v151 offset:50176
	ds_read_b128 v[204:207], v150 offset:49152
	ds_read_b128 v[208:211], v150 offset:50176
	ds_read_b128 v[212:215], v149 offset:49152
	ds_read_b128 v[216:219], v149 offset:50176
	global_load_lds_dwordx4 v[236:237], off
	v_lshl_add_u64 v[236:237], v[238:239], 0, s[26:27]
	s_mov_b32 m0, s45
	s_nop 0
	global_load_lds_dwordx4 v[236:237], off
	s_barrier
	s_waitcnt lgkmcnt(0)
	s_setprio 1
	s_waitcnt lgkmcnt(0)
	v_mfma_f32_16x16x32_bf16 v[60:63], v[172:175], v[188:191], v[60:63]
	v_mfma_f32_16x16x32_bf16 v[56:59], v[180:183], v[188:191], v[56:59]
	v_mfma_f32_16x16x32_bf16 v[52:55], v[172:175], v[196:199], v[52:55]
	v_mfma_f32_16x16x32_bf16 v[48:51], v[180:183], v[196:199], v[48:51]
	v_mfma_f32_16x16x32_bf16 v[44:47], v[172:175], v[204:207], v[44:47]
	v_mfma_f32_16x16x32_bf16 v[40:43], v[180:183], v[204:207], v[40:43]
	v_mfma_f32_16x16x32_bf16 v[36:39], v[172:175], v[212:215], v[36:39]
	v_mfma_f32_16x16x32_bf16 v[32:35], v[180:183], v[212:215], v[32:35]
	v_mfma_f32_16x16x32_bf16 v[60:63], v[176:179], v[192:195], v[60:63]
	v_mfma_f32_16x16x32_bf16 v[56:59], v[184:187], v[192:195], v[56:59]
	v_mfma_f32_16x16x32_bf16 v[52:55], v[176:179], v[200:203], v[52:55]
	v_mfma_f32_16x16x32_bf16 v[48:51], v[184:187], v[200:203], v[48:51]
	v_mfma_f32_16x16x32_bf16 v[44:47], v[176:179], v[208:211], v[44:47]
	v_mfma_f32_16x16x32_bf16 v[40:43], v[184:187], v[208:211], v[40:43]
	v_mfma_f32_16x16x32_bf16 v[36:39], v[176:179], v[216:219], v[36:39]
	v_mfma_f32_16x16x32_bf16 v[32:35], v[184:187], v[216:219], v[32:35]
	s_setprio 0
	s_barrier
	v_readfirstlane_b32 s45, v159
	v_add_u32_e32 v171, 0x2000, v159
	v_lshl_add_u64 v[172:173], v[240:241], 0, s[34:35]
	s_mov_b32 m0, s45
	v_readfirstlane_b32 s45, v171
	global_load_lds_dwordx4 v[172:173], off
	v_lshl_add_u64 v[172:173], v[242:243], 0, s[34:35]
	s_mov_b32 m0, s45
	s_nop 0
	global_load_lds_dwordx4 v[172:173], off
	s_waitcnt vmcnt(6)
	s_barrier
	s_setprio 1
	v_mfma_f32_16x16x32_bf16 v[28:31], v[220:223], v[188:191], v[28:31]
	v_mfma_f32_16x16x32_bf16 v[24:27], v[228:231], v[188:191], v[24:27]
	v_mfma_f32_16x16x32_bf16 v[20:23], v[220:223], v[196:199], v[20:23]
	v_mfma_f32_16x16x32_bf16 v[16:19], v[228:231], v[196:199], v[16:19]
	v_mfma_f32_16x16x32_bf16 v[12:15], v[220:223], v[204:207], v[12:15]
	v_mfma_f32_16x16x32_bf16 v[8:11], v[228:231], v[204:207], v[8:11]
	v_mfma_f32_16x16x32_bf16 v[4:7], v[220:223], v[212:215], v[4:7]
	v_mfma_f32_16x16x32_bf16 v[0:3], v[228:231], v[212:215], v[0:3]
	v_mfma_f32_16x16x32_bf16 v[28:31], v[224:227], v[192:195], v[28:31]
	v_mfma_f32_16x16x32_bf16 v[24:27], v[232:235], v[192:195], v[24:27]
	v_mfma_f32_16x16x32_bf16 v[20:23], v[224:227], v[200:203], v[20:23]
	v_mfma_f32_16x16x32_bf16 v[16:19], v[232:235], v[200:203], v[16:19]
	v_mfma_f32_16x16x32_bf16 v[12:15], v[224:227], v[208:211], v[12:15]
	v_mfma_f32_16x16x32_bf16 v[8:11], v[232:235], v[208:211], v[8:11]
	v_mfma_f32_16x16x32_bf16 v[4:7], v[224:227], v[216:219], v[4:7]
	v_mfma_f32_16x16x32_bf16 v[0:3], v[232:235], v[216:219], v[0:3]
	s_setprio 0
	s_add_i32 s44, s44, 2
	s_add_u32 s42, s42, 0x100
	s_addc_u32 s43, s43, 0
	s_cmp_gt_u32 s44, 27
	s_barrier
	s_cbranch_scc0 .LBB0_53
	s_add_i32 s42, s38, 0x80
	s_mul_hi_i32 s43, s42, 0x1080
	s_mulk_i32 s42, 0x1080
	s_add_u32 s42, s51, s42
	s_addc_u32 s43, s52, s43
	v_lshl_add_u64 v[158:159], s[42:43], 0, v[128:129]
	v_readfirstlane_b32 s44, v169
	v_lshl_add_u64 v[158:159], v[158:159], 0, s[36:37]
	s_mov_b32 m0, s44
	ds_read_b128 v[134:137], v161
	ds_read_b128 v[138:141], v161 offset:1024
	ds_read_b128 v[172:175], v161 offset:2048
	ds_read_b128 v[176:179], v161 offset:3072
	ds_read_b128 v[180:183], v152
	ds_read_b128 v[184:187], v152 offset:1024
	ds_read_b128 v[188:191], v151
	ds_read_b128 v[192:195], v151 offset:1024
	ds_read_b128 v[196:199], v150
	ds_read_b128 v[200:203], v150 offset:1024
	ds_read_b128 v[204:207], v149
	ds_read_b128 v[208:211], v149 offset:1024
	global_load_lds_dwordx4 v[158:159], off
	v_lshl_add_u64 v[158:159], s[42:43], 0, v[132:133]
	v_readfirstlane_b32 s42, v170
	v_lshl_add_u64 v[158:159], v[158:159], 0, s[36:37]
	s_mov_b32 m0, s42
	s_nop 0
	global_load_lds_dwordx4 v[158:159], off
	s_barrier
	s_waitcnt lgkmcnt(0)
	s_setprio 1
	s_waitcnt lgkmcnt(0)
	v_mfma_f32_16x16x32_bf16 v[124:127], v[134:137], v[180:183], v[124:127]
	v_mfma_f32_16x16x32_bf16 v[120:123], v[172:175], v[180:183], v[120:123]
	v_mfma_f32_16x16x32_bf16 v[116:119], v[134:137], v[188:191], v[116:119]
	v_mfma_f32_16x16x32_bf16 v[112:115], v[172:175], v[188:191], v[112:115]
	v_mfma_f32_16x16x32_bf16 v[108:111], v[134:137], v[196:199], v[108:111]
	v_mfma_f32_16x16x32_bf16 v[104:107], v[172:175], v[196:199], v[104:107]
	v_mfma_f32_16x16x32_bf16 v[100:103], v[134:137], v[204:207], v[100:103]
	v_mfma_f32_16x16x32_bf16 v[96:99], v[172:175], v[204:207], v[96:99]
	v_mfma_f32_16x16x32_bf16 v[124:127], v[138:141], v[184:187], v[124:127]
	v_mfma_f32_16x16x32_bf16 v[120:123], v[176:179], v[184:187], v[120:123]
	v_mfma_f32_16x16x32_bf16 v[116:119], v[138:141], v[192:195], v[116:119]
	v_mfma_f32_16x16x32_bf16 v[112:115], v[176:179], v[192:195], v[112:115]
	v_mfma_f32_16x16x32_bf16 v[108:111], v[138:141], v[200:203], v[108:111]
	v_mfma_f32_16x16x32_bf16 v[104:107], v[176:179], v[200:203], v[104:107]
	v_mfma_f32_16x16x32_bf16 v[100:103], v[138:141], v[208:211], v[100:103]
	v_mfma_f32_16x16x32_bf16 v[96:99], v[176:179], v[208:211], v[96:99]
	s_setprio 0
	s_barrier
	ds_read_b128 v[212:215], v160
	ds_read_b128 v[216:219], v160 offset:1024
	ds_read_b128 v[220:223], v160 offset:2048
	ds_read_b128 v[158:161], v160 offset:3072
	s_barrier
; #define LDA(dst, b, h) for (int m = 0; m < 4; ++m) for (int k = 0; k < 2; ++k) \
;     dst[m][k] = *reinterpret_cast<const bf16x8*>((char*)SA(b, h) + lds_byte(wr * 64 + m * 16 + fr, k * 32 + fq * 8))
; #define LDB(dst, b, h) for (int n = 0; n < 2; ++n) for (int k = 0; k < 2; ++k) \
;     dst[n][k] = *reinterpret_cast<const bf16x8*>((char*)SB(b, h) + lds_byte(wc * 32 + n * 16 + fr, k * 32 + fq * 8))
; #define MMA(ai, bj, At_, Bt_) do { __builtin_amdgcn_s_setprio(1); \
;     for (int k = 0; k < 2; ++k) for (int m = 0; m < 4; ++m) for (int n = 0; n < 2; ++n) \
;       acc[ai][bj][m][n] = __builtin_amdgcn_mfma_f32_16x16x32_bf16(At_[m][k], Bt_[n][k], acc[ai][bj][m][n], 0, 0, 0); \
;     __builtin_amdgcn_s_setprio(0); } while (0)
; #define WAIT_V(n) asm volatile("s_waitcnt vmcnt(" #n ")" ::: "memory")
; #define WAIT_L(n) asm volatile("s_waitcnt lgkmcnt(" #n ")" ::: "memory")
; #define BAR __builtin_amdgcn_s_barrier()
; template <int EPI, int lda, int ldb, int N, int K>
; __device__ __forceinline__ void gemm_phase(const u16* __restrict__ A, const u16* __restrict__ Bt, const GemmEpi ep, int wv) {
;     ...
;       BAR; WAIT_L(0); MMA(0, 0, At, B0); BAR;
;       LDB(B1, 0, 1); BAR; WAIT_L(0); MMA(0, 1, At, B1); BAR;
;       LDA(At, 0, 1); WAIT_V(4); BAR; WAIT_L(0); MMA(1, 0, At, B0); MMA(1, 1, At, B1); BAR; }
;     { LDB(B0, 1, 0); LDA(At, 1, 0); WAIT_V(2); BAR; WAIT_L(0); MMA(0, 0, At, B0); BAR;
;       LDB(B1, 1, 1); WAIT_V(0); BAR; WAIT_L(0); MMA(0, 1, At, B1); BAR;
;       LDA(At, 1, 1); BAR; WAIT_L(0); MMA(1, 0, At, B0); MMA(1, 1, At, B1); BAR; }
	s_waitcnt lgkmcnt(0)
	s_setprio 1
	s_waitcnt lgkmcnt(0)
	v_mfma_f32_16x16x32_bf16 v[92:95], v[212:215], v[180:183], v[92:95]
	v_mfma_f32_16x16x32_bf16 v[88:91], v[220:223], v[180:183], v[88:91]
	v_mfma_f32_16x16x32_bf16 v[76:79], v[212:215], v[196:199], v[76:79]
	v_mfma_f32_16x16x32_bf16 v[72:75], v[220:223], v[196:199], v[72:75]
	v_mfma_f32_16x16x32_bf16 v[84:87], v[212:215], v[188:191], v[84:87]
	v_mfma_f32_16x16x32_bf16 v[80:83], v[220:223], v[188:191], v[80:83]
	v_mfma_f32_16x16x32_bf16 v[68:71], v[212:215], v[204:207], v[68:71]
	v_mfma_f32_16x16x32_bf16 v[64:67], v[220:223], v[204:207], v[64:67]
	v_mfma_f32_16x16x32_bf16 v[92:95], v[216:219], v[184:187], v[92:95]
	v_mfma_f32_16x16x32_bf16 v[88:91], v[158:161], v[184:187], v[88:91]
	v_mfma_f32_16x16x32_bf16 v[76:79], v[216:219], v[200:203], v[76:79]
	v_mfma_f32_16x16x32_bf16 v[72:75], v[158:161], v[200:203], v[72:75]
	v_mfma_f32_16x16x32_bf16 v[180:183], v[216:219], v[192:195], v[84:87]
	v_mfma_f32_16x16x32_bf16 v[184:187], v[158:161], v[192:195], v[80:83]
	v_mfma_f32_16x16x32_bf16 v[188:191], v[216:219], v[208:211], v[68:71]
	v_mfma_f32_16x16x32_bf16 v[192:195], v[158:161], v[208:211], v[64:67]
	s_setprio 0
	s_barrier
	s_nop 0
	ds_read_b128 v[64:67], v152 offset:16384
	ds_read_b128 v[68:71], v152 offset:17408
	ds_read_b128 v[80:83], v151 offset:16384
	ds_read_b128 v[84:87], v151 offset:17408
	ds_read_b128 v[196:199], v150 offset:16384
	ds_read_b128 v[200:203], v150 offset:17408
	ds_read_b128 v[204:207], v149 offset:16384
	ds_read_b128 v[208:211], v149 offset:17408
	s_waitcnt vmcnt(4)
	s_barrier
	s_waitcnt lgkmcnt(0)
	s_setprio 1
	s_waitcnt lgkmcnt(0)
	v_mfma_f32_16x16x32_bf16 v[60:63], v[134:137], v[64:67], v[60:63]
	v_mfma_f32_16x16x32_bf16 v[56:59], v[172:175], v[64:67], v[56:59]
	v_mfma_f32_16x16x32_bf16 v[52:55], v[134:137], v[80:83], v[52:55]
	v_mfma_f32_16x16x32_bf16 v[48:51], v[172:175], v[80:83], v[48:51]
	v_mfma_f32_16x16x32_bf16 v[44:47], v[134:137], v[196:199], v[44:47]
	v_mfma_f32_16x16x32_bf16 v[40:43], v[172:175], v[196:199], v[40:43]
	v_mfma_f32_16x16x32_bf16 v[36:39], v[134:137], v[204:207], v[36:39]
	v_mfma_f32_16x16x32_bf16 v[32:35], v[172:175], v[204:207], v[32:35]
	v_mfma_f32_16x16x32_bf16 v[60:63], v[138:141], v[68:71], v[60:63]
	v_mfma_f32_16x16x32_bf16 v[56:59], v[176:179], v[68:71], v[56:59]
	v_mfma_f32_16x16x32_bf16 v[52:55], v[138:141], v[84:87], v[52:55]
	v_mfma_f32_16x16x32_bf16 v[48:51], v[176:179], v[84:87], v[48:51]
	v_mfma_f32_16x16x32_bf16 v[44:47], v[138:141], v[200:203], v[44:47]
	v_mfma_f32_16x16x32_bf16 v[40:43], v[176:179], v[200:203], v[40:43]
	v_mfma_f32_16x16x32_bf16 v[36:39], v[138:141], v[208:211], v[36:39]
	v_mfma_f32_16x16x32_bf16 v[32:35], v[176:179], v[208:211], v[32:35]
	s_setprio 0
	s_setprio 1
	v_mfma_f32_16x16x32_bf16 v[28:31], v[212:215], v[64:67], v[28:31]
	v_mfma_f32_16x16x32_bf16 v[24:27], v[220:223], v[64:67], v[24:27]
	v_mfma_f32_16x16x32_bf16 v[12:15], v[212:215], v[196:199], v[12:15]
	v_mfma_f32_16x16x32_bf16 v[8:11], v[220:223], v[196:199], v[8:11]
	v_mfma_f32_16x16x32_bf16 v[20:23], v[212:215], v[80:83], v[20:23]
	v_mfma_f32_16x16x32_bf16 v[16:19], v[220:223], v[80:83], v[16:19]
	v_mfma_f32_16x16x32_bf16 v[4:7], v[212:215], v[204:207], v[4:7]
	v_mfma_f32_16x16x32_bf16 v[0:3], v[220:223], v[204:207], v[0:3]
	v_mfma_f32_16x16x32_bf16 v[28:31], v[216:219], v[68:71], v[28:31]
	v_mfma_f32_16x16x32_bf16 v[24:27], v[158:161], v[68:71], v[24:27]
	v_mfma_f32_16x16x32_bf16 v[12:15], v[216:219], v[200:203], v[12:15]
	v_mfma_f32_16x16x32_bf16 v[8:11], v[158:161], v[200:203], v[8:11]
	v_mfma_f32_16x16x32_bf16 v[134:137], v[216:219], v[84:87], v[20:23]
	v_mfma_f32_16x16x32_bf16 v[138:141], v[158:161], v[84:87], v[16:19]
	v_mfma_f32_16x16x32_bf16 v[170:173], v[216:219], v[208:211], v[4:7]
	v_mfma_f32_16x16x32_bf16 v[158:161], v[158:161], v[208:211], v[0:3]
	s_setprio 0
	s_barrier
	s_nop 0
	ds_read_b128 v[0:3], v156
	ds_read_b128 v[4:7], v156 offset:1024
	ds_read_b128 v[16:19], v156 offset:2048
	ds_read_b128 v[174:177], v156 offset:3072
	ds_read_b128 v[20:23], v152 offset:32768
	ds_read_b128 v[196:199], v152 offset:33792
	ds_read_b128 v[200:203], v151 offset:32768
	ds_read_b128 v[204:207], v151 offset:33792
	ds_read_b128 v[208:211], v150 offset:32768
	ds_read_b128 v[212:215], v150 offset:33792
	ds_read_b128 v[216:219], v149 offset:32768
	ds_read_b128 v[220:223], v149 offset:33792
	s_waitcnt vmcnt(2)
	s_barrier
; #define LDA(dst, b, h) for (int m = 0; m < 4; ++m) for (int k = 0; k < 2; ++k) \
;     dst[m][k] = *reinterpret_cast<const bf16x8*>((char*)SA(b, h) + lds_byte(wr * 64 + m * 16 + fr, k * 32 + fq * 8))
; #define LDB(dst, b, h) for (int n = 0; n < 2; ++n) for (int k = 0; k < 2; ++k) \
;     dst[n][k] = *reinterpret_cast<const bf16x8*>((char*)SB(b, h) + lds_byte(wc * 32 + n * 16 + fr, k * 32 + fq * 8))
; #define MMA(ai, bj, At_, Bt_) do { __builtin_amdgcn_s_setprio(1); \
;     for (int k = 0; k < 2; ++k) for (int m = 0; m < 4; ++m) for (int n = 0; n < 2; ++n) \
;       acc[ai][bj][m][n] = __builtin_amdgcn_mfma_f32_16x16x32_bf16(At_[m][k], Bt_[n][k], acc[ai][bj][m][n], 0, 0, 0); \
;     __builtin_amdgcn_s_setprio(0); } while (0)
; #define WAIT_V(n) asm volatile("s_waitcnt vmcnt(" #n ")" ::: "memory")
; #define WAIT_L(n) asm volatile("s_waitcnt lgkmcnt(" #n ")" ::: "memory")
; #define BAR __builtin_amdgcn_s_barrier()
; template <int EPI, int lda, int ldb, int N, int K>
; __device__ __forceinline__ void gemm_phase(const u16* __restrict__ A, const u16* __restrict__ Bt, const GemmEpi ep, int wv) {
;     ...
;       LDA(At, 0, 1); WAIT_V(4); BAR; WAIT_L(0); MMA(1, 0, At, B0); MMA(1, 1, At, B1); BAR; }
;     { LDB(B0, 1, 0); LDA(At, 1, 0); WAIT_V(2); BAR; WAIT_L(0); MMA(0, 0, At, B0); BAR;
;       LDB(B1, 1, 1); WAIT_V(0); BAR; WAIT_L(0); MMA(0, 1, At, B1); BAR;
;       LDA(At, 1, 1); BAR; WAIT_L(0); MMA(1, 0, At, B0); MMA(1, 1, At, B1); BAR; }
;     if (wr == 0) BAR;
	s_waitcnt lgkmcnt(0)
	s_setprio 1
	s_waitcnt lgkmcnt(0)
	v_mfma_f32_16x16x32_bf16 v[64:67], v[0:3], v[20:23], v[124:127]
	v_mfma_f32_16x16x32_bf16 v[68:71], v[16:19], v[20:23], v[120:123]
	v_mfma_f32_16x16x32_bf16 v[80:83], v[0:3], v[200:203], v[116:119]
	v_mfma_f32_16x16x32_bf16 v[84:87], v[16:19], v[200:203], v[112:115]
	v_mfma_f32_16x16x32_bf16 v[108:111], v[0:3], v[208:211], v[108:111]
	v_mfma_f32_16x16x32_bf16 v[104:107], v[16:19], v[208:211], v[104:107]
	v_mfma_f32_16x16x32_bf16 v[120:123], v[0:3], v[216:219], v[100:103]
	v_mfma_f32_16x16x32_bf16 v[124:127], v[16:19], v[216:219], v[96:99]
	v_mfma_f32_16x16x32_bf16 v[116:119], v[4:7], v[196:199], v[64:67]
	v_mfma_f32_16x16x32_bf16 v[112:115], v[174:177], v[196:199], v[68:71]
	v_mfma_f32_16x16x32_bf16 v[100:103], v[4:7], v[204:207], v[80:83]
	v_mfma_f32_16x16x32_bf16 v[96:99], v[174:177], v[204:207], v[84:87]
	v_mfma_f32_16x16x32_bf16 v[84:87], v[4:7], v[212:215], v[108:111]
	v_mfma_f32_16x16x32_bf16 v[80:83], v[174:177], v[212:215], v[104:107]
	v_mfma_f32_16x16x32_bf16 v[68:71], v[4:7], v[220:223], v[120:123]
	v_mfma_f32_16x16x32_bf16 v[64:67], v[174:177], v[220:223], v[124:127]
	s_setprio 0
	s_barrier
	ds_read_b128 v[224:227], v154
	ds_read_b128 v[228:231], v154 offset:1024
	ds_read_b128 v[232:235], v154 offset:2048
	ds_read_b128 v[154:157], v154 offset:3072
	s_waitcnt vmcnt(0)
	s_barrier
	s_waitcnt lgkmcnt(0)
	s_setprio 1
	s_waitcnt lgkmcnt(0)
	v_mfma_f32_16x16x32_bf16 v[92:95], v[224:227], v[20:23], v[92:95]
	v_mfma_f32_16x16x32_bf16 v[20:23], v[232:235], v[20:23], v[88:91]
	v_mfma_f32_16x16x32_bf16 v[88:91], v[224:227], v[200:203], v[180:183]
	v_mfma_f32_16x16x32_bf16 v[104:107], v[232:235], v[200:203], v[184:187]
	v_mfma_f32_16x16x32_bf16 v[76:79], v[224:227], v[208:211], v[76:79]
	v_mfma_f32_16x16x32_bf16 v[72:75], v[232:235], v[208:211], v[72:75]
	v_mfma_f32_16x16x32_bf16 v[178:181], v[224:227], v[216:219], v[188:191]
	v_mfma_f32_16x16x32_bf16 v[182:185], v[232:235], v[216:219], v[192:195]
	v_mfma_f32_16x16x32_bf16 v[124:127], v[228:231], v[196:199], v[92:95]
	v_mfma_f32_16x16x32_bf16 v[120:123], v[154:157], v[196:199], v[20:23]
	v_mfma_f32_16x16x32_bf16 v[108:111], v[228:231], v[204:207], v[88:91]
	v_mfma_f32_16x16x32_bf16 v[104:107], v[154:157], v[204:207], v[104:107]
	v_mfma_f32_16x16x32_bf16 v[92:95], v[228:231], v[212:215], v[76:79]
	v_mfma_f32_16x16x32_bf16 v[88:91], v[154:157], v[212:215], v[72:75]
	v_mfma_f32_16x16x32_bf16 v[76:79], v[228:231], v[220:223], v[178:181]
	v_mfma_f32_16x16x32_bf16 v[72:75], v[154:157], v[220:223], v[182:185]
	s_setprio 0
	s_barrier
	ds_read_b128 v[178:181], v152 offset:49152
	ds_read_b128 v[182:185], v152 offset:50176
	ds_read_b128 v[186:189], v151 offset:49152
	ds_read_b128 v[190:193], v151 offset:50176
	ds_read_b128 v[194:197], v150 offset:49152
	ds_read_b128 v[150:153], v150 offset:50176
	ds_read_b128 v[198:201], v149 offset:49152
	ds_read_b128 v[202:205], v149 offset:50176
	s_barrier
	s_waitcnt lgkmcnt(0)
	s_setprio 1
	s_waitcnt lgkmcnt(0)
	v_mfma_f32_16x16x32_bf16 v[20:23], v[0:3], v[178:181], v[60:63]
	v_mfma_f32_16x16x32_bf16 v[56:59], v[16:19], v[178:181], v[56:59]
	v_mfma_f32_16x16x32_bf16 v[60:63], v[0:3], v[186:189], v[52:55]
	v_mfma_f32_16x16x32_bf16 v[206:209], v[16:19], v[186:189], v[48:51]
	v_mfma_f32_16x16x32_bf16 v[44:47], v[0:3], v[194:197], v[44:47]
	v_mfma_f32_16x16x32_bf16 v[40:43], v[16:19], v[194:197], v[40:43]
	v_mfma_f32_16x16x32_bf16 v[0:3], v[0:3], v[198:201], v[36:39]
	v_mfma_f32_16x16x32_bf16 v[210:213], v[16:19], v[198:201], v[32:35]
	v_mfma_f32_16x16x32_bf16 v[52:55], v[4:7], v[182:185], v[20:23]
	v_mfma_f32_16x16x32_bf16 v[48:51], v[174:177], v[182:185], v[56:59]
	v_mfma_f32_16x16x32_bf16 v[36:39], v[4:7], v[190:193], v[60:63]
	v_mfma_f32_16x16x32_bf16 v[32:35], v[174:177], v[190:193], v[206:209]
	v_mfma_f32_16x16x32_bf16 v[20:23], v[4:7], v[150:153], v[44:47]
	v_mfma_f32_16x16x32_bf16 v[16:19], v[174:177], v[150:153], v[40:43]
	v_mfma_f32_16x16x32_bf16 v[4:7], v[4:7], v[202:205], v[0:3]
	v_mfma_f32_16x16x32_bf16 v[0:3], v[174:177], v[202:205], v[210:213]
	s_setprio 0
	s_setprio 1
	v_mfma_f32_16x16x32_bf16 v[28:31], v[224:227], v[178:181], v[28:31]
	v_mfma_f32_16x16x32_bf16 v[24:27], v[232:235], v[178:181], v[24:27]
	v_mfma_f32_16x16x32_bf16 v[40:43], v[224:227], v[186:189], v[134:137]
	v_mfma_f32_16x16x32_bf16 v[134:137], v[232:235], v[186:189], v[138:141]
	v_mfma_f32_16x16x32_bf16 v[12:15], v[224:227], v[194:197], v[12:15]
	v_mfma_f32_16x16x32_bf16 v[8:11], v[232:235], v[194:197], v[8:11]
	v_mfma_f32_16x16x32_bf16 v[138:141], v[224:227], v[198:201], v[170:173]
	v_mfma_f32_16x16x32_bf16 v[158:161], v[232:235], v[198:201], v[158:161]
	v_mfma_f32_16x16x32_bf16 v[60:63], v[228:231], v[182:185], v[28:31]
	v_mfma_f32_16x16x32_bf16 v[56:59], v[154:157], v[182:185], v[24:27]
	v_mfma_f32_16x16x32_bf16 v[44:47], v[228:231], v[190:193], v[40:43]
	v_mfma_f32_16x16x32_bf16 v[40:43], v[154:157], v[190:193], v[134:137]
	v_mfma_f32_16x16x32_bf16 v[28:31], v[228:231], v[150:153], v[12:15]
	v_mfma_f32_16x16x32_bf16 v[24:27], v[154:157], v[150:153], v[8:11]
	v_mfma_f32_16x16x32_bf16 v[12:15], v[228:231], v[202:205], v[138:141]
	v_mfma_f32_16x16x32_bf16 v[8:11], v[154:157], v[202:205], v[158:161]
	s_setprio 0
	v_cmp_gt_u32_e32 vcc, s56, v130
	s_barrier
	s_and_saveexec_b64 s[42:43], vcc
	s_cbranch_execz .LBB0_56
	s_barrier

; __device__ __forceinline__ u16 f2bf(float x) { return (u16)(cvtpk(x, x) & 0xffffu); }
; #define UNR _Pragma("unroll")
; template <int EPI, int lda, int ldb, int N, int K>
; __device__ __forceinline__ void gemm_phase(const u16* __restrict__ A, const u16* __restrict__ Bt, const GemmEpi ep, int wv) {
;     ...
;     if constexpr (EPI == EPI_SWIGLU) {
;       u16* out = reinterpret_cast<u16*>(ep.out0);
;       UNR for (int ai = 0; ai < 2; ++ai) UNR for (int m = 0; m < 4; ++m) {
;         const int rl0 = ai * HALF + wr * 64 + m * 16 + fq * 4;
;         const f32x4 r4 = *reinterpret_cast<const f32x4*>(lrs + rl0);
;         UNR for (int j = 0; j < 4; ++j) {
;           const int row = brow + rl0 + j;
;           const float rs = r4[j], ce = -1.4426950408889634f * rs, r2 = rs * rs;
;           UNR for (int n = 0; n < 2; ++n) {
;             const int col = (bcol >> 1) + wc * 32 + n * 16 + fr;
;             const float g = acc[ai][0][m][n][j], u = acc[ai][1][m][n][j];
;             const float sg = __builtin_amdgcn_rcpf(1.f + __builtin_amdgcn_exp2f(ce * g));
;             out[(size_t)row * ep.ldc + col] = f2bf((g * u) * (r2 * sg));
;           }
;         }
;       }
.LBB0_60:
	s_or_b64 exec, exec, s[48:49]
	v_and_b32_e32 v135, 15, v130
	v_lshrrev_b32_e32 v149, 8, v130
	v_lshl_add_u32 v135, v149, 6, v135
	v_lshlrev_b32_e32 v133, 2, v135
	v_add_u32_e32 v133, 0x20000, v133
	ds_read_b32 v150, v133 offset:0
	ds_read_b32 v151, v133 offset:64
	ds_read_b32 v152, v133 offset:128
	ds_read_b32 v153, v133 offset:192
	v_add_u32_e32 v135, s38, v135
	v_mul_u32_u24_e32 v132, 0x2b00, v135
	v_bfe_u32 v149, v130, 6, 2
	v_lshlrev_b32_e32 v149, 5, v149
	v_bfe_u32 v135, v130, 4, 1
	v_lshl_add_u32 v149, v135, 4, v149
	v_bfe_u32 v135, v130, 5, 1
	v_lshl_add_u32 v149, v135, 3, v149
	v_lshrrev_b32_e64 v135, 1, s39
	v_add_u32_e32 v149, v135, v149
	v_lshl_add_u32 v132, v149, 1, v132
	s_waitcnt lgkmcnt(0)
	v_mul_f32_e32 v135, 0xbfb8aa3b, v150
	v_mul_f32_e32 v149, v150, v150
	ds_read_b32 v150, v133 offset:512
	v_mul_f32_e32 v124, v116, v124
	v_mul_f32_e32 v125, v117, v125
	v_mul_f32_e32 v116, v135, v116
	v_mul_f32_e32 v117, v135, v117
	v_exp_f32_e32 v116, v116
	v_exp_f32_e32 v117, v117
	v_add_f32_e32 v116, 1.0, v116
	v_add_f32_e32 v117, 1.0, v117
	v_rcp_f32_e32 v116, v116
	v_rcp_f32_e32 v117, v117
	v_mul_f32_e32 v116, v149, v116
	v_mul_f32_e32 v117, v149, v117
	v_mul_f32_e32 v124, v124, v116
	v_mul_f32_e32 v125, v125, v117
	v_cvt_pk_bf16_f32 v116, v124, v125
	v_mul_f32_e32 v126, v118, v126
	v_mul_f32_e32 v127, v119, v127
	v_mul_f32_e32 v118, v135, v118
	v_mul_f32_e32 v119, v135, v119
	v_exp_f32_e32 v118, v118
	v_exp_f32_e32 v119, v119
	v_add_f32_e32 v118, 1.0, v118
	v_add_f32_e32 v119, 1.0, v119
	v_rcp_f32_e32 v118, v118
	v_rcp_f32_e32 v119, v119
	v_mul_f32_e32 v118, v149, v118
	v_mul_f32_e32 v119, v149, v119
	v_mul_f32_e32 v126, v126, v118
	v_mul_f32_e32 v127, v127, v119
	v_cvt_pk_bf16_f32 v117, v126, v127
	v_mul_f32_e32 v120, v112, v120
	v_mul_f32_e32 v121, v113, v121
	v_mul_f32_e32 v112, v135, v112
	v_mul_f32_e32 v113, v135, v113
	v_exp_f32_e32 v112, v112
	v_exp_f32_e32 v113, v113
	v_add_f32_e32 v112, 1.0, v112
	v_add_f32_e32 v113, 1.0, v113
	v_rcp_f32_e32 v112, v112
	v_rcp_f32_e32 v113, v113
	v_mul_f32_e32 v112, v149, v112
	v_mul_f32_e32 v113, v149, v113
	v_mul_f32_e32 v120, v120, v112
	v_mul_f32_e32 v121, v121, v113
	v_cvt_pk_bf16_f32 v118, v120, v121
	v_mul_f32_e32 v122, v114, v122
	v_mul_f32_e32 v123, v115, v123
	v_mul_f32_e32 v114, v135, v114
	v_mul_f32_e32 v115, v135, v115
	v_exp_f32_e32 v114, v114
	v_exp_f32_e32 v115, v115
	v_add_f32_e32 v114, 1.0, v114
	v_add_f32_e32 v115, 1.0, v115
	v_rcp_f32_e32 v114, v114
	v_rcp_f32_e32 v115, v115
	v_mul_f32_e32 v114, v149, v114
	v_mul_f32_e32 v115, v149, v115
	v_mul_f32_e32 v122, v122, v114
	v_mul_f32_e32 v123, v123, v115
	v_cvt_pk_bf16_f32 v119, v122, v123
	s_nop 1
	v_permlane16_swap_b32_e32 v116, v118
	v_permlane16_swap_b32_e32 v117, v119
	global_store_dwordx4 v132, v[116:119], s[10:11]
	v_add_u32_e32 v134, 0x2b000, v132
	v_mul_f32_e32 v135, 0xbfb8aa3b, v151
	v_mul_f32_e32 v149, v151, v151
	ds_read_b32 v151, v133 offset:576
	v_mul_f32_e32 v108, v100, v108
	v_mul_f32_e32 v109, v101, v109
	v_mul_f32_e32 v100, v135, v100
	v_mul_f32_e32 v101, v135, v101
	v_exp_f32_e32 v100, v100
	v_exp_f32_e32 v101, v101
	v_add_f32_e32 v100, 1.0, v100
	v_add_f32_e32 v101, 1.0, v101
	v_rcp_f32_e32 v100, v100
	v_rcp_f32_e32 v101, v101
	v_mul_f32_e32 v100, v149, v100
	v_mul_f32_e32 v101, v149, v101
	v_mul_f32_e32 v108, v108, v100
	v_mul_f32_e32 v109, v109, v101
	v_cvt_pk_bf16_f32 v100, v108, v109
	v_mul_f32_e32 v110, v102, v110
	v_mul_f32_e32 v111, v103, v111
	v_mul_f32_e32 v102, v135, v102
	v_mul_f32_e32 v103, v135, v103
	v_exp_f32_e32 v102, v102
	v_exp_f32_e32 v103, v103
	v_add_f32_e32 v102, 1.0, v102
	v_add_f32_e32 v103, 1.0, v103
	v_rcp_f32_e32 v102, v102
	v_rcp_f32_e32 v103, v103
	v_mul_f32_e32 v102, v149, v102
	v_mul_f32_e32 v103, v149, v103
	v_mul_f32_e32 v110, v110, v102
	v_mul_f32_e32 v111, v111, v103
	v_cvt_pk_bf16_f32 v101, v110, v111
	v_mul_f32_e32 v104, v96, v104
	v_mul_f32_e32 v105, v97, v105
	v_mul_f32_e32 v96, v135, v96
	v_mul_f32_e32 v97, v135, v97
	v_exp_f32_e32 v96, v96
	v_exp_f32_e32 v97, v97
	v_add_f32_e32 v96, 1.0, v96
	v_add_f32_e32 v97, 1.0, v97
	v_rcp_f32_e32 v96, v96
	v_rcp_f32_e32 v97, v97
	v_mul_f32_e32 v96, v149, v96
	v_mul_f32_e32 v97, v149, v97
	v_mul_f32_e32 v104, v104, v96
	v_mul_f32_e32 v105, v105, v97
	v_cvt_pk_bf16_f32 v102, v104, v105
	v_mul_f32_e32 v106, v98, v106
	v_mul_f32_e32 v107, v99, v107
	v_mul_f32_e32 v98, v135, v98
	v_mul_f32_e32 v99, v135, v99
	v_exp_f32_e32 v98, v98
	v_exp_f32_e32 v99, v99
	v_add_f32_e32 v98, 1.0, v98
	v_add_f32_e32 v99, 1.0, v99
	v_rcp_f32_e32 v98, v98
	v_rcp_f32_e32 v99, v99
	v_mul_f32_e32 v98, v149, v98
	v_mul_f32_e32 v99, v149, v99
	v_mul_f32_e32 v106, v106, v98
	v_mul_f32_e32 v107, v107, v99
	v_cvt_pk_bf16_f32 v103, v106, v107
	s_nop 1
	v_permlane16_swap_b32_e32 v100, v102
	v_permlane16_swap_b32_e32 v101, v103
	global_store_dwordx4 v134, v[100:103], s[10:11]
	v_add_u32_e32 v134, 0x56000, v132
	v_mul_f32_e32 v135, 0xbfb8aa3b, v152
	v_mul_f32_e32 v149, v152, v152
	ds_read_b32 v152, v133 offset:640
	v_mul_f32_e32 v92, v84, v92
	v_mul_f32_e32 v93, v85, v93
	v_mul_f32_e32 v84, v135, v84
	v_mul_f32_e32 v85, v135, v85
	v_exp_f32_e32 v84, v84
	v_exp_f32_e32 v85, v85
	v_add_f32_e32 v84, 1.0, v84
	v_add_f32_e32 v85, 1.0, v85
	v_rcp_f32_e32 v84, v84
	v_rcp_f32_e32 v85, v85
	v_mul_f32_e32 v84, v149, v84
	v_mul_f32_e32 v85, v149, v85
	v_mul_f32_e32 v92, v92, v84
	v_mul_f32_e32 v93, v93, v85
	v_cvt_pk_bf16_f32 v84, v92, v93
	v_mul_f32_e32 v94, v86, v94
	v_mul_f32_e32 v95, v87, v95
	v_mul_f32_e32 v86, v135, v86
	v_mul_f32_e32 v87, v135, v87
	v_exp_f32_e32 v86, v86
	v_exp_f32_e32 v87, v87
	v_add_f32_e32 v86, 1.0, v86
	v_add_f32_e32 v87, 1.0, v87
; __device__ __forceinline__ u16 f2bf(float x) { return (u16)(cvtpk(x, x) & 0xffffu); }
; #define UNR _Pragma("unroll")
; template <int EPI, int lda, int ldb, int N, int K>
; __device__ __forceinline__ void gemm_phase(const u16* __restrict__ A, const u16* __restrict__ Bt, const GemmEpi ep, int wv) {
;     ...
;     if constexpr (EPI == EPI_SWIGLU) {
;       u16* out = reinterpret_cast<u16*>(ep.out0);
;       UNR for (int ai = 0; ai < 2; ++ai) UNR for (int m = 0; m < 4; ++m) {
;         const int rl0 = ai * HALF + wr * 64 + m * 16 + fq * 4;
;         const f32x4 r4 = *reinterpret_cast<const f32x4*>(lrs + rl0);
;         UNR for (int j = 0; j < 4; ++j) {
;           const int row = brow + rl0 + j;
;           const float rs = r4[j], ce = -1.4426950408889634f * rs, r2 = rs * rs;
;           UNR for (int n = 0; n < 2; ++n) {
;             const int col = (bcol >> 1) + wc * 32 + n * 16 + fr;
;             const float g = acc[ai][0][m][n][j], u = acc[ai][1][m][n][j];
;             const float sg = __builtin_amdgcn_rcpf(1.f + __builtin_amdgcn_exp2f(ce * g));
;             out[(size_t)row * ep.ldc + col] = f2bf((g * u) * (r2 * sg));
;           }
;         }
;       }
	v_rcp_f32_e32 v86, v86
	v_rcp_f32_e32 v87, v87
	v_mul_f32_e32 v86, v149, v86
	v_mul_f32_e32 v87, v149, v87
	v_mul_f32_e32 v94, v94, v86
	v_mul_f32_e32 v95, v95, v87
	v_cvt_pk_bf16_f32 v85, v94, v95
	v_mul_f32_e32 v88, v80, v88
	v_mul_f32_e32 v89, v81, v89
	v_mul_f32_e32 v80, v135, v80
	v_mul_f32_e32 v81, v135, v81
	v_exp_f32_e32 v80, v80
	v_exp_f32_e32 v81, v81
	v_add_f32_e32 v80, 1.0, v80
	v_add_f32_e32 v81, 1.0, v81
	v_rcp_f32_e32 v80, v80
	v_rcp_f32_e32 v81, v81
	v_mul_f32_e32 v80, v149, v80
	v_mul_f32_e32 v81, v149, v81
	v_mul_f32_e32 v88, v88, v80
	v_mul_f32_e32 v89, v89, v81
	v_cvt_pk_bf16_f32 v86, v88, v89
	v_mul_f32_e32 v90, v82, v90
	v_mul_f32_e32 v91, v83, v91
	v_mul_f32_e32 v82, v135, v82
	v_mul_f32_e32 v83, v135, v83
	v_exp_f32_e32 v82, v82
	v_exp_f32_e32 v83, v83
	v_add_f32_e32 v82, 1.0, v82
	v_add_f32_e32 v83, 1.0, v83
	v_rcp_f32_e32 v82, v82
	v_rcp_f32_e32 v83, v83
	v_mul_f32_e32 v82, v149, v82
	v_mul_f32_e32 v83, v149, v83
	v_mul_f32_e32 v90, v90, v82
	v_mul_f32_e32 v91, v91, v83
	v_cvt_pk_bf16_f32 v87, v90, v91
	s_nop 1
	v_permlane16_swap_b32_e32 v84, v86
	v_permlane16_swap_b32_e32 v85, v87
	global_store_dwordx4 v134, v[84:87], s[10:11]
	v_add_u32_e32 v134, 0x81000, v132
	v_mul_f32_e32 v135, 0xbfb8aa3b, v153
	v_mul_f32_e32 v149, v153, v153
	ds_read_b32 v153, v133 offset:704
	v_mul_f32_e32 v76, v68, v76
	v_mul_f32_e32 v77, v69, v77
	v_mul_f32_e32 v68, v135, v68
	v_mul_f32_e32 v69, v135, v69
	v_exp_f32_e32 v68, v68
	v_exp_f32_e32 v69, v69
	v_add_f32_e32 v68, 1.0, v68
	v_add_f32_e32 v69, 1.0, v69
	v_rcp_f32_e32 v68, v68
	v_rcp_f32_e32 v69, v69
	v_mul_f32_e32 v68, v149, v68
	v_mul_f32_e32 v69, v149, v69
	v_mul_f32_e32 v76, v76, v68
	v_mul_f32_e32 v77, v77, v69
	v_cvt_pk_bf16_f32 v68, v76, v77
	v_mul_f32_e32 v78, v70, v78
	v_mul_f32_e32 v79, v71, v79
	v_mul_f32_e32 v70, v135, v70
	v_mul_f32_e32 v71, v135, v71
	v_exp_f32_e32 v70, v70
	v_exp_f32_e32 v71, v71
	v_add_f32_e32 v70, 1.0, v70
	v_add_f32_e32 v71, 1.0, v71
	v_rcp_f32_e32 v70, v70
	v_rcp_f32_e32 v71, v71
	v_mul_f32_e32 v70, v149, v70
	v_mul_f32_e32 v71, v149, v71
	v_mul_f32_e32 v78, v78, v70
	v_mul_f32_e32 v79, v79, v71
	v_cvt_pk_bf16_f32 v69, v78, v79
	v_mul_f32_e32 v72, v64, v72
	v_mul_f32_e32 v73, v65, v73
	v_mul_f32_e32 v64, v135, v64
	v_mul_f32_e32 v65, v135, v65
	v_exp_f32_e32 v64, v64
	v_exp_f32_e32 v65, v65
	v_add_f32_e32 v64, 1.0, v64
	v_add_f32_e32 v65, 1.0, v65
	v_rcp_f32_e32 v64, v64
	v_rcp_f32_e32 v65, v65
	v_mul_f32_e32 v64, v149, v64
	v_mul_f32_e32 v65, v149, v65
	v_mul_f32_e32 v72, v72, v64
	v_mul_f32_e32 v73, v73, v65
	v_cvt_pk_bf16_f32 v70, v72, v73
	v_mul_f32_e32 v74, v66, v74
	v_mul_f32_e32 v75, v67, v75
	v_mul_f32_e32 v66, v135, v66
	v_mul_f32_e32 v67, v135, v67
	v_exp_f32_e32 v66, v66
	v_exp_f32_e32 v67, v67
	v_add_f32_e32 v66, 1.0, v66
	v_add_f32_e32 v67, 1.0, v67
	v_rcp_f32_e32 v66, v66
	v_rcp_f32_e32 v67, v67
	v_mul_f32_e32 v66, v149, v66
	v_mul_f32_e32 v67, v149, v67
	v_mul_f32_e32 v74, v74, v66
	v_mul_f32_e32 v75, v75, v67
	v_cvt_pk_bf16_f32 v71, v74, v75
	s_nop 1
	v_permlane16_swap_b32_e32 v68, v70
	v_permlane16_swap_b32_e32 v69, v71
	global_store_dwordx4 v134, v[68:71], s[10:11]
	s_waitcnt lgkmcnt(0)
	v_add_u32_e32 v134, 0x158000, v132
	v_mul_f32_e32 v135, 0xbfb8aa3b, v150
	v_mul_f32_e32 v149, v150, v150
	v_mul_f32_e32 v60, v52, v60
	v_mul_f32_e32 v61, v53, v61
	v_mul_f32_e32 v52, v135, v52
	v_mul_f32_e32 v53, v135, v53
	v_exp_f32_e32 v52, v52
	v_exp_f32_e32 v53, v53
	v_add_f32_e32 v52, 1.0, v52
	v_add_f32_e32 v53, 1.0, v53
	v_rcp_f32_e32 v52, v52
	v_rcp_f32_e32 v53, v53
	v_mul_f32_e32 v52, v149, v52
	v_mul_f32_e32 v53, v149, v53
	v_mul_f32_e32 v60, v60, v52
	v_mul_f32_e32 v61, v61, v53
	v_cvt_pk_bf16_f32 v52, v60, v61
	v_mul_f32_e32 v62, v54, v62
	v_mul_f32_e32 v63, v55, v63
	v_mul_f32_e32 v54, v135, v54
	v_mul_f32_e32 v55, v135, v55
	v_exp_f32_e32 v54, v54
	v_exp_f32_e32 v55, v55
	v_add_f32_e32 v54, 1.0, v54
	v_add_f32_e32 v55, 1.0, v55
	v_rcp_f32_e32 v54, v54
	v_rcp_f32_e32 v55, v55
	v_mul_f32_e32 v54, v149, v54
	v_mul_f32_e32 v55, v149, v55
	v_mul_f32_e32 v62, v62, v54
	v_mul_f32_e32 v63, v63, v55
	v_cvt_pk_bf16_f32 v53, v62, v63
	v_mul_f32_e32 v56, v48, v56
	v_mul_f32_e32 v57, v49, v57
	v_mul_f32_e32 v48, v135, v48
	v_mul_f32_e32 v49, v135, v49
	v_exp_f32_e32 v48, v48
	v_exp_f32_e32 v49, v49
	v_add_f32_e32 v48, 1.0, v48
	v_add_f32_e32 v49, 1.0, v49
	v_rcp_f32_e32 v48, v48
	v_rcp_f32_e32 v49, v49
	v_mul_f32_e32 v48, v149, v48
	v_mul_f32_e32 v49, v149, v49
	v_mul_f32_e32 v56, v56, v48
	v_mul_f32_e32 v57, v57, v49
	v_cvt_pk_bf16_f32 v54, v56, v57
	v_mul_f32_e32 v58, v50, v58
	v_mul_f32_e32 v59, v51, v59
	v_mul_f32_e32 v50, v135, v50
	v_mul_f32_e32 v51, v135, v51
	v_exp_f32_e32 v50, v50
	v_exp_f32_e32 v51, v51
	v_add_f32_e32 v50, 1.0, v50
	v_add_f32_e32 v51, 1.0, v51
	v_rcp_f32_e32 v50, v50
	v_rcp_f32_e32 v51, v51
	v_mul_f32_e32 v50, v149, v50
	v_mul_f32_e32 v51, v149, v51
	v_mul_f32_e32 v58, v58, v50
	v_mul_f32_e32 v59, v59, v51
	v_cvt_pk_bf16_f32 v55, v58, v59
	s_nop 1
	v_permlane16_swap_b32_e32 v52, v54
	v_permlane16_swap_b32_e32 v53, v55
	global_store_dwordx4 v134, v[52:55], s[10:11]
	v_add_u32_e32 v134, 0x183000, v132
	v_mul_f32_e32 v135, 0xbfb8aa3b, v151
	v_mul_f32_e32 v149, v151, v151
	v_mul_f32_e32 v44, v36, v44
	v_mul_f32_e32 v45, v37, v45
	v_mul_f32_e32 v36, v135, v36
	v_mul_f32_e32 v37, v135, v37
	v_exp_f32_e32 v36, v36
	v_exp_f32_e32 v37, v37
	v_add_f32_e32 v36, 1.0, v36
	v_add_f32_e32 v37, 1.0, v37
	v_rcp_f32_e32 v36, v36
	v_rcp_f32_e32 v37, v37
	v_mul_f32_e32 v36, v149, v36
	v_mul_f32_e32 v37, v149, v37
	v_mul_f32_e32 v44, v44, v36
	v_mul_f32_e32 v45, v45, v37
	v_cvt_pk_bf16_f32 v36, v44, v45
	v_mul_f32_e32 v46, v38, v46
; __device__ __forceinline__ u16 f2bf(float x) { return (u16)(cvtpk(x, x) & 0xffffu); }
; #define UNR _Pragma("unroll")
; #define WAIT_V(n) asm volatile("s_waitcnt vmcnt(" #n ")" ::: "memory")
; template <int EPI, int lda, int ldb, int N, int K>
; __device__ __forceinline__ void gemm_phase(const u16* __restrict__ A, const u16* __restrict__ Bt, const GemmEpi ep, int wv) {
;     ...
;     if constexpr (EPI == EPI_SWIGLU) {
;       u16* out = reinterpret_cast<u16*>(ep.out0);
;       UNR for (int ai = 0; ai < 2; ++ai) UNR for (int m = 0; m < 4; ++m) {
;         const int rl0 = ai * HALF + wr * 64 + m * 16 + fq * 4;
;         const f32x4 r4 = *reinterpret_cast<const f32x4*>(lrs + rl0);
;         UNR for (int j = 0; j < 4; ++j) {
;           const int row = brow + rl0 + j;
;           const float rs = r4[j], ce = -1.4426950408889634f * rs, r2 = rs * rs;
;           UNR for (int n = 0; n < 2; ++n) {
;             const int col = (bcol >> 1) + wc * 32 + n * 16 + fr;
;             const float g = acc[ai][0][m][n][j], u = acc[ai][1][m][n][j];
;             const float sg = __builtin_amdgcn_rcpf(1.f + __builtin_amdgcn_exp2f(ce * g));
;             out[(size_t)row * ep.ldc + col] = f2bf((g * u) * (r2 * sg));
;           }
;         }
;       }
;     ...
;     if constexpr (PF) {
;       WAIT_V(0);
;       __syncthreads();
;       if constexpr (CONS) { if (more && tidx < 256) { float sq = 0.f; UNR for (int pp = 0; pp < 8; ++pp) sq += nss[pp];
;         lrs[tidx] = rsqrtf(sq * (1.f / DM) + 1e-6f); } }
;       if (!more) break;
	v_mul_f32_e32 v47, v39, v47
	v_mul_f32_e32 v38, v135, v38
	v_mul_f32_e32 v39, v135, v39
	v_exp_f32_e32 v38, v38
	v_exp_f32_e32 v39, v39
	v_add_f32_e32 v38, 1.0, v38
	v_add_f32_e32 v39, 1.0, v39
	v_rcp_f32_e32 v38, v38
	v_rcp_f32_e32 v39, v39
	v_mul_f32_e32 v38, v149, v38
	v_mul_f32_e32 v39, v149, v39
	v_mul_f32_e32 v46, v46, v38
	v_mul_f32_e32 v47, v47, v39
	v_cvt_pk_bf16_f32 v37, v46, v47
	v_mul_f32_e32 v40, v32, v40
	v_mul_f32_e32 v41, v33, v41
	v_mul_f32_e32 v32, v135, v32
	v_mul_f32_e32 v33, v135, v33
	v_exp_f32_e32 v32, v32
	v_exp_f32_e32 v33, v33
	v_add_f32_e32 v32, 1.0, v32
	v_add_f32_e32 v33, 1.0, v33
	v_rcp_f32_e32 v32, v32
	v_rcp_f32_e32 v33, v33
	v_mul_f32_e32 v32, v149, v32
	v_mul_f32_e32 v33, v149, v33
	v_mul_f32_e32 v40, v40, v32
	v_mul_f32_e32 v41, v41, v33
	v_cvt_pk_bf16_f32 v38, v40, v41
	v_mul_f32_e32 v42, v34, v42
	v_mul_f32_e32 v43, v35, v43
	v_mul_f32_e32 v34, v135, v34
	v_mul_f32_e32 v35, v135, v35
	v_exp_f32_e32 v34, v34
	v_exp_f32_e32 v35, v35
	v_add_f32_e32 v34, 1.0, v34
	v_add_f32_e32 v35, 1.0, v35
	v_rcp_f32_e32 v34, v34
	v_rcp_f32_e32 v35, v35
	v_mul_f32_e32 v34, v149, v34
	v_mul_f32_e32 v35, v149, v35
	v_mul_f32_e32 v42, v42, v34
	v_mul_f32_e32 v43, v43, v35
	v_cvt_pk_bf16_f32 v39, v42, v43
	s_nop 1
	v_permlane16_swap_b32_e32 v36, v38
	v_permlane16_swap_b32_e32 v37, v39
	global_store_dwordx4 v134, v[36:39], s[10:11]
	v_add_u32_e32 v134, 0x1ae000, v132
	v_mul_f32_e32 v135, 0xbfb8aa3b, v152
	v_mul_f32_e32 v149, v152, v152
	v_mul_f32_e32 v28, v20, v28
	v_mul_f32_e32 v29, v21, v29
	v_mul_f32_e32 v20, v135, v20
	v_mul_f32_e32 v21, v135, v21
	v_exp_f32_e32 v20, v20
	v_exp_f32_e32 v21, v21
	v_add_f32_e32 v20, 1.0, v20
	v_add_f32_e32 v21, 1.0, v21
	v_rcp_f32_e32 v20, v20
	v_rcp_f32_e32 v21, v21
	v_mul_f32_e32 v20, v149, v20
	v_mul_f32_e32 v21, v149, v21
	v_mul_f32_e32 v28, v28, v20
	v_mul_f32_e32 v29, v29, v21
	v_cvt_pk_bf16_f32 v20, v28, v29
	v_mul_f32_e32 v30, v22, v30
	v_mul_f32_e32 v31, v23, v31
	v_mul_f32_e32 v22, v135, v22
	v_mul_f32_e32 v23, v135, v23
	v_exp_f32_e32 v22, v22
	v_exp_f32_e32 v23, v23
	v_add_f32_e32 v22, 1.0, v22
	v_add_f32_e32 v23, 1.0, v23
	v_rcp_f32_e32 v22, v22
	v_rcp_f32_e32 v23, v23
	v_mul_f32_e32 v22, v149, v22
	v_mul_f32_e32 v23, v149, v23
	v_mul_f32_e32 v30, v30, v22
	v_mul_f32_e32 v31, v31, v23
	v_cvt_pk_bf16_f32 v21, v30, v31
	v_mul_f32_e32 v24, v16, v24
	v_mul_f32_e32 v25, v17, v25
	v_mul_f32_e32 v16, v135, v16
	v_mul_f32_e32 v17, v135, v17
	v_exp_f32_e32 v16, v16
	v_exp_f32_e32 v17, v17
	v_add_f32_e32 v16, 1.0, v16
	v_add_f32_e32 v17, 1.0, v17
	v_rcp_f32_e32 v16, v16
	v_rcp_f32_e32 v17, v17
	v_mul_f32_e32 v16, v149, v16
	v_mul_f32_e32 v17, v149, v17
	v_mul_f32_e32 v24, v24, v16
	v_mul_f32_e32 v25, v25, v17
	v_cvt_pk_bf16_f32 v22, v24, v25
	v_mul_f32_e32 v26, v18, v26
	v_mul_f32_e32 v27, v19, v27
	v_mul_f32_e32 v18, v135, v18
	v_mul_f32_e32 v19, v135, v19
	v_exp_f32_e32 v18, v18
	v_exp_f32_e32 v19, v19
	v_add_f32_e32 v18, 1.0, v18
	v_add_f32_e32 v19, 1.0, v19
	v_rcp_f32_e32 v18, v18
	v_rcp_f32_e32 v19, v19
	v_mul_f32_e32 v18, v149, v18
	v_mul_f32_e32 v19, v149, v19
	v_mul_f32_e32 v26, v26, v18
	v_mul_f32_e32 v27, v27, v19
	v_cvt_pk_bf16_f32 v23, v26, v27
	s_nop 1
	v_permlane16_swap_b32_e32 v20, v22
	v_permlane16_swap_b32_e32 v21, v23
	global_store_dwordx4 v134, v[20:23], s[10:11]
	v_add_u32_e32 v134, 0x1d9000, v132
	v_mul_f32_e32 v135, 0xbfb8aa3b, v153
	v_mul_f32_e32 v149, v153, v153
	v_mul_f32_e32 v12, v4, v12
	v_mul_f32_e32 v13, v5, v13
	v_mul_f32_e32 v4, v135, v4
	v_mul_f32_e32 v5, v135, v5
	v_exp_f32_e32 v4, v4
	v_exp_f32_e32 v5, v5
	v_add_f32_e32 v4, 1.0, v4
	v_add_f32_e32 v5, 1.0, v5
	v_rcp_f32_e32 v4, v4
	v_rcp_f32_e32 v5, v5
	v_mul_f32_e32 v4, v149, v4
	v_mul_f32_e32 v5, v149, v5
	v_mul_f32_e32 v12, v12, v4
	v_mul_f32_e32 v13, v13, v5
	v_cvt_pk_bf16_f32 v4, v12, v13
	v_mul_f32_e32 v14, v6, v14
	v_mul_f32_e32 v15, v7, v15
	v_mul_f32_e32 v6, v135, v6
	v_mul_f32_e32 v7, v135, v7
	v_exp_f32_e32 v6, v6
	v_exp_f32_e32 v7, v7
	v_add_f32_e32 v6, 1.0, v6
	v_add_f32_e32 v7, 1.0, v7
	v_rcp_f32_e32 v6, v6
	v_rcp_f32_e32 v7, v7
	v_mul_f32_e32 v6, v149, v6
	v_mul_f32_e32 v7, v149, v7
	v_mul_f32_e32 v14, v14, v6
	v_mul_f32_e32 v15, v15, v7
	v_cvt_pk_bf16_f32 v5, v14, v15
	v_mul_f32_e32 v8, v0, v8
	v_mul_f32_e32 v9, v1, v9
	v_mul_f32_e32 v0, v135, v0
	v_mul_f32_e32 v1, v135, v1
	v_exp_f32_e32 v0, v0
	v_exp_f32_e32 v1, v1
	v_add_f32_e32 v0, 1.0, v0
	v_add_f32_e32 v1, 1.0, v1
	v_rcp_f32_e32 v0, v0
	v_rcp_f32_e32 v1, v1
	v_mul_f32_e32 v0, v149, v0
	v_mul_f32_e32 v1, v149, v1
	v_mul_f32_e32 v8, v8, v0
	v_mul_f32_e32 v9, v9, v1
	v_cvt_pk_bf16_f32 v6, v8, v9
	v_mul_f32_e32 v10, v2, v10
	v_mul_f32_e32 v11, v3, v11
	v_mul_f32_e32 v2, v135, v2
	v_mul_f32_e32 v3, v135, v3
	v_exp_f32_e32 v2, v2
	v_exp_f32_e32 v3, v3
	v_add_f32_e32 v2, 1.0, v2
	v_add_f32_e32 v3, 1.0, v3
	v_rcp_f32_e32 v2, v2
	v_rcp_f32_e32 v3, v3
	v_mul_f32_e32 v2, v149, v2
	v_mul_f32_e32 v3, v149, v3
	v_mul_f32_e32 v10, v10, v2
	v_mul_f32_e32 v11, v11, v3
	v_cvt_pk_bf16_f32 v7, v10, v11
	s_nop 1
	v_permlane16_swap_b32_e32 v4, v6
	v_permlane16_swap_b32_e32 v5, v7
	global_store_dwordx4 v134, v[4:7], s[10:11]
	s_waitcnt vmcnt(0)
	s_waitcnt vmcnt(0)
	v_add_f32_e32 v148, 0, v131
	s_barrier
	s_and_saveexec_b64 s[38:39], s[46:47]
	s_cbranch_execz .LBB0_49
	v_add_f32_e32 v0, v141, v148
	v_add_f32_e32 v0, v140, v0
	v_add_f32_e32 v0, v139, v0
	v_add_f32_e32 v0, v138, v0
	v_add_f32_e32 v0, v137, v0
	v_add_f32_e32 v0, v136, v0
	v_add_f32_e32 v0, v128, v0
	v_fmamk_f32 v0, v0, 0x3a000000, v143
	v_mul_f32_e32 v1, 0x4b800000, v0
	v_cmp_gt_f32_e32 vcc, s64, v0
	s_nop 1
	v_cndmask_b32_e32 v0, v0, v1, vcc
	v_rsq_f32_e32 v0, v0
	v_lshl_add_u32 v1, v130, 2, 0
	v_add_u32_e32 v1, 0x20000, v1
	v_mul_f32_e32 v2, 0x45800000, v0
	v_cndmask_b32_e32 v0, v0, v2, vcc
	ds_write_b32 v1, v0
	s_branch .LBB0_49

; #define STAGE(P, BASE, LD, br, kt) do { const char* _g = (const char*)((BASE) + (size_t)(br) * (LD) + (size_t)(kt) * 64); \
;     for (int _i = 0; _i < 2; ++_i) { int _b = tidx * 16 + _i * 8192; int _r, _c; stage_rc(_b, _r, _c); \
;       __builtin_amdgcn_global_load_lds((const unsigned*)(_g + (unsigned)((_r * (LD) + _c) * 2)), (unsigned*)((char*)(P) + _b), 16, 0, 0); } } while (0)
; #define LDA(dst, b, h) for (int m = 0; m < 4; ++m) for (int k = 0; k < 2; ++k) \
;     dst[m][k] = *reinterpret_cast<const bf16x8*>((char*)SA(b, h) + lds_byte(wr * 64 + m * 16 + fr, k * 32 + fq * 8))
; #define LDB(dst, b, h) for (int n = 0; n < 2; ++n) for (int k = 0; k < 2; ++k) \
;     dst[n][k] = *reinterpret_cast<const bf16x8*>((char*)SB(b, h) + lds_byte(wc * 32 + n * 16 + fr, k * 32 + fq * 8))
; #define MMA(ai, bj, At_, Bt_) do { __builtin_amdgcn_s_setprio(1); \
;     for (int k = 0; k < 2; ++k) for (int m = 0; m < 4; ++m) for (int n = 0; n < 2; ++n) \
;       acc[ai][bj][m][n] = __builtin_amdgcn_mfma_f32_16x16x32_bf16(At_[m][k], Bt_[n][k], acc[ai][bj][m][n], 0, 0, 0); \
;     __builtin_amdgcn_s_setprio(0); } while (0)
; #define WAIT_V(n) asm volatile("s_waitcnt vmcnt(" #n ")" ::: "memory")
; #define WAIT_L(n) asm volatile("s_waitcnt lgkmcnt(" #n ")" ::: "memory")
; #define BAR __builtin_amdgcn_s_barrier()
; #define SCHED __builtin_amdgcn_sched_barrier(0)
; template <int EPI, int lda, int ldb, int N, int K>
; __device__ __forceinline__ void gemm_phase(const u16* __restrict__ A, const u16* __restrict__ Bt, const GemmEpi ep, int wv) {
;     ...
;     for (int t = 0; t < nt - 2; t += 2) {
;       LDB(B0, 0, 0); SCHED; LDA(At, 0, 0); STAGE(SA(1, 1), Ab, lda, brow + HALF, t + 1);
;       WAIT_L(8); BAR; WAIT_L(0); MMA(0, 0, At, B0); BAR; SCHED;
;       LDB(B1, 0, 1); STAGE(SB(0, 0), Bt, ldb, bcol, t + 2);
;       BAR; WAIT_L(0); MMA(0, 1, At, B1); BAR;
;       LDA(At, 0, 1); STAGE(SA(0, 0), Ab, lda, brow, t + 2);
;       BAR; WAIT_L(0); MMA(1, 0, At, B0); BAR; SCHED;
;       STAGE(SB(0, 1), Bt, ldb, bcol + HALF, t + 2);
;       WAIT_V(6); BAR; MMA(1, 1, At, B1); BAR;
;       LDB(B0, 1, 0); SCHED; LDA(At, 1, 0); STAGE(SA(0, 1), Ab, lda, brow + HALF, t + 2);
;       WAIT_L(8); BAR; WAIT_L(0); MMA(0, 0, At, B0); BAR; SCHED;
.LBB0_770:
	ds_read_b128 v[172:175], v161
	ds_read_b128 v[176:179], v161 offset:1024
	ds_read_b128 v[180:183], v161 offset:2048
	ds_read_b128 v[184:187], v161 offset:3072
	v_add_u32_e32 v169, 0xc000, v148
	v_lshl_add_u64 v[236:237], v[136:137], 0, s[50:51]
	v_readfirstlane_b32 s53, v169
	v_add_u32_e32 v170, 0xe000, v148
	v_lshl_add_u64 v[162:163], v[236:237], 0, s[18:19]
	s_mov_b32 m0, s53
	v_lshl_add_u64 v[238:239], v[134:135], 0, s[50:51]
	v_readfirstlane_b32 s53, v170
	ds_read_b128 v[164:167], v152
	ds_read_b128 v[188:191], v152 offset:1024
	ds_read_b128 v[192:195], v151
	ds_read_b128 v[196:199], v151 offset:1024
	ds_read_b128 v[200:203], v150
	ds_read_b128 v[204:207], v150 offset:1024
	ds_read_b128 v[208:211], v149
	ds_read_b128 v[212:215], v149 offset:1024
	global_load_lds_dwordx4 v[162:163], off
	v_lshl_add_u64 v[162:163], v[238:239], 0, s[18:19]
	s_mov_b32 m0, s53
	s_nop 0
	global_load_lds_dwordx4 v[162:163], off
	s_waitcnt lgkmcnt(8)
	s_barrier
	s_waitcnt lgkmcnt(0)
	s_setprio 1
	s_waitcnt lgkmcnt(0)
	v_mfma_f32_16x16x32_bf16 v[124:127], v[172:175], v[164:167], v[124:127]
	v_mfma_f32_16x16x32_bf16 v[120:123], v[180:183], v[164:167], v[120:123]
	v_mfma_f32_16x16x32_bf16 v[116:119], v[172:175], v[192:195], v[116:119]
	v_mfma_f32_16x16x32_bf16 v[112:115], v[180:183], v[192:195], v[112:115]
	v_mfma_f32_16x16x32_bf16 v[108:111], v[172:175], v[200:203], v[108:111]
	v_mfma_f32_16x16x32_bf16 v[104:107], v[180:183], v[200:203], v[104:107]
	v_mfma_f32_16x16x32_bf16 v[100:103], v[172:175], v[208:211], v[100:103]
	v_mfma_f32_16x16x32_bf16 v[96:99], v[180:183], v[208:211], v[96:99]
	v_mfma_f32_16x16x32_bf16 v[124:127], v[176:179], v[188:191], v[124:127]
	v_mfma_f32_16x16x32_bf16 v[120:123], v[184:187], v[188:191], v[120:123]
	v_mfma_f32_16x16x32_bf16 v[116:119], v[176:179], v[196:199], v[116:119]
	v_mfma_f32_16x16x32_bf16 v[112:115], v[184:187], v[196:199], v[112:115]
	v_mfma_f32_16x16x32_bf16 v[108:111], v[176:179], v[204:207], v[108:111]
	v_mfma_f32_16x16x32_bf16 v[104:107], v[184:187], v[204:207], v[104:107]
	v_mfma_f32_16x16x32_bf16 v[100:103], v[176:179], v[212:215], v[100:103]
	v_mfma_f32_16x16x32_bf16 v[96:99], v[184:187], v[212:215], v[96:99]
	s_setprio 0
	s_barrier
	v_add_u32_e32 v162, s64, v153
	v_lshl_add_u64 v[240:241], v[140:141], 0, s[50:51]
	v_readfirstlane_b32 s53, v162
	v_add_u32_e32 v163, 0x2000, v162
	v_lshl_add_u64 v[232:233], v[240:241], 0, s[20:21]
	s_mov_b32 m0, s53
	v_lshl_add_u64 v[242:243], v[138:139], 0, s[50:51]
	v_readfirstlane_b32 s53, v163
	ds_read_b128 v[216:219], v160
	ds_read_b128 v[220:223], v160 offset:1024
	ds_read_b128 v[224:227], v160 offset:2048
	ds_read_b128 v[228:231], v160 offset:3072
	global_load_lds_dwordx4 v[232:233], off
	v_lshl_add_u64 v[232:233], v[242:243], 0, s[20:21]
	s_mov_b32 m0, s53
	s_nop 0
	global_load_lds_dwordx4 v[232:233], off
	s_barrier
	s_waitcnt lgkmcnt(0)
	s_setprio 1
	s_waitcnt lgkmcnt(0)
	v_mfma_f32_16x16x32_bf16 v[92:95], v[216:219], v[164:167], v[92:95]
	v_mfma_f32_16x16x32_bf16 v[88:91], v[224:227], v[164:167], v[88:91]
	v_mfma_f32_16x16x32_bf16 v[84:87], v[216:219], v[192:195], v[84:87]
	v_mfma_f32_16x16x32_bf16 v[80:83], v[224:227], v[192:195], v[80:83]
	v_mfma_f32_16x16x32_bf16 v[76:79], v[216:219], v[200:203], v[76:79]
	v_mfma_f32_16x16x32_bf16 v[72:75], v[224:227], v[200:203], v[72:75]
	v_mfma_f32_16x16x32_bf16 v[68:71], v[216:219], v[208:211], v[68:71]
	v_mfma_f32_16x16x32_bf16 v[64:67], v[224:227], v[208:211], v[64:67]
	v_mfma_f32_16x16x32_bf16 v[92:95], v[220:223], v[188:191], v[92:95]
	v_mfma_f32_16x16x32_bf16 v[88:91], v[228:231], v[188:191], v[88:91]
	v_mfma_f32_16x16x32_bf16 v[84:87], v[220:223], v[196:199], v[84:87]
	v_mfma_f32_16x16x32_bf16 v[80:83], v[228:231], v[196:199], v[80:83]
	v_mfma_f32_16x16x32_bf16 v[76:79], v[220:223], v[204:207], v[76:79]
	v_mfma_f32_16x16x32_bf16 v[72:75], v[228:231], v[204:207], v[72:75]
	v_mfma_f32_16x16x32_bf16 v[68:71], v[220:223], v[212:215], v[68:71]
	v_mfma_f32_16x16x32_bf16 v[64:67], v[228:231], v[212:215], v[64:67]
	s_setprio 0
	v_readfirstlane_b32 s53, v148
	v_lshl_add_u64 v[164:165], v[236:237], 0, s[22:23]
	s_mov_b32 m0, s53
	s_barrier
	ds_read_b128 v[188:191], v152 offset:16384
	ds_read_b128 v[192:195], v152 offset:17408
	ds_read_b128 v[196:199], v151 offset:16384
	ds_read_b128 v[200:203], v151 offset:17408
	ds_read_b128 v[204:207], v150 offset:16384
	ds_read_b128 v[208:211], v150 offset:17408
	ds_read_b128 v[212:215], v149 offset:16384
	ds_read_b128 v[232:235], v149 offset:17408
	global_load_lds_dwordx4 v[164:165], off
	v_add_u32_e32 v164, 0x2000, v148
	v_lshl_add_u64 v[166:167], v[238:239], 0, s[22:23]
	v_readfirstlane_b32 s53, v164
	s_mov_b32 m0, s53
	s_nop 0
	global_load_lds_dwordx4 v[166:167], off
	s_barrier
	s_waitcnt lgkmcnt(0)
	s_setprio 1
	s_waitcnt lgkmcnt(0)
	v_mfma_f32_16x16x32_bf16 v[60:63], v[172:175], v[188:191], v[60:63]
	v_mfma_f32_16x16x32_bf16 v[56:59], v[180:183], v[188:191], v[56:59]
	v_mfma_f32_16x16x32_bf16 v[52:55], v[172:175], v[196:199], v[52:55]
	v_mfma_f32_16x16x32_bf16 v[48:51], v[180:183], v[196:199], v[48:51]
	v_mfma_f32_16x16x32_bf16 v[44:47], v[172:175], v[204:207], v[44:47]
	v_mfma_f32_16x16x32_bf16 v[40:43], v[180:183], v[204:207], v[40:43]
	v_mfma_f32_16x16x32_bf16 v[36:39], v[172:175], v[212:215], v[36:39]
	v_mfma_f32_16x16x32_bf16 v[32:35], v[180:183], v[212:215], v[32:35]
	v_mfma_f32_16x16x32_bf16 v[60:63], v[176:179], v[192:195], v[60:63]
	v_mfma_f32_16x16x32_bf16 v[56:59], v[184:187], v[192:195], v[56:59]
	v_mfma_f32_16x16x32_bf16 v[52:55], v[176:179], v[200:203], v[52:55]
	v_mfma_f32_16x16x32_bf16 v[48:51], v[184:187], v[200:203], v[48:51]
	v_mfma_f32_16x16x32_bf16 v[44:47], v[176:179], v[208:211], v[44:47]
	v_mfma_f32_16x16x32_bf16 v[40:43], v[184:187], v[208:211], v[40:43]
	v_mfma_f32_16x16x32_bf16 v[36:39], v[176:179], v[232:235], v[36:39]
	v_mfma_f32_16x16x32_bf16 v[32:35], v[184:187], v[232:235], v[32:35]
	s_setprio 0
	s_barrier
; #define STAGE(P, BASE, LD, br, kt) do { const char* _g = (const char*)((BASE) + (size_t)(br) * (LD) + (size_t)(kt) * 64); \
;     for (int _i = 0; _i < 2; ++_i) { int _b = tidx * 16 + _i * 8192; int _r, _c; stage_rc(_b, _r, _c); \
;       __builtin_amdgcn_global_load_lds((const unsigned*)(_g + (unsigned)((_r * (LD) + _c) * 2)), (unsigned*)((char*)(P) + _b), 16, 0, 0); } } while (0)
; #define LDA(dst, b, h) for (int m = 0; m < 4; ++m) for (int k = 0; k < 2; ++k) \
;     dst[m][k] = *reinterpret_cast<const bf16x8*>((char*)SA(b, h) + lds_byte(wr * 64 + m * 16 + fr, k * 32 + fq * 8))
; #define LDB(dst, b, h) for (int n = 0; n < 2; ++n) for (int k = 0; k < 2; ++k) \
;     dst[n][k] = *reinterpret_cast<const bf16x8*>((char*)SB(b, h) + lds_byte(wc * 32 + n * 16 + fr, k * 32 + fq * 8))
; #define MMA(ai, bj, At_, Bt_) do { __builtin_amdgcn_s_setprio(1); \
;     for (int k = 0; k < 2; ++k) for (int m = 0; m < 4; ++m) for (int n = 0; n < 2; ++n) \
;       acc[ai][bj][m][n] = __builtin_amdgcn_mfma_f32_16x16x32_bf16(At_[m][k], Bt_[n][k], acc[ai][bj][m][n], 0, 0, 0); \
;     __builtin_amdgcn_s_setprio(0); } while (0)
; #define WAIT_V(n) asm volatile("s_waitcnt vmcnt(" #n ")" ::: "memory")
; #define WAIT_L(n) asm volatile("s_waitcnt lgkmcnt(" #n ")" ::: "memory")
; #define BAR __builtin_amdgcn_s_barrier()
; #define SCHED __builtin_amdgcn_sched_barrier(0)
; template <int EPI, int lda, int ldb, int N, int K>
; __device__ __forceinline__ void gemm_phase(const u16* __restrict__ A, const u16* __restrict__ Bt, const GemmEpi ep, int wv) {
;     ...
;       STAGE(SB(0, 1), Bt, ldb, bcol + HALF, t + 2);
;       WAIT_V(6); BAR; MMA(1, 1, At, B1); BAR;
;       LDB(B0, 1, 0); SCHED; LDA(At, 1, 0); STAGE(SA(0, 1), Ab, lda, brow + HALF, t + 2);
;       WAIT_L(8); BAR; WAIT_L(0); MMA(0, 0, At, B0); BAR; SCHED;
;       LDB(B1, 1, 1); STAGE(SB(1, 0), Bt, ldb, bcol, t + 3);
;       BAR; WAIT_L(0); MMA(0, 1, At, B1); BAR;
;       LDA(At, 1, 1); STAGE(SA(1, 0), Ab, lda, brow, t + 3);
;       BAR; WAIT_L(0); MMA(1, 0, At, B0); BAR; SCHED;
	v_add_u32_e32 v165, s65, v153
	v_lshl_add_u64 v[166:167], v[240:241], 0, s[24:25]
	v_readfirstlane_b32 s53, v165
	s_mov_b32 m0, s53
	v_lshl_add_u64 v[172:173], v[242:243], 0, s[24:25]
	global_load_lds_dwordx4 v[166:167], off
	v_add_u32_e32 v166, 0x2000, v165
	s_nop 0
	v_readfirstlane_b32 s53, v166
	s_mov_b32 m0, s53
	s_nop 0
	global_load_lds_dwordx4 v[172:173], off
	s_waitcnt vmcnt(6)
	s_barrier
	s_setprio 1
	v_mfma_f32_16x16x32_bf16 v[28:31], v[216:219], v[188:191], v[28:31]
	v_mfma_f32_16x16x32_bf16 v[24:27], v[224:227], v[188:191], v[24:27]
	v_mfma_f32_16x16x32_bf16 v[20:23], v[216:219], v[196:199], v[20:23]
	v_mfma_f32_16x16x32_bf16 v[16:19], v[224:227], v[196:199], v[16:19]
	v_mfma_f32_16x16x32_bf16 v[12:15], v[216:219], v[204:207], v[12:15]
	v_mfma_f32_16x16x32_bf16 v[8:11], v[224:227], v[204:207], v[8:11]
	v_mfma_f32_16x16x32_bf16 v[4:7], v[216:219], v[212:215], v[4:7]
	v_mfma_f32_16x16x32_bf16 v[0:3], v[224:227], v[212:215], v[0:3]
	v_mfma_f32_16x16x32_bf16 v[28:31], v[220:223], v[192:195], v[28:31]
	v_mfma_f32_16x16x32_bf16 v[24:27], v[228:231], v[192:195], v[24:27]
	v_mfma_f32_16x16x32_bf16 v[20:23], v[220:223], v[200:203], v[20:23]
	v_mfma_f32_16x16x32_bf16 v[16:19], v[228:231], v[200:203], v[16:19]
	v_mfma_f32_16x16x32_bf16 v[12:15], v[220:223], v[208:211], v[12:15]
	v_mfma_f32_16x16x32_bf16 v[8:11], v[228:231], v[208:211], v[8:11]
	v_mfma_f32_16x16x32_bf16 v[4:7], v[220:223], v[232:235], v[4:7]
	v_mfma_f32_16x16x32_bf16 v[0:3], v[228:231], v[232:235], v[0:3]
	s_setprio 0
	s_barrier
	ds_read_b128 v[172:175], v156
	ds_read_b128 v[176:179], v156 offset:1024
	ds_read_b128 v[180:183], v156 offset:2048
	ds_read_b128 v[184:187], v156 offset:3072
	v_add_u32_e32 v167, 0x4000, v148
	v_add_u32_e32 v168, 0x6000, v148
	v_readfirstlane_b32 s53, v167
	v_lshl_add_u64 v[220:221], v[236:237], 0, s[26:27]
	s_mov_b32 m0, s53
	v_readfirstlane_b32 s53, v168
	ds_read_b128 v[188:191], v152 offset:32768
	ds_read_b128 v[192:195], v152 offset:33792
	ds_read_b128 v[196:199], v151 offset:32768
	ds_read_b128 v[200:203], v151 offset:33792
	ds_read_b128 v[204:207], v150 offset:32768
	ds_read_b128 v[208:211], v150 offset:33792
	ds_read_b128 v[212:215], v149 offset:32768
	ds_read_b128 v[216:219], v149 offset:33792
	global_load_lds_dwordx4 v[220:221], off
	v_lshl_add_u64 v[220:221], v[238:239], 0, s[26:27]
	s_mov_b32 m0, s53
	s_nop 0
	global_load_lds_dwordx4 v[220:221], off
	s_waitcnt lgkmcnt(8)
	s_barrier
	s_waitcnt lgkmcnt(0)
	s_setprio 1
	s_waitcnt lgkmcnt(0)
	v_mfma_f32_16x16x32_bf16 v[124:127], v[172:175], v[188:191], v[124:127]
	v_mfma_f32_16x16x32_bf16 v[120:123], v[180:183], v[188:191], v[120:123]
	v_mfma_f32_16x16x32_bf16 v[116:119], v[172:175], v[196:199], v[116:119]
	v_mfma_f32_16x16x32_bf16 v[112:115], v[180:183], v[196:199], v[112:115]
	v_mfma_f32_16x16x32_bf16 v[108:111], v[172:175], v[204:207], v[108:111]
	v_mfma_f32_16x16x32_bf16 v[104:107], v[180:183], v[204:207], v[104:107]
	v_mfma_f32_16x16x32_bf16 v[100:103], v[172:175], v[212:215], v[100:103]
	v_mfma_f32_16x16x32_bf16 v[96:99], v[180:183], v[212:215], v[96:99]
	v_mfma_f32_16x16x32_bf16 v[124:127], v[176:179], v[192:195], v[124:127]
	v_mfma_f32_16x16x32_bf16 v[120:123], v[184:187], v[192:195], v[120:123]
	v_mfma_f32_16x16x32_bf16 v[116:119], v[176:179], v[200:203], v[116:119]
	v_mfma_f32_16x16x32_bf16 v[112:115], v[184:187], v[200:203], v[112:115]
	v_mfma_f32_16x16x32_bf16 v[108:111], v[176:179], v[208:211], v[108:111]
	v_mfma_f32_16x16x32_bf16 v[104:107], v[184:187], v[208:211], v[104:107]
	v_mfma_f32_16x16x32_bf16 v[100:103], v[176:179], v[216:219], v[100:103]
	v_mfma_f32_16x16x32_bf16 v[96:99], v[184:187], v[216:219], v[96:99]
	s_setprio 0
	s_barrier
	v_readfirstlane_b32 s53, v155
	v_add_u32_e32 v171, 0x2000, v155
	v_lshl_add_u64 v[244:245], v[240:241], 0, s[40:41]
	s_mov_b32 m0, s53
	v_readfirstlane_b32 s53, v171
	ds_read_b128 v[220:223], v154
	ds_read_b128 v[224:227], v154 offset:1024
	ds_read_b128 v[228:231], v154 offset:2048
	ds_read_b128 v[232:235], v154 offset:3072
	global_load_lds_dwordx4 v[244:245], off
	v_lshl_add_u64 v[244:245], v[242:243], 0, s[40:41]
	s_mov_b32 m0, s53
	s_nop 0
	global_load_lds_dwordx4 v[244:245], off
	s_barrier
	s_waitcnt lgkmcnt(0)
	s_setprio 1
	s_waitcnt lgkmcnt(0)
	v_mfma_f32_16x16x32_bf16 v[92:95], v[220:223], v[188:191], v[92:95]
	v_mfma_f32_16x16x32_bf16 v[88:91], v[228:231], v[188:191], v[88:91]
	v_mfma_f32_16x16x32_bf16 v[84:87], v[220:223], v[196:199], v[84:87]
	v_mfma_f32_16x16x32_bf16 v[80:83], v[228:231], v[196:199], v[80:83]
	v_mfma_f32_16x16x32_bf16 v[76:79], v[220:223], v[204:207], v[76:79]
	v_mfma_f32_16x16x32_bf16 v[72:75], v[228:231], v[204:207], v[72:75]
	v_mfma_f32_16x16x32_bf16 v[68:71], v[220:223], v[212:215], v[68:71]
	v_mfma_f32_16x16x32_bf16 v[64:67], v[228:231], v[212:215], v[64:67]
	v_mfma_f32_16x16x32_bf16 v[92:95], v[224:227], v[192:195], v[92:95]
	v_mfma_f32_16x16x32_bf16 v[88:91], v[232:235], v[192:195], v[88:91]
	v_mfma_f32_16x16x32_bf16 v[84:87], v[224:227], v[200:203], v[84:87]
	v_mfma_f32_16x16x32_bf16 v[80:83], v[232:235], v[200:203], v[80:83]
	v_mfma_f32_16x16x32_bf16 v[76:79], v[224:227], v[208:211], v[76:79]
	v_mfma_f32_16x16x32_bf16 v[72:75], v[232:235], v[208:211], v[72:75]
	v_mfma_f32_16x16x32_bf16 v[68:71], v[224:227], v[216:219], v[68:71]
	v_mfma_f32_16x16x32_bf16 v[64:67], v[232:235], v[216:219], v[64:67]
	s_setprio 0
	v_readfirstlane_b32 s53, v157
	v_lshl_add_u64 v[236:237], v[236:237], 0, s[42:43]
	s_mov_b32 m0, s53
	v_readfirstlane_b32 s53, v158
	s_barrier
; #define STAGE(P, BASE, LD, br, kt) do { const char* _g = (const char*)((BASE) + (size_t)(br) * (LD) + (size_t)(kt) * 64); \
;     for (int _i = 0; _i < 2; ++_i) { int _b = tidx * 16 + _i * 8192; int _r, _c; stage_rc(_b, _r, _c); \
;       __builtin_amdgcn_global_load_lds((const unsigned*)(_g + (unsigned)((_r * (LD) + _c) * 2)), (unsigned*)((char*)(P) + _b), 16, 0, 0); } } while (0)
; #define LDA(dst, b, h) for (int m = 0; m < 4; ++m) for (int k = 0; k < 2; ++k) \
;     dst[m][k] = *reinterpret_cast<const bf16x8*>((char*)SA(b, h) + lds_byte(wr * 64 + m * 16 + fr, k * 32 + fq * 8))
; #define LDB(dst, b, h) for (int n = 0; n < 2; ++n) for (int k = 0; k < 2; ++k) \
;     dst[n][k] = *reinterpret_cast<const bf16x8*>((char*)SB(b, h) + lds_byte(wc * 32 + n * 16 + fr, k * 32 + fq * 8))
; #define MMA(ai, bj, At_, Bt_) do { __builtin_amdgcn_s_setprio(1); \
;     for (int k = 0; k < 2; ++k) for (int m = 0; m < 4; ++m) for (int n = 0; n < 2; ++n) \
;       acc[ai][bj][m][n] = __builtin_amdgcn_mfma_f32_16x16x32_bf16(At_[m][k], Bt_[n][k], acc[ai][bj][m][n], 0, 0, 0); \
;     __builtin_amdgcn_s_setprio(0); } while (0)
; #define WAIT_V(n) asm volatile("s_waitcnt vmcnt(" #n ")" ::: "memory")
; #define WAIT_L(n) asm volatile("s_waitcnt lgkmcnt(" #n ")" ::: "memory")
; #define BAR __builtin_amdgcn_s_barrier()
; #define SCHED __builtin_amdgcn_sched_barrier(0)
; template <int EPI, int lda, int ldb, int N, int K>
; __device__ __forceinline__ void gemm_phase(const u16* __restrict__ A, const u16* __restrict__ Bt, const GemmEpi ep, int wv) {
;     ...
;       LDA(At, 1, 1); STAGE(SA(1, 0), Ab, lda, brow, t + 3);
;       BAR; WAIT_L(0); MMA(1, 0, At, B0); BAR; SCHED;
;       STAGE(SB(1, 1), Bt, ldb, bcol + HALF, t + 3);
;       WAIT_V(6); BAR; MMA(1, 1, At, B1); BAR;
;     }
;     { LDB(B0, 0, 0); LDA(At, 0, 0); STAGE(SA(1, 1), Ab, lda, brow + HALF, nt - 1);
;       BAR; WAIT_L(0); MMA(0, 0, At, B0); BAR;
	ds_read_b128 v[188:191], v152 offset:49152
	ds_read_b128 v[192:195], v152 offset:50176
	ds_read_b128 v[196:199], v151 offset:49152
	ds_read_b128 v[200:203], v151 offset:50176
	ds_read_b128 v[204:207], v150 offset:49152
	ds_read_b128 v[208:211], v150 offset:50176
	ds_read_b128 v[212:215], v149 offset:49152
	ds_read_b128 v[216:219], v149 offset:50176
	global_load_lds_dwordx4 v[236:237], off
	v_lshl_add_u64 v[236:237], v[238:239], 0, s[42:43]
	s_mov_b32 m0, s53
	s_nop 0
	global_load_lds_dwordx4 v[236:237], off
	s_barrier
	s_waitcnt lgkmcnt(0)
	s_setprio 1
	s_waitcnt lgkmcnt(0)
	v_mfma_f32_16x16x32_bf16 v[60:63], v[172:175], v[188:191], v[60:63]
	v_mfma_f32_16x16x32_bf16 v[56:59], v[180:183], v[188:191], v[56:59]
	v_mfma_f32_16x16x32_bf16 v[52:55], v[172:175], v[196:199], v[52:55]
	v_mfma_f32_16x16x32_bf16 v[48:51], v[180:183], v[196:199], v[48:51]
	v_mfma_f32_16x16x32_bf16 v[44:47], v[172:175], v[204:207], v[44:47]
	v_mfma_f32_16x16x32_bf16 v[40:43], v[180:183], v[204:207], v[40:43]
	v_mfma_f32_16x16x32_bf16 v[36:39], v[172:175], v[212:215], v[36:39]
	v_mfma_f32_16x16x32_bf16 v[32:35], v[180:183], v[212:215], v[32:35]
	v_mfma_f32_16x16x32_bf16 v[60:63], v[176:179], v[192:195], v[60:63]
	v_mfma_f32_16x16x32_bf16 v[56:59], v[184:187], v[192:195], v[56:59]
	v_mfma_f32_16x16x32_bf16 v[52:55], v[176:179], v[200:203], v[52:55]
	v_mfma_f32_16x16x32_bf16 v[48:51], v[184:187], v[200:203], v[48:51]
	v_mfma_f32_16x16x32_bf16 v[44:47], v[176:179], v[208:211], v[44:47]
	v_mfma_f32_16x16x32_bf16 v[40:43], v[184:187], v[208:211], v[40:43]
	v_mfma_f32_16x16x32_bf16 v[36:39], v[176:179], v[216:219], v[36:39]
	v_mfma_f32_16x16x32_bf16 v[32:35], v[184:187], v[216:219], v[32:35]
	s_setprio 0
	s_barrier
	v_readfirstlane_b32 s53, v159
	v_add_u32_e32 v171, 0x2000, v159
	v_lshl_add_u64 v[172:173], v[240:241], 0, s[44:45]
	s_mov_b32 m0, s53
	v_readfirstlane_b32 s53, v171
	global_load_lds_dwordx4 v[172:173], off
	v_lshl_add_u64 v[172:173], v[242:243], 0, s[44:45]
	s_mov_b32 m0, s53
	s_nop 0
	global_load_lds_dwordx4 v[172:173], off
	s_waitcnt vmcnt(6)
	s_barrier
	s_setprio 1
	v_mfma_f32_16x16x32_bf16 v[28:31], v[220:223], v[188:191], v[28:31]
	v_mfma_f32_16x16x32_bf16 v[24:27], v[228:231], v[188:191], v[24:27]
	v_mfma_f32_16x16x32_bf16 v[20:23], v[220:223], v[196:199], v[20:23]
	v_mfma_f32_16x16x32_bf16 v[16:19], v[228:231], v[196:199], v[16:19]
	v_mfma_f32_16x16x32_bf16 v[12:15], v[220:223], v[204:207], v[12:15]
	v_mfma_f32_16x16x32_bf16 v[8:11], v[228:231], v[204:207], v[8:11]
	v_mfma_f32_16x16x32_bf16 v[4:7], v[220:223], v[212:215], v[4:7]
	v_mfma_f32_16x16x32_bf16 v[0:3], v[228:231], v[212:215], v[0:3]
	v_mfma_f32_16x16x32_bf16 v[28:31], v[224:227], v[192:195], v[28:31]
	v_mfma_f32_16x16x32_bf16 v[24:27], v[232:235], v[192:195], v[24:27]
	v_mfma_f32_16x16x32_bf16 v[20:23], v[224:227], v[200:203], v[20:23]
	v_mfma_f32_16x16x32_bf16 v[16:19], v[232:235], v[200:203], v[16:19]
	v_mfma_f32_16x16x32_bf16 v[12:15], v[224:227], v[208:211], v[12:15]
	v_mfma_f32_16x16x32_bf16 v[8:11], v[232:235], v[208:211], v[8:11]
	v_mfma_f32_16x16x32_bf16 v[4:7], v[224:227], v[216:219], v[4:7]
	v_mfma_f32_16x16x32_bf16 v[0:3], v[232:235], v[216:219], v[0:3]
	s_setprio 0
	s_add_i32 s52, s52, 2
	s_add_u32 s50, s50, 0x100
	s_addc_u32 s51, s51, 0
	s_cmp_gt_u32 s52, 27
	s_barrier
	s_cbranch_scc0 .LBB0_770
	s_add_i32 s50, s48, 0x80
	s_mul_hi_i32 s51, s50, 0x1080
	s_mulk_i32 s50, 0x1080
	s_add_u32 s50, s61, s50
	s_addc_u32 s51, s62, s51
	v_lshl_add_u64 v[158:159], s[50:51], 0, v[128:129]
	v_readfirstlane_b32 s52, v169
	v_lshl_add_u64 v[158:159], v[158:159], 0, s[46:47]
	s_mov_b32 m0, s52
	ds_read_b128 v[134:137], v161
	ds_read_b128 v[138:141], v161 offset:1024
	ds_read_b128 v[172:175], v161 offset:2048
	ds_read_b128 v[176:179], v161 offset:3072
	ds_read_b128 v[180:183], v152
	ds_read_b128 v[184:187], v152 offset:1024
	ds_read_b128 v[188:191], v151
	ds_read_b128 v[192:195], v151 offset:1024
	ds_read_b128 v[196:199], v150
	ds_read_b128 v[200:203], v150 offset:1024
	ds_read_b128 v[204:207], v149
	ds_read_b128 v[208:211], v149 offset:1024
	global_load_lds_dwordx4 v[158:159], off
	v_lshl_add_u64 v[158:159], s[50:51], 0, v[132:133]
	v_readfirstlane_b32 s50, v170
	v_lshl_add_u64 v[158:159], v[158:159], 0, s[46:47]
	s_mov_b32 m0, s50
	s_nop 0
	global_load_lds_dwordx4 v[158:159], off
	s_barrier
	s_waitcnt lgkmcnt(0)
	s_setprio 1
	s_waitcnt lgkmcnt(0)
	v_mfma_f32_16x16x32_bf16 v[124:127], v[134:137], v[180:183], v[124:127]
	v_mfma_f32_16x16x32_bf16 v[120:123], v[172:175], v[180:183], v[120:123]
	v_mfma_f32_16x16x32_bf16 v[116:119], v[134:137], v[188:191], v[116:119]
	v_mfma_f32_16x16x32_bf16 v[112:115], v[172:175], v[188:191], v[112:115]
	v_mfma_f32_16x16x32_bf16 v[108:111], v[134:137], v[196:199], v[108:111]
	v_mfma_f32_16x16x32_bf16 v[104:107], v[172:175], v[196:199], v[104:107]
	v_mfma_f32_16x16x32_bf16 v[100:103], v[134:137], v[204:207], v[100:103]
	v_mfma_f32_16x16x32_bf16 v[96:99], v[172:175], v[204:207], v[96:99]
	v_mfma_f32_16x16x32_bf16 v[124:127], v[138:141], v[184:187], v[124:127]
	v_mfma_f32_16x16x32_bf16 v[120:123], v[176:179], v[184:187], v[120:123]
	v_mfma_f32_16x16x32_bf16 v[116:119], v[138:141], v[192:195], v[116:119]
	v_mfma_f32_16x16x32_bf16 v[112:115], v[176:179], v[192:195], v[112:115]
	v_mfma_f32_16x16x32_bf16 v[108:111], v[138:141], v[200:203], v[108:111]
	v_mfma_f32_16x16x32_bf16 v[104:107], v[176:179], v[200:203], v[104:107]
	v_mfma_f32_16x16x32_bf16 v[100:103], v[138:141], v[208:211], v[100:103]
	v_mfma_f32_16x16x32_bf16 v[96:99], v[176:179], v[208:211], v[96:99]
	s_setprio 0
	s_barrier
	ds_read_b128 v[212:215], v160
	ds_read_b128 v[216:219], v160 offset:1024
	ds_read_b128 v[220:223], v160 offset:2048
	ds_read_b128 v[158:161], v160 offset:3072
	s_barrier
; #define LDA(dst, b, h) for (int m = 0; m < 4; ++m) for (int k = 0; k < 2; ++k) \
;     dst[m][k] = *reinterpret_cast<const bf16x8*>((char*)SA(b, h) + lds_byte(wr * 64 + m * 16 + fr, k * 32 + fq * 8))
; #define LDB(dst, b, h) for (int n = 0; n < 2; ++n) for (int k = 0; k < 2; ++k) \
;     dst[n][k] = *reinterpret_cast<const bf16x8*>((char*)SB(b, h) + lds_byte(wc * 32 + n * 16 + fr, k * 32 + fq * 8))
; #define MMA(ai, bj, At_, Bt_) do { __builtin_amdgcn_s_setprio(1); \
;     for (int k = 0; k < 2; ++k) for (int m = 0; m < 4; ++m) for (int n = 0; n < 2; ++n) \
;       acc[ai][bj][m][n] = __builtin_amdgcn_mfma_f32_16x16x32_bf16(At_[m][k], Bt_[n][k], acc[ai][bj][m][n], 0, 0, 0); \
;     __builtin_amdgcn_s_setprio(0); } while (0)
; #define WAIT_V(n) asm volatile("s_waitcnt vmcnt(" #n ")" ::: "memory")
; #define WAIT_L(n) asm volatile("s_waitcnt lgkmcnt(" #n ")" ::: "memory")
; #define BAR __builtin_amdgcn_s_barrier()
; template <int EPI, int lda, int ldb, int N, int K>
; __device__ __forceinline__ void gemm_phase(const u16* __restrict__ A, const u16* __restrict__ Bt, const GemmEpi ep, int wv) {
;     ...
;       BAR; WAIT_L(0); MMA(0, 0, At, B0); BAR;
;       LDB(B1, 0, 1); BAR; WAIT_L(0); MMA(0, 1, At, B1); BAR;
;       LDA(At, 0, 1); WAIT_V(4); BAR; WAIT_L(0); MMA(1, 0, At, B0); MMA(1, 1, At, B1); BAR; }
;     { LDB(B0, 1, 0); LDA(At, 1, 0); WAIT_V(2); BAR; WAIT_L(0); MMA(0, 0, At, B0); BAR;
;       LDB(B1, 1, 1); WAIT_V(0); BAR; WAIT_L(0); MMA(0, 1, At, B1); BAR;
;       LDA(At, 1, 1); BAR; WAIT_L(0); MMA(1, 0, At, B0); MMA(1, 1, At, B1); BAR; }
	s_waitcnt lgkmcnt(0)
	s_setprio 1
	s_waitcnt lgkmcnt(0)
	v_mfma_f32_16x16x32_bf16 v[92:95], v[212:215], v[180:183], v[92:95]
	v_mfma_f32_16x16x32_bf16 v[88:91], v[220:223], v[180:183], v[88:91]
	v_mfma_f32_16x16x32_bf16 v[76:79], v[212:215], v[196:199], v[76:79]
	v_mfma_f32_16x16x32_bf16 v[72:75], v[220:223], v[196:199], v[72:75]
	v_mfma_f32_16x16x32_bf16 v[84:87], v[212:215], v[188:191], v[84:87]
	v_mfma_f32_16x16x32_bf16 v[80:83], v[220:223], v[188:191], v[80:83]
	v_mfma_f32_16x16x32_bf16 v[68:71], v[212:215], v[204:207], v[68:71]
	v_mfma_f32_16x16x32_bf16 v[64:67], v[220:223], v[204:207], v[64:67]
	v_mfma_f32_16x16x32_bf16 v[92:95], v[216:219], v[184:187], v[92:95]
	v_mfma_f32_16x16x32_bf16 v[88:91], v[158:161], v[184:187], v[88:91]
	v_mfma_f32_16x16x32_bf16 v[76:79], v[216:219], v[200:203], v[76:79]
	v_mfma_f32_16x16x32_bf16 v[72:75], v[158:161], v[200:203], v[72:75]
	v_mfma_f32_16x16x32_bf16 v[180:183], v[216:219], v[192:195], v[84:87]
	v_mfma_f32_16x16x32_bf16 v[184:187], v[158:161], v[192:195], v[80:83]
	v_mfma_f32_16x16x32_bf16 v[188:191], v[216:219], v[208:211], v[68:71]
	v_mfma_f32_16x16x32_bf16 v[192:195], v[158:161], v[208:211], v[64:67]
	s_setprio 0
	s_barrier
	s_nop 0
	ds_read_b128 v[64:67], v152 offset:16384
	ds_read_b128 v[68:71], v152 offset:17408
	ds_read_b128 v[80:83], v151 offset:16384
	ds_read_b128 v[84:87], v151 offset:17408
	ds_read_b128 v[196:199], v150 offset:16384
	ds_read_b128 v[200:203], v150 offset:17408
	ds_read_b128 v[204:207], v149 offset:16384
	ds_read_b128 v[208:211], v149 offset:17408
	s_waitcnt vmcnt(4)
	s_barrier
	s_waitcnt lgkmcnt(0)
	s_setprio 1
	s_waitcnt lgkmcnt(0)
	v_mfma_f32_16x16x32_bf16 v[60:63], v[134:137], v[64:67], v[60:63]
	v_mfma_f32_16x16x32_bf16 v[56:59], v[172:175], v[64:67], v[56:59]
	v_mfma_f32_16x16x32_bf16 v[52:55], v[134:137], v[80:83], v[52:55]
	v_mfma_f32_16x16x32_bf16 v[48:51], v[172:175], v[80:83], v[48:51]
	v_mfma_f32_16x16x32_bf16 v[44:47], v[134:137], v[196:199], v[44:47]
	v_mfma_f32_16x16x32_bf16 v[40:43], v[172:175], v[196:199], v[40:43]
	v_mfma_f32_16x16x32_bf16 v[36:39], v[134:137], v[204:207], v[36:39]
	v_mfma_f32_16x16x32_bf16 v[32:35], v[172:175], v[204:207], v[32:35]
	v_mfma_f32_16x16x32_bf16 v[60:63], v[138:141], v[68:71], v[60:63]
	v_mfma_f32_16x16x32_bf16 v[56:59], v[176:179], v[68:71], v[56:59]
	v_mfma_f32_16x16x32_bf16 v[52:55], v[138:141], v[84:87], v[52:55]
	v_mfma_f32_16x16x32_bf16 v[48:51], v[176:179], v[84:87], v[48:51]
	v_mfma_f32_16x16x32_bf16 v[44:47], v[138:141], v[200:203], v[44:47]
	v_mfma_f32_16x16x32_bf16 v[40:43], v[176:179], v[200:203], v[40:43]
	v_mfma_f32_16x16x32_bf16 v[36:39], v[138:141], v[208:211], v[36:39]
	v_mfma_f32_16x16x32_bf16 v[32:35], v[176:179], v[208:211], v[32:35]
	s_setprio 0
	s_setprio 1
	v_mfma_f32_16x16x32_bf16 v[28:31], v[212:215], v[64:67], v[28:31]
	v_mfma_f32_16x16x32_bf16 v[24:27], v[220:223], v[64:67], v[24:27]
	v_mfma_f32_16x16x32_bf16 v[12:15], v[212:215], v[196:199], v[12:15]
	v_mfma_f32_16x16x32_bf16 v[8:11], v[220:223], v[196:199], v[8:11]
	v_mfma_f32_16x16x32_bf16 v[20:23], v[212:215], v[80:83], v[20:23]
	v_mfma_f32_16x16x32_bf16 v[16:19], v[220:223], v[80:83], v[16:19]
	v_mfma_f32_16x16x32_bf16 v[4:7], v[212:215], v[204:207], v[4:7]
	v_mfma_f32_16x16x32_bf16 v[0:3], v[220:223], v[204:207], v[0:3]
	v_mfma_f32_16x16x32_bf16 v[28:31], v[216:219], v[68:71], v[28:31]
	v_mfma_f32_16x16x32_bf16 v[24:27], v[158:161], v[68:71], v[24:27]
	v_mfma_f32_16x16x32_bf16 v[12:15], v[216:219], v[200:203], v[12:15]
	v_mfma_f32_16x16x32_bf16 v[8:11], v[158:161], v[200:203], v[8:11]
	v_mfma_f32_16x16x32_bf16 v[134:137], v[216:219], v[84:87], v[20:23]
	v_mfma_f32_16x16x32_bf16 v[138:141], v[158:161], v[84:87], v[16:19]
	v_mfma_f32_16x16x32_bf16 v[170:173], v[216:219], v[208:211], v[4:7]
	v_mfma_f32_16x16x32_bf16 v[158:161], v[158:161], v[208:211], v[0:3]
	s_setprio 0
	s_barrier
	s_nop 0
	ds_read_b128 v[0:3], v156
	ds_read_b128 v[4:7], v156 offset:1024
	ds_read_b128 v[16:19], v156 offset:2048
	ds_read_b128 v[174:177], v156 offset:3072
	ds_read_b128 v[20:23], v152 offset:32768
	ds_read_b128 v[196:199], v152 offset:33792
	ds_read_b128 v[200:203], v151 offset:32768
	ds_read_b128 v[204:207], v151 offset:33792
	ds_read_b128 v[208:211], v150 offset:32768
	ds_read_b128 v[212:215], v150 offset:33792
	ds_read_b128 v[216:219], v149 offset:32768
	ds_read_b128 v[220:223], v149 offset:33792
	s_waitcnt vmcnt(2)
	s_barrier
; #define LDA(dst, b, h) for (int m = 0; m < 4; ++m) for (int k = 0; k < 2; ++k) \
;     dst[m][k] = *reinterpret_cast<const bf16x8*>((char*)SA(b, h) + lds_byte(wr * 64 + m * 16 + fr, k * 32 + fq * 8))
; #define LDB(dst, b, h) for (int n = 0; n < 2; ++n) for (int k = 0; k < 2; ++k) \
;     dst[n][k] = *reinterpret_cast<const bf16x8*>((char*)SB(b, h) + lds_byte(wc * 32 + n * 16 + fr, k * 32 + fq * 8))
; #define MMA(ai, bj, At_, Bt_) do { __builtin_amdgcn_s_setprio(1); \
;     for (int k = 0; k < 2; ++k) for (int m = 0; m < 4; ++m) for (int n = 0; n < 2; ++n) \
;       acc[ai][bj][m][n] = __builtin_amdgcn_mfma_f32_16x16x32_bf16(At_[m][k], Bt_[n][k], acc[ai][bj][m][n], 0, 0, 0); \
;     __builtin_amdgcn_s_setprio(0); } while (0)
; #define WAIT_V(n) asm volatile("s_waitcnt vmcnt(" #n ")" ::: "memory")
; #define WAIT_L(n) asm volatile("s_waitcnt lgkmcnt(" #n ")" ::: "memory")
; #define BAR __builtin_amdgcn_s_barrier()
; template <int EPI, int lda, int ldb, int N, int K>
; __device__ __forceinline__ void gemm_phase(const u16* __restrict__ A, const u16* __restrict__ Bt, const GemmEpi ep, int wv) {
;     ...
;       LDA(At, 0, 1); WAIT_V(4); BAR; WAIT_L(0); MMA(1, 0, At, B0); MMA(1, 1, At, B1); BAR; }
;     { LDB(B0, 1, 0); LDA(At, 1, 0); WAIT_V(2); BAR; WAIT_L(0); MMA(0, 0, At, B0); BAR;
;       LDB(B1, 1, 1); WAIT_V(0); BAR; WAIT_L(0); MMA(0, 1, At, B1); BAR;
;       LDA(At, 1, 1); BAR; WAIT_L(0); MMA(1, 0, At, B0); MMA(1, 1, At, B1); BAR; }
;     if (wr == 0) BAR;
	s_waitcnt lgkmcnt(0)
	s_setprio 1
	s_waitcnt lgkmcnt(0)
	v_mfma_f32_16x16x32_bf16 v[64:67], v[0:3], v[20:23], v[124:127]
	v_mfma_f32_16x16x32_bf16 v[68:71], v[16:19], v[20:23], v[120:123]
	v_mfma_f32_16x16x32_bf16 v[80:83], v[0:3], v[200:203], v[116:119]
	v_mfma_f32_16x16x32_bf16 v[84:87], v[16:19], v[200:203], v[112:115]
	v_mfma_f32_16x16x32_bf16 v[108:111], v[0:3], v[208:211], v[108:111]
	v_mfma_f32_16x16x32_bf16 v[104:107], v[16:19], v[208:211], v[104:107]
	v_mfma_f32_16x16x32_bf16 v[120:123], v[0:3], v[216:219], v[100:103]
	v_mfma_f32_16x16x32_bf16 v[124:127], v[16:19], v[216:219], v[96:99]
	v_mfma_f32_16x16x32_bf16 v[116:119], v[4:7], v[196:199], v[64:67]
	v_mfma_f32_16x16x32_bf16 v[112:115], v[174:177], v[196:199], v[68:71]
	v_mfma_f32_16x16x32_bf16 v[100:103], v[4:7], v[204:207], v[80:83]
	v_mfma_f32_16x16x32_bf16 v[96:99], v[174:177], v[204:207], v[84:87]
	v_mfma_f32_16x16x32_bf16 v[84:87], v[4:7], v[212:215], v[108:111]
	v_mfma_f32_16x16x32_bf16 v[80:83], v[174:177], v[212:215], v[104:107]
	v_mfma_f32_16x16x32_bf16 v[68:71], v[4:7], v[220:223], v[120:123]
	v_mfma_f32_16x16x32_bf16 v[64:67], v[174:177], v[220:223], v[124:127]
	s_setprio 0
	s_barrier
	ds_read_b128 v[224:227], v154
	ds_read_b128 v[228:231], v154 offset:1024
	ds_read_b128 v[232:235], v154 offset:2048
	ds_read_b128 v[154:157], v154 offset:3072
	s_waitcnt vmcnt(0)
	s_barrier
	s_waitcnt lgkmcnt(0)
	s_setprio 1
	s_waitcnt lgkmcnt(0)
	v_mfma_f32_16x16x32_bf16 v[92:95], v[224:227], v[20:23], v[92:95]
	v_mfma_f32_16x16x32_bf16 v[20:23], v[232:235], v[20:23], v[88:91]
	v_mfma_f32_16x16x32_bf16 v[88:91], v[224:227], v[200:203], v[180:183]
	v_mfma_f32_16x16x32_bf16 v[104:107], v[232:235], v[200:203], v[184:187]
	v_mfma_f32_16x16x32_bf16 v[76:79], v[224:227], v[208:211], v[76:79]
	v_mfma_f32_16x16x32_bf16 v[72:75], v[232:235], v[208:211], v[72:75]
	v_mfma_f32_16x16x32_bf16 v[178:181], v[224:227], v[216:219], v[188:191]
	v_mfma_f32_16x16x32_bf16 v[182:185], v[232:235], v[216:219], v[192:195]
	v_mfma_f32_16x16x32_bf16 v[124:127], v[228:231], v[196:199], v[92:95]
	v_mfma_f32_16x16x32_bf16 v[120:123], v[154:157], v[196:199], v[20:23]
	v_mfma_f32_16x16x32_bf16 v[108:111], v[228:231], v[204:207], v[88:91]
	v_mfma_f32_16x16x32_bf16 v[104:107], v[154:157], v[204:207], v[104:107]
	v_mfma_f32_16x16x32_bf16 v[92:95], v[228:231], v[212:215], v[76:79]
	v_mfma_f32_16x16x32_bf16 v[88:91], v[154:157], v[212:215], v[72:75]
	v_mfma_f32_16x16x32_bf16 v[76:79], v[228:231], v[220:223], v[178:181]
	v_mfma_f32_16x16x32_bf16 v[72:75], v[154:157], v[220:223], v[182:185]
	s_setprio 0
	s_barrier
	ds_read_b128 v[178:181], v152 offset:49152
	ds_read_b128 v[182:185], v152 offset:50176
	ds_read_b128 v[186:189], v151 offset:49152
	ds_read_b128 v[190:193], v151 offset:50176
	ds_read_b128 v[194:197], v150 offset:49152
	ds_read_b128 v[150:153], v150 offset:50176
	ds_read_b128 v[198:201], v149 offset:49152
	ds_read_b128 v[202:205], v149 offset:50176
	s_barrier
	s_waitcnt lgkmcnt(0)
	s_setprio 1
	s_waitcnt lgkmcnt(0)
	v_mfma_f32_16x16x32_bf16 v[20:23], v[0:3], v[178:181], v[60:63]
	v_mfma_f32_16x16x32_bf16 v[56:59], v[16:19], v[178:181], v[56:59]
	v_mfma_f32_16x16x32_bf16 v[60:63], v[0:3], v[186:189], v[52:55]
	v_mfma_f32_16x16x32_bf16 v[206:209], v[16:19], v[186:189], v[48:51]
	v_mfma_f32_16x16x32_bf16 v[44:47], v[0:3], v[194:197], v[44:47]
	v_mfma_f32_16x16x32_bf16 v[40:43], v[16:19], v[194:197], v[40:43]
	v_mfma_f32_16x16x32_bf16 v[0:3], v[0:3], v[198:201], v[36:39]
	v_mfma_f32_16x16x32_bf16 v[210:213], v[16:19], v[198:201], v[32:35]
	v_mfma_f32_16x16x32_bf16 v[52:55], v[4:7], v[182:185], v[20:23]
	v_mfma_f32_16x16x32_bf16 v[48:51], v[174:177], v[182:185], v[56:59]
	v_mfma_f32_16x16x32_bf16 v[36:39], v[4:7], v[190:193], v[60:63]
	v_mfma_f32_16x16x32_bf16 v[32:35], v[174:177], v[190:193], v[206:209]
	v_mfma_f32_16x16x32_bf16 v[20:23], v[4:7], v[150:153], v[44:47]
	v_mfma_f32_16x16x32_bf16 v[16:19], v[174:177], v[150:153], v[40:43]
	v_mfma_f32_16x16x32_bf16 v[4:7], v[4:7], v[202:205], v[0:3]
	v_mfma_f32_16x16x32_bf16 v[0:3], v[174:177], v[202:205], v[210:213]
	s_setprio 0
	s_setprio 1
	v_mfma_f32_16x16x32_bf16 v[28:31], v[224:227], v[178:181], v[28:31]
	v_mfma_f32_16x16x32_bf16 v[24:27], v[232:235], v[178:181], v[24:27]
	v_mfma_f32_16x16x32_bf16 v[40:43], v[224:227], v[186:189], v[134:137]
	v_mfma_f32_16x16x32_bf16 v[134:137], v[232:235], v[186:189], v[138:141]
	v_mfma_f32_16x16x32_bf16 v[12:15], v[224:227], v[194:197], v[12:15]
	v_mfma_f32_16x16x32_bf16 v[8:11], v[232:235], v[194:197], v[8:11]
	v_mfma_f32_16x16x32_bf16 v[138:141], v[224:227], v[198:201], v[170:173]
	v_mfma_f32_16x16x32_bf16 v[158:161], v[232:235], v[198:201], v[158:161]
	v_mfma_f32_16x16x32_bf16 v[60:63], v[228:231], v[182:185], v[28:31]
	v_mfma_f32_16x16x32_bf16 v[56:59], v[154:157], v[182:185], v[24:27]
	v_mfma_f32_16x16x32_bf16 v[44:47], v[228:231], v[190:193], v[40:43]
	v_mfma_f32_16x16x32_bf16 v[40:43], v[154:157], v[190:193], v[134:137]
	v_mfma_f32_16x16x32_bf16 v[28:31], v[228:231], v[150:153], v[12:15]
	v_mfma_f32_16x16x32_bf16 v[24:27], v[154:157], v[150:153], v[8:11]
	v_mfma_f32_16x16x32_bf16 v[12:15], v[228:231], v[202:205], v[138:141]
	v_mfma_f32_16x16x32_bf16 v[8:11], v[154:157], v[202:205], v[158:161]
	s_setprio 0
	v_cmp_gt_u32_e32 vcc, s66, v130
	s_barrier
	s_and_saveexec_b64 s[50:51], vcc
	s_cbranch_execz .LBB0_773
	s_barrier

; __device__ __forceinline__ u16 f2bf(float x) { return (u16)(cvtpk(x, x) & 0xffffu); }
; #define UNR _Pragma("unroll")
; template <int EPI, int lda, int ldb, int N, int K>
; __device__ __forceinline__ void gemm_phase(const u16* __restrict__ A, const u16* __restrict__ Bt, const GemmEpi ep, int wv) {
;     ...
;     if constexpr (EPI == EPI_SWIGLU) {
;       u16* out = reinterpret_cast<u16*>(ep.out0);
;       UNR for (int ai = 0; ai < 2; ++ai) UNR for (int m = 0; m < 4; ++m) {
;         const int rl0 = ai * HALF + wr * 64 + m * 16 + fq * 4;
;         const f32x4 r4 = *reinterpret_cast<const f32x4*>(lrs + rl0);
;         UNR for (int j = 0; j < 4; ++j) {
;           const int row = brow + rl0 + j;
;           const float rs = r4[j], ce = -1.4426950408889634f * rs, r2 = rs * rs;
;           UNR for (int n = 0; n < 2; ++n) {
;             const int col = (bcol >> 1) + wc * 32 + n * 16 + fr;
;             const float g = acc[ai][0][m][n][j], u = acc[ai][1][m][n][j];
;             const float sg = __builtin_amdgcn_rcpf(1.f + __builtin_amdgcn_exp2f(ce * g));
;             out[(size_t)row * ep.ldc + col] = f2bf((g * u) * (r2 * sg));
;           }
;         }
;       }
.LBB0_777:
	s_or_b64 exec, exec, s[56:57]
	v_and_b32_e32 v135, 15, v130
	v_lshrrev_b32_e32 v149, 8, v130
	v_lshl_add_u32 v135, v149, 6, v135
	v_lshlrev_b32_e32 v133, 2, v135
	v_add_u32_e32 v133, 0x20000, v133
	ds_read_b32 v150, v133 offset:0
	ds_read_b32 v151, v133 offset:64
	ds_read_b32 v152, v133 offset:128
	ds_read_b32 v153, v133 offset:192
	v_add_u32_e32 v135, s48, v135
	v_mul_u32_u24_e32 v132, 0x2b00, v135
	v_bfe_u32 v149, v130, 6, 2
	v_lshlrev_b32_e32 v149, 5, v149
	v_bfe_u32 v135, v130, 4, 1
	v_lshl_add_u32 v149, v135, 4, v149
	v_bfe_u32 v135, v130, 5, 1
	v_lshl_add_u32 v149, v135, 3, v149
	v_lshrrev_b32_e64 v135, 1, s49
	v_add_u32_e32 v149, v135, v149
	v_lshl_add_u32 v132, v149, 1, v132
	s_waitcnt lgkmcnt(0)
	v_mul_f32_e32 v135, 0xbfb8aa3b, v150
	v_mul_f32_e32 v149, v150, v150
	ds_read_b32 v150, v133 offset:512
	v_mul_f32_e32 v124, v116, v124
	v_mul_f32_e32 v125, v117, v125
	v_mul_f32_e32 v116, v135, v116
	v_mul_f32_e32 v117, v135, v117
	v_exp_f32_e32 v116, v116
	v_exp_f32_e32 v117, v117
	v_add_f32_e32 v116, 1.0, v116
	v_add_f32_e32 v117, 1.0, v117
	v_rcp_f32_e32 v116, v116
	v_rcp_f32_e32 v117, v117
	v_mul_f32_e32 v116, v149, v116
	v_mul_f32_e32 v117, v149, v117
	v_mul_f32_e32 v124, v124, v116
	v_mul_f32_e32 v125, v125, v117
	v_cvt_pk_bf16_f32 v116, v124, v125
	v_mul_f32_e32 v126, v118, v126
	v_mul_f32_e32 v127, v119, v127
	v_mul_f32_e32 v118, v135, v118
	v_mul_f32_e32 v119, v135, v119
	v_exp_f32_e32 v118, v118
	v_exp_f32_e32 v119, v119
	v_add_f32_e32 v118, 1.0, v118
	v_add_f32_e32 v119, 1.0, v119
	v_rcp_f32_e32 v118, v118
	v_rcp_f32_e32 v119, v119
	v_mul_f32_e32 v118, v149, v118
	v_mul_f32_e32 v119, v149, v119
	v_mul_f32_e32 v126, v126, v118
	v_mul_f32_e32 v127, v127, v119
	v_cvt_pk_bf16_f32 v117, v126, v127
	v_mul_f32_e32 v120, v112, v120
	v_mul_f32_e32 v121, v113, v121
	v_mul_f32_e32 v112, v135, v112
	v_mul_f32_e32 v113, v135, v113
	v_exp_f32_e32 v112, v112
	v_exp_f32_e32 v113, v113
	v_add_f32_e32 v112, 1.0, v112
	v_add_f32_e32 v113, 1.0, v113
	v_rcp_f32_e32 v112, v112
	v_rcp_f32_e32 v113, v113
	v_mul_f32_e32 v112, v149, v112
	v_mul_f32_e32 v113, v149, v113
	v_mul_f32_e32 v120, v120, v112
	v_mul_f32_e32 v121, v121, v113
	v_cvt_pk_bf16_f32 v118, v120, v121
	v_mul_f32_e32 v122, v114, v122
	v_mul_f32_e32 v123, v115, v123
	v_mul_f32_e32 v114, v135, v114
	v_mul_f32_e32 v115, v135, v115
	v_exp_f32_e32 v114, v114
	v_exp_f32_e32 v115, v115
	v_add_f32_e32 v114, 1.0, v114
	v_add_f32_e32 v115, 1.0, v115
	v_rcp_f32_e32 v114, v114
	v_rcp_f32_e32 v115, v115
	v_mul_f32_e32 v114, v149, v114
	v_mul_f32_e32 v115, v149, v115
	v_mul_f32_e32 v122, v122, v114
	v_mul_f32_e32 v123, v123, v115
	v_cvt_pk_bf16_f32 v119, v122, v123
	s_nop 1
	v_permlane16_swap_b32_e32 v116, v118
	v_permlane16_swap_b32_e32 v117, v119
	global_store_dwordx4 v132, v[116:119], s[14:15]
	v_add_u32_e32 v134, 0x2b000, v132
	v_mul_f32_e32 v135, 0xbfb8aa3b, v151
	v_mul_f32_e32 v149, v151, v151
	ds_read_b32 v151, v133 offset:576
	v_mul_f32_e32 v108, v100, v108
	v_mul_f32_e32 v109, v101, v109
	v_mul_f32_e32 v100, v135, v100
	v_mul_f32_e32 v101, v135, v101
	v_exp_f32_e32 v100, v100
	v_exp_f32_e32 v101, v101
	v_add_f32_e32 v100, 1.0, v100
	v_add_f32_e32 v101, 1.0, v101
	v_rcp_f32_e32 v100, v100
	v_rcp_f32_e32 v101, v101
	v_mul_f32_e32 v100, v149, v100
	v_mul_f32_e32 v101, v149, v101
	v_mul_f32_e32 v108, v108, v100
	v_mul_f32_e32 v109, v109, v101
	v_cvt_pk_bf16_f32 v100, v108, v109
	v_mul_f32_e32 v110, v102, v110
	v_mul_f32_e32 v111, v103, v111
	v_mul_f32_e32 v102, v135, v102
	v_mul_f32_e32 v103, v135, v103
	v_exp_f32_e32 v102, v102
	v_exp_f32_e32 v103, v103
	v_add_f32_e32 v102, 1.0, v102
	v_add_f32_e32 v103, 1.0, v103
	v_rcp_f32_e32 v102, v102
	v_rcp_f32_e32 v103, v103
	v_mul_f32_e32 v102, v149, v102
	v_mul_f32_e32 v103, v149, v103
	v_mul_f32_e32 v110, v110, v102
	v_mul_f32_e32 v111, v111, v103
	v_cvt_pk_bf16_f32 v101, v110, v111
	v_mul_f32_e32 v104, v96, v104
	v_mul_f32_e32 v105, v97, v105
	v_mul_f32_e32 v96, v135, v96
	v_mul_f32_e32 v97, v135, v97
	v_exp_f32_e32 v96, v96
	v_exp_f32_e32 v97, v97
	v_add_f32_e32 v96, 1.0, v96
	v_add_f32_e32 v97, 1.0, v97
	v_rcp_f32_e32 v96, v96
	v_rcp_f32_e32 v97, v97
	v_mul_f32_e32 v96, v149, v96
	v_mul_f32_e32 v97, v149, v97
	v_mul_f32_e32 v104, v104, v96
	v_mul_f32_e32 v105, v105, v97
	v_cvt_pk_bf16_f32 v102, v104, v105
	v_mul_f32_e32 v106, v98, v106
	v_mul_f32_e32 v107, v99, v107
	v_mul_f32_e32 v98, v135, v98
	v_mul_f32_e32 v99, v135, v99
	v_exp_f32_e32 v98, v98
	v_exp_f32_e32 v99, v99
	v_add_f32_e32 v98, 1.0, v98
	v_add_f32_e32 v99, 1.0, v99
	v_rcp_f32_e32 v98, v98
	v_rcp_f32_e32 v99, v99
	v_mul_f32_e32 v98, v149, v98
	v_mul_f32_e32 v99, v149, v99
	v_mul_f32_e32 v106, v106, v98
	v_mul_f32_e32 v107, v107, v99
	v_cvt_pk_bf16_f32 v103, v106, v107
	s_nop 1
	v_permlane16_swap_b32_e32 v100, v102
	v_permlane16_swap_b32_e32 v101, v103
	global_store_dwordx4 v134, v[100:103], s[14:15]
	v_add_u32_e32 v134, 0x56000, v132
	v_mul_f32_e32 v135, 0xbfb8aa3b, v152
	v_mul_f32_e32 v149, v152, v152
	ds_read_b32 v152, v133 offset:640
	v_mul_f32_e32 v92, v84, v92
	v_mul_f32_e32 v93, v85, v93
	v_mul_f32_e32 v84, v135, v84
	v_mul_f32_e32 v85, v135, v85
	v_exp_f32_e32 v84, v84
	v_exp_f32_e32 v85, v85
	v_add_f32_e32 v84, 1.0, v84
	v_add_f32_e32 v85, 1.0, v85
	v_rcp_f32_e32 v84, v84
	v_rcp_f32_e32 v85, v85
	v_mul_f32_e32 v84, v149, v84
	v_mul_f32_e32 v85, v149, v85
	v_mul_f32_e32 v92, v92, v84
	v_mul_f32_e32 v93, v93, v85
	v_cvt_pk_bf16_f32 v84, v92, v93
	v_mul_f32_e32 v94, v86, v94
	v_mul_f32_e32 v95, v87, v95
	v_mul_f32_e32 v86, v135, v86
	v_mul_f32_e32 v87, v135, v87
	v_exp_f32_e32 v86, v86
	v_exp_f32_e32 v87, v87
	v_add_f32_e32 v86, 1.0, v86
	v_add_f32_e32 v87, 1.0, v87
; __device__ __forceinline__ u16 f2bf(float x) { return (u16)(cvtpk(x, x) & 0xffffu); }
; #define UNR _Pragma("unroll")
; template <int EPI, int lda, int ldb, int N, int K>
; __device__ __forceinline__ void gemm_phase(const u16* __restrict__ A, const u16* __restrict__ Bt, const GemmEpi ep, int wv) {
;     ...
;     if constexpr (EPI == EPI_SWIGLU) {
;       u16* out = reinterpret_cast<u16*>(ep.out0);
;       UNR for (int ai = 0; ai < 2; ++ai) UNR for (int m = 0; m < 4; ++m) {
;         const int rl0 = ai * HALF + wr * 64 + m * 16 + fq * 4;
;         const f32x4 r4 = *reinterpret_cast<const f32x4*>(lrs + rl0);
;         UNR for (int j = 0; j < 4; ++j) {
;           const int row = brow + rl0 + j;
;           const float rs = r4[j], ce = -1.4426950408889634f * rs, r2 = rs * rs;
;           UNR for (int n = 0; n < 2; ++n) {
;             const int col = (bcol >> 1) + wc * 32 + n * 16 + fr;
;             const float g = acc[ai][0][m][n][j], u = acc[ai][1][m][n][j];
;             const float sg = __builtin_amdgcn_rcpf(1.f + __builtin_amdgcn_exp2f(ce * g));
;             out[(size_t)row * ep.ldc + col] = f2bf((g * u) * (r2 * sg));
;           }
;         }
;       }
	v_rcp_f32_e32 v86, v86
	v_rcp_f32_e32 v87, v87
	v_mul_f32_e32 v86, v149, v86
	v_mul_f32_e32 v87, v149, v87
	v_mul_f32_e32 v94, v94, v86
	v_mul_f32_e32 v95, v95, v87
	v_cvt_pk_bf16_f32 v85, v94, v95
	v_mul_f32_e32 v88, v80, v88
	v_mul_f32_e32 v89, v81, v89
	v_mul_f32_e32 v80, v135, v80
	v_mul_f32_e32 v81, v135, v81
	v_exp_f32_e32 v80, v80
	v_exp_f32_e32 v81, v81
	v_add_f32_e32 v80, 1.0, v80
	v_add_f32_e32 v81, 1.0, v81
	v_rcp_f32_e32 v80, v80
	v_rcp_f32_e32 v81, v81
	v_mul_f32_e32 v80, v149, v80
	v_mul_f32_e32 v81, v149, v81
	v_mul_f32_e32 v88, v88, v80
	v_mul_f32_e32 v89, v89, v81
	v_cvt_pk_bf16_f32 v86, v88, v89
	v_mul_f32_e32 v90, v82, v90
	v_mul_f32_e32 v91, v83, v91
	v_mul_f32_e32 v82, v135, v82
	v_mul_f32_e32 v83, v135, v83
	v_exp_f32_e32 v82, v82
	v_exp_f32_e32 v83, v83
	v_add_f32_e32 v82, 1.0, v82
	v_add_f32_e32 v83, 1.0, v83
	v_rcp_f32_e32 v82, v82
	v_rcp_f32_e32 v83, v83
	v_mul_f32_e32 v82, v149, v82
	v_mul_f32_e32 v83, v149, v83
	v_mul_f32_e32 v90, v90, v82
	v_mul_f32_e32 v91, v91, v83
	v_cvt_pk_bf16_f32 v87, v90, v91
	s_nop 1
	v_permlane16_swap_b32_e32 v84, v86
	v_permlane16_swap_b32_e32 v85, v87
	global_store_dwordx4 v134, v[84:87], s[14:15]
	v_add_u32_e32 v134, 0x81000, v132
	v_mul_f32_e32 v135, 0xbfb8aa3b, v153
	v_mul_f32_e32 v149, v153, v153
	ds_read_b32 v153, v133 offset:704
	v_mul_f32_e32 v76, v68, v76
	v_mul_f32_e32 v77, v69, v77
	v_mul_f32_e32 v68, v135, v68
	v_mul_f32_e32 v69, v135, v69
	v_exp_f32_e32 v68, v68
	v_exp_f32_e32 v69, v69
	v_add_f32_e32 v68, 1.0, v68
	v_add_f32_e32 v69, 1.0, v69
	v_rcp_f32_e32 v68, v68
	v_rcp_f32_e32 v69, v69
	v_mul_f32_e32 v68, v149, v68
	v_mul_f32_e32 v69, v149, v69
	v_mul_f32_e32 v76, v76, v68
	v_mul_f32_e32 v77, v77, v69
	v_cvt_pk_bf16_f32 v68, v76, v77
	v_mul_f32_e32 v78, v70, v78
	v_mul_f32_e32 v79, v71, v79
	v_mul_f32_e32 v70, v135, v70
	v_mul_f32_e32 v71, v135, v71
	v_exp_f32_e32 v70, v70
	v_exp_f32_e32 v71, v71
	v_add_f32_e32 v70, 1.0, v70
	v_add_f32_e32 v71, 1.0, v71
	v_rcp_f32_e32 v70, v70
	v_rcp_f32_e32 v71, v71
	v_mul_f32_e32 v70, v149, v70
	v_mul_f32_e32 v71, v149, v71
	v_mul_f32_e32 v78, v78, v70
	v_mul_f32_e32 v79, v79, v71
	v_cvt_pk_bf16_f32 v69, v78, v79
	v_mul_f32_e32 v72, v64, v72
	v_mul_f32_e32 v73, v65, v73
	v_mul_f32_e32 v64, v135, v64
	v_mul_f32_e32 v65, v135, v65
	v_exp_f32_e32 v64, v64
	v_exp_f32_e32 v65, v65
	v_add_f32_e32 v64, 1.0, v64
	v_add_f32_e32 v65, 1.0, v65
	v_rcp_f32_e32 v64, v64
	v_rcp_f32_e32 v65, v65
	v_mul_f32_e32 v64, v149, v64
	v_mul_f32_e32 v65, v149, v65
	v_mul_f32_e32 v72, v72, v64
	v_mul_f32_e32 v73, v73, v65
	v_cvt_pk_bf16_f32 v70, v72, v73
	v_mul_f32_e32 v74, v66, v74
	v_mul_f32_e32 v75, v67, v75
	v_mul_f32_e32 v66, v135, v66
	v_mul_f32_e32 v67, v135, v67
	v_exp_f32_e32 v66, v66
	v_exp_f32_e32 v67, v67
	v_add_f32_e32 v66, 1.0, v66
	v_add_f32_e32 v67, 1.0, v67
	v_rcp_f32_e32 v66, v66
	v_rcp_f32_e32 v67, v67
	v_mul_f32_e32 v66, v149, v66
	v_mul_f32_e32 v67, v149, v67
	v_mul_f32_e32 v74, v74, v66
	v_mul_f32_e32 v75, v75, v67
	v_cvt_pk_bf16_f32 v71, v74, v75
	s_nop 1
	v_permlane16_swap_b32_e32 v68, v70
	v_permlane16_swap_b32_e32 v69, v71
	global_store_dwordx4 v134, v[68:71], s[14:15]
	s_waitcnt lgkmcnt(0)
	v_add_u32_e32 v134, 0x158000, v132
	v_mul_f32_e32 v135, 0xbfb8aa3b, v150
	v_mul_f32_e32 v149, v150, v150
	v_mul_f32_e32 v60, v52, v60
	v_mul_f32_e32 v61, v53, v61
	v_mul_f32_e32 v52, v135, v52
	v_mul_f32_e32 v53, v135, v53
	v_exp_f32_e32 v52, v52
	v_exp_f32_e32 v53, v53
	v_add_f32_e32 v52, 1.0, v52
	v_add_f32_e32 v53, 1.0, v53
	v_rcp_f32_e32 v52, v52
	v_rcp_f32_e32 v53, v53
	v_mul_f32_e32 v52, v149, v52
	v_mul_f32_e32 v53, v149, v53
	v_mul_f32_e32 v60, v60, v52
	v_mul_f32_e32 v61, v61, v53
	v_cvt_pk_bf16_f32 v52, v60, v61
	v_mul_f32_e32 v62, v54, v62
	v_mul_f32_e32 v63, v55, v63
	v_mul_f32_e32 v54, v135, v54
	v_mul_f32_e32 v55, v135, v55
	v_exp_f32_e32 v54, v54
	v_exp_f32_e32 v55, v55
	v_add_f32_e32 v54, 1.0, v54
	v_add_f32_e32 v55, 1.0, v55
	v_rcp_f32_e32 v54, v54
	v_rcp_f32_e32 v55, v55
	v_mul_f32_e32 v54, v149, v54
	v_mul_f32_e32 v55, v149, v55
	v_mul_f32_e32 v62, v62, v54
	v_mul_f32_e32 v63, v63, v55
	v_cvt_pk_bf16_f32 v53, v62, v63
	v_mul_f32_e32 v56, v48, v56
	v_mul_f32_e32 v57, v49, v57
	v_mul_f32_e32 v48, v135, v48
	v_mul_f32_e32 v49, v135, v49
	v_exp_f32_e32 v48, v48
	v_exp_f32_e32 v49, v49
	v_add_f32_e32 v48, 1.0, v48
	v_add_f32_e32 v49, 1.0, v49
	v_rcp_f32_e32 v48, v48
	v_rcp_f32_e32 v49, v49
	v_mul_f32_e32 v48, v149, v48
	v_mul_f32_e32 v49, v149, v49
	v_mul_f32_e32 v56, v56, v48
	v_mul_f32_e32 v57, v57, v49
	v_cvt_pk_bf16_f32 v54, v56, v57
	v_mul_f32_e32 v58, v50, v58
	v_mul_f32_e32 v59, v51, v59
	v_mul_f32_e32 v50, v135, v50
	v_mul_f32_e32 v51, v135, v51
	v_exp_f32_e32 v50, v50
	v_exp_f32_e32 v51, v51
	v_add_f32_e32 v50, 1.0, v50
	v_add_f32_e32 v51, 1.0, v51
	v_rcp_f32_e32 v50, v50
	v_rcp_f32_e32 v51, v51
	v_mul_f32_e32 v50, v149, v50
	v_mul_f32_e32 v51, v149, v51
	v_mul_f32_e32 v58, v58, v50
	v_mul_f32_e32 v59, v59, v51
	v_cvt_pk_bf16_f32 v55, v58, v59
	s_nop 1
	v_permlane16_swap_b32_e32 v52, v54
	v_permlane16_swap_b32_e32 v53, v55
	global_store_dwordx4 v134, v[52:55], s[14:15]
	v_add_u32_e32 v134, 0x183000, v132
	v_mul_f32_e32 v135, 0xbfb8aa3b, v151
	v_mul_f32_e32 v149, v151, v151
	v_mul_f32_e32 v44, v36, v44
	v_mul_f32_e32 v45, v37, v45
	v_mul_f32_e32 v36, v135, v36
	v_mul_f32_e32 v37, v135, v37
	v_exp_f32_e32 v36, v36
	v_exp_f32_e32 v37, v37
	v_add_f32_e32 v36, 1.0, v36
	v_add_f32_e32 v37, 1.0, v37
	v_rcp_f32_e32 v36, v36
	v_rcp_f32_e32 v37, v37
	v_mul_f32_e32 v36, v149, v36
	v_mul_f32_e32 v37, v149, v37
	v_mul_f32_e32 v44, v44, v36
	v_mul_f32_e32 v45, v45, v37
	v_cvt_pk_bf16_f32 v36, v44, v45
	v_mul_f32_e32 v46, v38, v46
; __device__ __forceinline__ u16 f2bf(float x) { return (u16)(cvtpk(x, x) & 0xffffu); }
; #define UNR _Pragma("unroll")
; #define WAIT_V(n) asm volatile("s_waitcnt vmcnt(" #n ")" ::: "memory")
; template <int EPI, int lda, int ldb, int N, int K>
; __device__ __forceinline__ void gemm_phase(const u16* __restrict__ A, const u16* __restrict__ Bt, const GemmEpi ep, int wv) {
;     ...
;     if constexpr (EPI == EPI_SWIGLU) {
;       u16* out = reinterpret_cast<u16*>(ep.out0);
;       UNR for (int ai = 0; ai < 2; ++ai) UNR for (int m = 0; m < 4; ++m) {
;         const int rl0 = ai * HALF + wr * 64 + m * 16 + fq * 4;
;         const f32x4 r4 = *reinterpret_cast<const f32x4*>(lrs + rl0);
;         UNR for (int j = 0; j < 4; ++j) {
;           const int row = brow + rl0 + j;
;           const float rs = r4[j], ce = -1.4426950408889634f * rs, r2 = rs * rs;
;           UNR for (int n = 0; n < 2; ++n) {
;             const int col = (bcol >> 1) + wc * 32 + n * 16 + fr;
;             const float g = acc[ai][0][m][n][j], u = acc[ai][1][m][n][j];
;             const float sg = __builtin_amdgcn_rcpf(1.f + __builtin_amdgcn_exp2f(ce * g));
;             out[(size_t)row * ep.ldc + col] = f2bf((g * u) * (r2 * sg));
;           }
;         }
;       }
;     ...
;     if constexpr (PF) {
;       WAIT_V(0);
;       __syncthreads();
;       if constexpr (CONS) { if (more && tidx < 256) { float sq = 0.f; UNR for (int pp = 0; pp < 8; ++pp) sq += nss[pp];
;         lrs[tidx] = rsqrtf(sq * (1.f / DM) + 1e-6f); } }
;       if (!more) break;
	v_mul_f32_e32 v47, v39, v47
	v_mul_f32_e32 v38, v135, v38
	v_mul_f32_e32 v39, v135, v39
	v_exp_f32_e32 v38, v38
	v_exp_f32_e32 v39, v39
	v_add_f32_e32 v38, 1.0, v38
	v_add_f32_e32 v39, 1.0, v39
	v_rcp_f32_e32 v38, v38
	v_rcp_f32_e32 v39, v39
	v_mul_f32_e32 v38, v149, v38
	v_mul_f32_e32 v39, v149, v39
	v_mul_f32_e32 v46, v46, v38
	v_mul_f32_e32 v47, v47, v39
	v_cvt_pk_bf16_f32 v37, v46, v47
	v_mul_f32_e32 v40, v32, v40
	v_mul_f32_e32 v41, v33, v41
	v_mul_f32_e32 v32, v135, v32
	v_mul_f32_e32 v33, v135, v33
	v_exp_f32_e32 v32, v32
	v_exp_f32_e32 v33, v33
	v_add_f32_e32 v32, 1.0, v32
	v_add_f32_e32 v33, 1.0, v33
	v_rcp_f32_e32 v32, v32
	v_rcp_f32_e32 v33, v33
	v_mul_f32_e32 v32, v149, v32
	v_mul_f32_e32 v33, v149, v33
	v_mul_f32_e32 v40, v40, v32
	v_mul_f32_e32 v41, v41, v33
	v_cvt_pk_bf16_f32 v38, v40, v41
	v_mul_f32_e32 v42, v34, v42
	v_mul_f32_e32 v43, v35, v43
	v_mul_f32_e32 v34, v135, v34
	v_mul_f32_e32 v35, v135, v35
	v_exp_f32_e32 v34, v34
	v_exp_f32_e32 v35, v35
	v_add_f32_e32 v34, 1.0, v34
	v_add_f32_e32 v35, 1.0, v35
	v_rcp_f32_e32 v34, v34
	v_rcp_f32_e32 v35, v35
	v_mul_f32_e32 v34, v149, v34
	v_mul_f32_e32 v35, v149, v35
	v_mul_f32_e32 v42, v42, v34
	v_mul_f32_e32 v43, v43, v35
	v_cvt_pk_bf16_f32 v39, v42, v43
	s_nop 1
	v_permlane16_swap_b32_e32 v36, v38
	v_permlane16_swap_b32_e32 v37, v39
	global_store_dwordx4 v134, v[36:39], s[14:15]
	v_add_u32_e32 v134, 0x1ae000, v132
	v_mul_f32_e32 v135, 0xbfb8aa3b, v152
	v_mul_f32_e32 v149, v152, v152
	v_mul_f32_e32 v28, v20, v28
	v_mul_f32_e32 v29, v21, v29
	v_mul_f32_e32 v20, v135, v20
	v_mul_f32_e32 v21, v135, v21
	v_exp_f32_e32 v20, v20
	v_exp_f32_e32 v21, v21
	v_add_f32_e32 v20, 1.0, v20
	v_add_f32_e32 v21, 1.0, v21
	v_rcp_f32_e32 v20, v20
	v_rcp_f32_e32 v21, v21
	v_mul_f32_e32 v20, v149, v20
	v_mul_f32_e32 v21, v149, v21
	v_mul_f32_e32 v28, v28, v20
	v_mul_f32_e32 v29, v29, v21
	v_cvt_pk_bf16_f32 v20, v28, v29
	v_mul_f32_e32 v30, v22, v30
	v_mul_f32_e32 v31, v23, v31
	v_mul_f32_e32 v22, v135, v22
	v_mul_f32_e32 v23, v135, v23
	v_exp_f32_e32 v22, v22
	v_exp_f32_e32 v23, v23
	v_add_f32_e32 v22, 1.0, v22
	v_add_f32_e32 v23, 1.0, v23
	v_rcp_f32_e32 v22, v22
	v_rcp_f32_e32 v23, v23
	v_mul_f32_e32 v22, v149, v22
	v_mul_f32_e32 v23, v149, v23
	v_mul_f32_e32 v30, v30, v22
	v_mul_f32_e32 v31, v31, v23
	v_cvt_pk_bf16_f32 v21, v30, v31
	v_mul_f32_e32 v24, v16, v24
	v_mul_f32_e32 v25, v17, v25
	v_mul_f32_e32 v16, v135, v16
	v_mul_f32_e32 v17, v135, v17
	v_exp_f32_e32 v16, v16
	v_exp_f32_e32 v17, v17
	v_add_f32_e32 v16, 1.0, v16
	v_add_f32_e32 v17, 1.0, v17
	v_rcp_f32_e32 v16, v16
	v_rcp_f32_e32 v17, v17
	v_mul_f32_e32 v16, v149, v16
	v_mul_f32_e32 v17, v149, v17
	v_mul_f32_e32 v24, v24, v16
	v_mul_f32_e32 v25, v25, v17
	v_cvt_pk_bf16_f32 v22, v24, v25
	v_mul_f32_e32 v26, v18, v26
	v_mul_f32_e32 v27, v19, v27
	v_mul_f32_e32 v18, v135, v18
	v_mul_f32_e32 v19, v135, v19
	v_exp_f32_e32 v18, v18
	v_exp_f32_e32 v19, v19
	v_add_f32_e32 v18, 1.0, v18
	v_add_f32_e32 v19, 1.0, v19
	v_rcp_f32_e32 v18, v18
	v_rcp_f32_e32 v19, v19
	v_mul_f32_e32 v18, v149, v18
	v_mul_f32_e32 v19, v149, v19
	v_mul_f32_e32 v26, v26, v18
	v_mul_f32_e32 v27, v27, v19
	v_cvt_pk_bf16_f32 v23, v26, v27
	s_nop 1
	v_permlane16_swap_b32_e32 v20, v22
	v_permlane16_swap_b32_e32 v21, v23
	global_store_dwordx4 v134, v[20:23], s[14:15]
	v_add_u32_e32 v134, 0x1d9000, v132
	v_mul_f32_e32 v135, 0xbfb8aa3b, v153
	v_mul_f32_e32 v149, v153, v153
	v_mul_f32_e32 v12, v4, v12
	v_mul_f32_e32 v13, v5, v13
	v_mul_f32_e32 v4, v135, v4
	v_mul_f32_e32 v5, v135, v5
	v_exp_f32_e32 v4, v4
	v_exp_f32_e32 v5, v5
	v_add_f32_e32 v4, 1.0, v4
	v_add_f32_e32 v5, 1.0, v5
	v_rcp_f32_e32 v4, v4
	v_rcp_f32_e32 v5, v5
	v_mul_f32_e32 v4, v149, v4
	v_mul_f32_e32 v5, v149, v5
	v_mul_f32_e32 v12, v12, v4
	v_mul_f32_e32 v13, v13, v5
	v_cvt_pk_bf16_f32 v4, v12, v13
	v_mul_f32_e32 v14, v6, v14
	v_mul_f32_e32 v15, v7, v15
	v_mul_f32_e32 v6, v135, v6
	v_mul_f32_e32 v7, v135, v7
	v_exp_f32_e32 v6, v6
	v_exp_f32_e32 v7, v7
	v_add_f32_e32 v6, 1.0, v6
	v_add_f32_e32 v7, 1.0, v7
	v_rcp_f32_e32 v6, v6
	v_rcp_f32_e32 v7, v7
	v_mul_f32_e32 v6, v149, v6
	v_mul_f32_e32 v7, v149, v7
	v_mul_f32_e32 v14, v14, v6
	v_mul_f32_e32 v15, v15, v7
	v_cvt_pk_bf16_f32 v5, v14, v15
	v_mul_f32_e32 v8, v0, v8
	v_mul_f32_e32 v9, v1, v9
	v_mul_f32_e32 v0, v135, v0
	v_mul_f32_e32 v1, v135, v1
	v_exp_f32_e32 v0, v0
	v_exp_f32_e32 v1, v1
	v_add_f32_e32 v0, 1.0, v0
	v_add_f32_e32 v1, 1.0, v1
	v_rcp_f32_e32 v0, v0
	v_rcp_f32_e32 v1, v1
	v_mul_f32_e32 v0, v149, v0
	v_mul_f32_e32 v1, v149, v1
	v_mul_f32_e32 v8, v8, v0
	v_mul_f32_e32 v9, v9, v1
	v_cvt_pk_bf16_f32 v6, v8, v9
	v_mul_f32_e32 v10, v2, v10
	v_mul_f32_e32 v11, v3, v11
	v_mul_f32_e32 v2, v135, v2
	v_mul_f32_e32 v3, v135, v3
	v_exp_f32_e32 v2, v2
	v_exp_f32_e32 v3, v3
	v_add_f32_e32 v2, 1.0, v2
	v_add_f32_e32 v3, 1.0, v3
	v_rcp_f32_e32 v2, v2
	v_rcp_f32_e32 v3, v3
	v_mul_f32_e32 v2, v149, v2
	v_mul_f32_e32 v3, v149, v3
	v_mul_f32_e32 v10, v10, v2
	v_mul_f32_e32 v11, v11, v3
	v_cvt_pk_bf16_f32 v7, v10, v11
	s_nop 1
	v_permlane16_swap_b32_e32 v4, v6
	v_permlane16_swap_b32_e32 v5, v7
	global_store_dwordx4 v134, v[4:7], s[14:15]
	s_waitcnt vmcnt(0)
	s_waitcnt vmcnt(0)
	v_add_f32_e32 v148, 0, v131
	s_barrier
	s_and_saveexec_b64 s[48:49], s[54:55]
	s_cbranch_execz .LBB0_766
	v_add_f32_e32 v0, v141, v148
	v_add_f32_e32 v0, v140, v0
	v_add_f32_e32 v0, v139, v0
	v_add_f32_e32 v0, v138, v0
	v_add_f32_e32 v0, v137, v0
	v_add_f32_e32 v0, v136, v0
	v_add_f32_e32 v0, v128, v0
	v_fmamk_f32 v0, v0, 0x3a000000, v143
	v_mul_f32_e32 v1, 0x4b800000, v0
	v_cmp_gt_f32_e32 vcc, s73, v0
	s_nop 1
	v_cndmask_b32_e32 v0, v0, v1, vcc
	v_rsq_f32_e32 v0, v0
	v_lshl_add_u32 v1, v130, 2, 0
	v_add_u32_e32 v1, 0x20000, v1
	v_mul_f32_e32 v2, 0x45800000, v0
	v_cndmask_b32_e32 v0, v0, v2, vcc
	ds_write_b32 v1, v0
	s_branch .LBB0_766

; #define STAGE(P, BASE, LD, br, kt) do { const char* _g = (const char*)((BASE) + (size_t)(br) * (LD) + (size_t)(kt) * 64); \
;     for (int _i = 0; _i < 2; ++_i) { int _b = tidx * 16 + _i * 8192; int _r, _c; stage_rc(_b, _r, _c); \
;       __builtin_amdgcn_global_load_lds((const unsigned*)(_g + (unsigned)((_r * (LD) + _c) * 2)), (unsigned*)((char*)(P) + _b), 16, 0, 0); } } while (0)
; #define LDA(dst, b, h) for (int m = 0; m < 4; ++m) for (int k = 0; k < 2; ++k) \
;     dst[m][k] = *reinterpret_cast<const bf16x8*>((char*)SA(b, h) + lds_byte(wr * 64 + m * 16 + fr, k * 32 + fq * 8))
; #define LDB(dst, b, h) for (int n = 0; n < 2; ++n) for (int k = 0; k < 2; ++k) \
;     dst[n][k] = *reinterpret_cast<const bf16x8*>((char*)SB(b, h) + lds_byte(wc * 32 + n * 16 + fr, k * 32 + fq * 8))
; #define MMA(ai, bj, At_, Bt_) do { __builtin_amdgcn_s_setprio(1); \
;     for (int k = 0; k < 2; ++k) for (int m = 0; m < 4; ++m) for (int n = 0; n < 2; ++n) \
;       acc[ai][bj][m][n] = __builtin_amdgcn_mfma_f32_16x16x32_bf16(At_[m][k], Bt_[n][k], acc[ai][bj][m][n], 0, 0, 0); \
;     __builtin_amdgcn_s_setprio(0); } while (0)
; #define WAIT_V(n) asm volatile("s_waitcnt vmcnt(" #n ")" ::: "memory")
; #define WAIT_L(n) asm volatile("s_waitcnt lgkmcnt(" #n ")" ::: "memory")
; #define BAR __builtin_amdgcn_s_barrier()
; #define SCHED __builtin_amdgcn_sched_barrier(0)
; template <int EPI, int lda, int ldb, int N, int K>
; __device__ __forceinline__ void gemm_phase(const u16* __restrict__ A, const u16* __restrict__ Bt, const GemmEpi ep, int wv) {
;     ...
;     for (int t = 0; t < nt - 2; t += 2) {
;       LDB(B0, 0, 0); SCHED; LDA(At, 0, 0); STAGE(SA(1, 1), Ab, lda, brow + HALF, t + 1);
;       WAIT_L(8); BAR; WAIT_L(0); MMA(0, 0, At, B0); BAR; SCHED;
;       LDB(B1, 0, 1); STAGE(SB(0, 0), Bt, ldb, bcol, t + 2);
;       BAR; WAIT_L(0); MMA(0, 1, At, B1); BAR;
;       LDA(At, 0, 1); STAGE(SA(0, 0), Ab, lda, brow, t + 2);
;       BAR; WAIT_L(0); MMA(1, 0, At, B0); BAR; SCHED;
;       STAGE(SB(0, 1), Bt, ldb, bcol + HALF, t + 2);
;       WAIT_V(6); BAR; MMA(1, 1, At, B1); BAR;
;       LDB(B0, 1, 0); SCHED; LDA(At, 1, 0); STAGE(SA(0, 1), Ab, lda, brow + HALF, t + 2);
;       WAIT_L(8); BAR; WAIT_L(0); MMA(0, 0, At, B0); BAR; SCHED;
.LBB0_1564:
	ds_read_b128 v[172:175], v161
	ds_read_b128 v[176:179], v161 offset:1024
	ds_read_b128 v[180:183], v161 offset:2048
	ds_read_b128 v[184:187], v161 offset:3072
	v_add_u32_e32 v169, 0xc000, v148
	v_lshl_add_u64 v[236:237], v[136:137], 0, s[40:41]
	v_readfirstlane_b32 s43, v169
	v_add_u32_e32 v170, 0xe000, v148
	v_lshl_add_u64 v[162:163], v[236:237], 0, s[14:15]
	s_mov_b32 m0, s43
	v_lshl_add_u64 v[238:239], v[134:135], 0, s[40:41]
	v_readfirstlane_b32 s43, v170
	ds_read_b128 v[164:167], v152
	ds_read_b128 v[188:191], v152 offset:1024
	ds_read_b128 v[192:195], v151
	ds_read_b128 v[196:199], v151 offset:1024
	ds_read_b128 v[200:203], v150
	ds_read_b128 v[204:207], v150 offset:1024
	ds_read_b128 v[208:211], v149
	ds_read_b128 v[212:215], v149 offset:1024
	global_load_lds_dwordx4 v[162:163], off
	v_lshl_add_u64 v[162:163], v[238:239], 0, s[14:15]
	s_mov_b32 m0, s43
	s_nop 0
	global_load_lds_dwordx4 v[162:163], off
	s_waitcnt lgkmcnt(8)
	s_barrier
	s_waitcnt lgkmcnt(0)
	s_setprio 1
	s_waitcnt lgkmcnt(0)
	v_mfma_f32_16x16x32_bf16 v[124:127], v[172:175], v[164:167], v[124:127]
	v_mfma_f32_16x16x32_bf16 v[120:123], v[180:183], v[164:167], v[120:123]
	v_mfma_f32_16x16x32_bf16 v[116:119], v[172:175], v[192:195], v[116:119]
	v_mfma_f32_16x16x32_bf16 v[112:115], v[180:183], v[192:195], v[112:115]
	v_mfma_f32_16x16x32_bf16 v[108:111], v[172:175], v[200:203], v[108:111]
	v_mfma_f32_16x16x32_bf16 v[104:107], v[180:183], v[200:203], v[104:107]
	v_mfma_f32_16x16x32_bf16 v[100:103], v[172:175], v[208:211], v[100:103]
	v_mfma_f32_16x16x32_bf16 v[96:99], v[180:183], v[208:211], v[96:99]
	v_mfma_f32_16x16x32_bf16 v[124:127], v[176:179], v[188:191], v[124:127]
	v_mfma_f32_16x16x32_bf16 v[120:123], v[184:187], v[188:191], v[120:123]
	v_mfma_f32_16x16x32_bf16 v[116:119], v[176:179], v[196:199], v[116:119]
	v_mfma_f32_16x16x32_bf16 v[112:115], v[184:187], v[196:199], v[112:115]
	v_mfma_f32_16x16x32_bf16 v[108:111], v[176:179], v[204:207], v[108:111]
	v_mfma_f32_16x16x32_bf16 v[104:107], v[184:187], v[204:207], v[104:107]
	v_mfma_f32_16x16x32_bf16 v[100:103], v[176:179], v[212:215], v[100:103]
	v_mfma_f32_16x16x32_bf16 v[96:99], v[184:187], v[212:215], v[96:99]
	s_setprio 0
	s_barrier
	v_add_u32_e32 v162, s52, v153
	v_lshl_add_u64 v[240:241], v[140:141], 0, s[40:41]
	v_readfirstlane_b32 s43, v162
	v_add_u32_e32 v163, 0x2000, v162
	v_lshl_add_u64 v[232:233], v[240:241], 0, s[16:17]
	s_mov_b32 m0, s43
	v_lshl_add_u64 v[242:243], v[138:139], 0, s[40:41]
	v_readfirstlane_b32 s43, v163
	ds_read_b128 v[216:219], v160
	ds_read_b128 v[220:223], v160 offset:1024
	ds_read_b128 v[224:227], v160 offset:2048
	ds_read_b128 v[228:231], v160 offset:3072
	global_load_lds_dwordx4 v[232:233], off
	v_lshl_add_u64 v[232:233], v[242:243], 0, s[16:17]
	s_mov_b32 m0, s43
	s_nop 0
	global_load_lds_dwordx4 v[232:233], off
	s_barrier
	s_waitcnt lgkmcnt(0)
	s_setprio 1
	s_waitcnt lgkmcnt(0)
	v_mfma_f32_16x16x32_bf16 v[92:95], v[216:219], v[164:167], v[92:95]
	v_mfma_f32_16x16x32_bf16 v[88:91], v[224:227], v[164:167], v[88:91]
	v_mfma_f32_16x16x32_bf16 v[84:87], v[216:219], v[192:195], v[84:87]
	v_mfma_f32_16x16x32_bf16 v[80:83], v[224:227], v[192:195], v[80:83]
	v_mfma_f32_16x16x32_bf16 v[76:79], v[216:219], v[200:203], v[76:79]
	v_mfma_f32_16x16x32_bf16 v[72:75], v[224:227], v[200:203], v[72:75]
	v_mfma_f32_16x16x32_bf16 v[68:71], v[216:219], v[208:211], v[68:71]
	v_mfma_f32_16x16x32_bf16 v[64:67], v[224:227], v[208:211], v[64:67]
	v_mfma_f32_16x16x32_bf16 v[92:95], v[220:223], v[188:191], v[92:95]
	v_mfma_f32_16x16x32_bf16 v[88:91], v[228:231], v[188:191], v[88:91]
	v_mfma_f32_16x16x32_bf16 v[84:87], v[220:223], v[196:199], v[84:87]
	v_mfma_f32_16x16x32_bf16 v[80:83], v[228:231], v[196:199], v[80:83]
	v_mfma_f32_16x16x32_bf16 v[76:79], v[220:223], v[204:207], v[76:79]
	v_mfma_f32_16x16x32_bf16 v[72:75], v[228:231], v[204:207], v[72:75]
	v_mfma_f32_16x16x32_bf16 v[68:71], v[220:223], v[212:215], v[68:71]
	v_mfma_f32_16x16x32_bf16 v[64:67], v[228:231], v[212:215], v[64:67]
	s_setprio 0
	v_readfirstlane_b32 s43, v148
	v_lshl_add_u64 v[164:165], v[236:237], 0, s[18:19]
	s_mov_b32 m0, s43
	s_barrier
	ds_read_b128 v[188:191], v152 offset:16384
	ds_read_b128 v[192:195], v152 offset:17408
	ds_read_b128 v[196:199], v151 offset:16384
	ds_read_b128 v[200:203], v151 offset:17408
	ds_read_b128 v[204:207], v150 offset:16384
	ds_read_b128 v[208:211], v150 offset:17408
	ds_read_b128 v[212:215], v149 offset:16384
	ds_read_b128 v[232:235], v149 offset:17408
	global_load_lds_dwordx4 v[164:165], off
	v_add_u32_e32 v164, 0x2000, v148
	v_lshl_add_u64 v[166:167], v[238:239], 0, s[18:19]
	v_readfirstlane_b32 s43, v164
	s_mov_b32 m0, s43
	s_nop 0
	global_load_lds_dwordx4 v[166:167], off
	s_barrier
	s_waitcnt lgkmcnt(0)
	s_setprio 1
	s_waitcnt lgkmcnt(0)
	v_mfma_f32_16x16x32_bf16 v[60:63], v[172:175], v[188:191], v[60:63]
	v_mfma_f32_16x16x32_bf16 v[56:59], v[180:183], v[188:191], v[56:59]
	v_mfma_f32_16x16x32_bf16 v[52:55], v[172:175], v[196:199], v[52:55]
	v_mfma_f32_16x16x32_bf16 v[48:51], v[180:183], v[196:199], v[48:51]
	v_mfma_f32_16x16x32_bf16 v[44:47], v[172:175], v[204:207], v[44:47]
	v_mfma_f32_16x16x32_bf16 v[40:43], v[180:183], v[204:207], v[40:43]
	v_mfma_f32_16x16x32_bf16 v[36:39], v[172:175], v[212:215], v[36:39]
	v_mfma_f32_16x16x32_bf16 v[32:35], v[180:183], v[212:215], v[32:35]
	v_mfma_f32_16x16x32_bf16 v[60:63], v[176:179], v[192:195], v[60:63]
	v_mfma_f32_16x16x32_bf16 v[56:59], v[184:187], v[192:195], v[56:59]
	v_mfma_f32_16x16x32_bf16 v[52:55], v[176:179], v[200:203], v[52:55]
	v_mfma_f32_16x16x32_bf16 v[48:51], v[184:187], v[200:203], v[48:51]
	v_mfma_f32_16x16x32_bf16 v[44:47], v[176:179], v[208:211], v[44:47]
	v_mfma_f32_16x16x32_bf16 v[40:43], v[184:187], v[208:211], v[40:43]
	v_mfma_f32_16x16x32_bf16 v[36:39], v[176:179], v[232:235], v[36:39]
	v_mfma_f32_16x16x32_bf16 v[32:35], v[184:187], v[232:235], v[32:35]
	s_setprio 0
	s_barrier
; #define STAGE(P, BASE, LD, br, kt) do { const char* _g = (const char*)((BASE) + (size_t)(br) * (LD) + (size_t)(kt) * 64); \
;     for (int _i = 0; _i < 2; ++_i) { int _b = tidx * 16 + _i * 8192; int _r, _c; stage_rc(_b, _r, _c); \
;       __builtin_amdgcn_global_load_lds((const unsigned*)(_g + (unsigned)((_r * (LD) + _c) * 2)), (unsigned*)((char*)(P) + _b), 16, 0, 0); } } while (0)
; #define LDA(dst, b, h) for (int m = 0; m < 4; ++m) for (int k = 0; k < 2; ++k) \
;     dst[m][k] = *reinterpret_cast<const bf16x8*>((char*)SA(b, h) + lds_byte(wr * 64 + m * 16 + fr, k * 32 + fq * 8))
; #define LDB(dst, b, h) for (int n = 0; n < 2; ++n) for (int k = 0; k < 2; ++k) \
;     dst[n][k] = *reinterpret_cast<const bf16x8*>((char*)SB(b, h) + lds_byte(wc * 32 + n * 16 + fr, k * 32 + fq * 8))
; #define MMA(ai, bj, At_, Bt_) do { __builtin_amdgcn_s_setprio(1); \
;     for (int k = 0; k < 2; ++k) for (int m = 0; m < 4; ++m) for (int n = 0; n < 2; ++n) \
;       acc[ai][bj][m][n] = __builtin_amdgcn_mfma_f32_16x16x32_bf16(At_[m][k], Bt_[n][k], acc[ai][bj][m][n], 0, 0, 0); \
;     __builtin_amdgcn_s_setprio(0); } while (0)
; #define WAIT_V(n) asm volatile("s_waitcnt vmcnt(" #n ")" ::: "memory")
; #define WAIT_L(n) asm volatile("s_waitcnt lgkmcnt(" #n ")" ::: "memory")
; #define BAR __builtin_amdgcn_s_barrier()
; #define SCHED __builtin_amdgcn_sched_barrier(0)
; template <int EPI, int lda, int ldb, int N, int K>
; __device__ __forceinline__ void gemm_phase(const u16* __restrict__ A, const u16* __restrict__ Bt, const GemmEpi ep, int wv) {
;     ...
;       BAR; WAIT_L(0); MMA(1, 0, At, B0); BAR; SCHED;
;       STAGE(SB(0, 1), Bt, ldb, bcol + HALF, t + 2);
;       WAIT_V(6); BAR; MMA(1, 1, At, B1); BAR;
;       LDB(B0, 1, 0); SCHED; LDA(At, 1, 0); STAGE(SA(0, 1), Ab, lda, brow + HALF, t + 2);
;       WAIT_L(8); BAR; WAIT_L(0); MMA(0, 0, At, B0); BAR; SCHED;
;       LDB(B1, 1, 1); STAGE(SB(1, 0), Bt, ldb, bcol, t + 3);
;       BAR; WAIT_L(0); MMA(0, 1, At, B1); BAR;
;       LDA(At, 1, 1); STAGE(SA(1, 0), Ab, lda, brow, t + 3);
;       BAR; WAIT_L(0); MMA(1, 0, At, B0); BAR; SCHED;
;       STAGE(SB(1, 1), Bt, ldb, bcol + HALF, t + 3);
;       WAIT_V(6); BAR; MMA(1, 1, At, B1); BAR;
	v_add_u32_e32 v165, s53, v153
	v_lshl_add_u64 v[166:167], v[240:241], 0, s[20:21]
	v_readfirstlane_b32 s43, v165
	s_mov_b32 m0, s43
	v_lshl_add_u64 v[172:173], v[242:243], 0, s[20:21]
	global_load_lds_dwordx4 v[166:167], off
	v_add_u32_e32 v166, 0x2000, v165
	s_nop 0
	v_readfirstlane_b32 s43, v166
	s_mov_b32 m0, s43
	s_nop 0
	global_load_lds_dwordx4 v[172:173], off
	s_waitcnt vmcnt(6)
	s_barrier
	s_setprio 1
	v_mfma_f32_16x16x32_bf16 v[28:31], v[216:219], v[188:191], v[28:31]
	v_mfma_f32_16x16x32_bf16 v[24:27], v[224:227], v[188:191], v[24:27]
	v_mfma_f32_16x16x32_bf16 v[20:23], v[216:219], v[196:199], v[20:23]
	v_mfma_f32_16x16x32_bf16 v[16:19], v[224:227], v[196:199], v[16:19]
	v_mfma_f32_16x16x32_bf16 v[12:15], v[216:219], v[204:207], v[12:15]
	v_mfma_f32_16x16x32_bf16 v[8:11], v[224:227], v[204:207], v[8:11]
	v_mfma_f32_16x16x32_bf16 v[4:7], v[216:219], v[212:215], v[4:7]
	v_mfma_f32_16x16x32_bf16 v[0:3], v[224:227], v[212:215], v[0:3]
	v_mfma_f32_16x16x32_bf16 v[28:31], v[220:223], v[192:195], v[28:31]
	v_mfma_f32_16x16x32_bf16 v[24:27], v[228:231], v[192:195], v[24:27]
	v_mfma_f32_16x16x32_bf16 v[20:23], v[220:223], v[200:203], v[20:23]
	v_mfma_f32_16x16x32_bf16 v[16:19], v[228:231], v[200:203], v[16:19]
	v_mfma_f32_16x16x32_bf16 v[12:15], v[220:223], v[208:211], v[12:15]
	v_mfma_f32_16x16x32_bf16 v[8:11], v[228:231], v[208:211], v[8:11]
	v_mfma_f32_16x16x32_bf16 v[4:7], v[220:223], v[232:235], v[4:7]
	v_mfma_f32_16x16x32_bf16 v[0:3], v[228:231], v[232:235], v[0:3]
	s_setprio 0
	s_barrier
	ds_read_b128 v[172:175], v156
	ds_read_b128 v[176:179], v156 offset:1024
	ds_read_b128 v[180:183], v156 offset:2048
	ds_read_b128 v[184:187], v156 offset:3072
	v_add_u32_e32 v167, 0x4000, v148
	v_add_u32_e32 v168, 0x6000, v148
	v_readfirstlane_b32 s43, v167
	v_lshl_add_u64 v[220:221], v[236:237], 0, s[22:23]
	s_mov_b32 m0, s43
	v_readfirstlane_b32 s43, v168
	ds_read_b128 v[188:191], v152 offset:32768
	ds_read_b128 v[192:195], v152 offset:33792
	ds_read_b128 v[196:199], v151 offset:32768
	ds_read_b128 v[200:203], v151 offset:33792
	ds_read_b128 v[204:207], v150 offset:32768
	ds_read_b128 v[208:211], v150 offset:33792
	ds_read_b128 v[212:215], v149 offset:32768
	ds_read_b128 v[216:219], v149 offset:33792
	global_load_lds_dwordx4 v[220:221], off
	v_lshl_add_u64 v[220:221], v[238:239], 0, s[22:23]
	s_mov_b32 m0, s43
	s_nop 0
	global_load_lds_dwordx4 v[220:221], off
	s_waitcnt lgkmcnt(8)
	s_barrier
	s_waitcnt lgkmcnt(0)
	s_setprio 1
	s_waitcnt lgkmcnt(0)
	v_mfma_f32_16x16x32_bf16 v[124:127], v[172:175], v[188:191], v[124:127]
	v_mfma_f32_16x16x32_bf16 v[120:123], v[180:183], v[188:191], v[120:123]
	v_mfma_f32_16x16x32_bf16 v[116:119], v[172:175], v[196:199], v[116:119]
	v_mfma_f32_16x16x32_bf16 v[112:115], v[180:183], v[196:199], v[112:115]
	v_mfma_f32_16x16x32_bf16 v[108:111], v[172:175], v[204:207], v[108:111]
	v_mfma_f32_16x16x32_bf16 v[104:107], v[180:183], v[204:207], v[104:107]
	v_mfma_f32_16x16x32_bf16 v[100:103], v[172:175], v[212:215], v[100:103]
	v_mfma_f32_16x16x32_bf16 v[96:99], v[180:183], v[212:215], v[96:99]
	v_mfma_f32_16x16x32_bf16 v[124:127], v[176:179], v[192:195], v[124:127]
	v_mfma_f32_16x16x32_bf16 v[120:123], v[184:187], v[192:195], v[120:123]
	v_mfma_f32_16x16x32_bf16 v[116:119], v[176:179], v[200:203], v[116:119]
	v_mfma_f32_16x16x32_bf16 v[112:115], v[184:187], v[200:203], v[112:115]
	v_mfma_f32_16x16x32_bf16 v[108:111], v[176:179], v[208:211], v[108:111]
	v_mfma_f32_16x16x32_bf16 v[104:107], v[184:187], v[208:211], v[104:107]
	v_mfma_f32_16x16x32_bf16 v[100:103], v[176:179], v[216:219], v[100:103]
	v_mfma_f32_16x16x32_bf16 v[96:99], v[184:187], v[216:219], v[96:99]
	s_setprio 0
	s_barrier
	v_readfirstlane_b32 s43, v155
	v_add_u32_e32 v171, 0x2000, v155
	v_lshl_add_u64 v[244:245], v[240:241], 0, s[24:25]
	s_mov_b32 m0, s43
	v_readfirstlane_b32 s43, v171
	ds_read_b128 v[220:223], v154
	ds_read_b128 v[224:227], v154 offset:1024
	ds_read_b128 v[228:231], v154 offset:2048
	ds_read_b128 v[232:235], v154 offset:3072
	global_load_lds_dwordx4 v[244:245], off
	v_lshl_add_u64 v[244:245], v[242:243], 0, s[24:25]
	s_mov_b32 m0, s43
	s_nop 0
	global_load_lds_dwordx4 v[244:245], off
	s_barrier
	s_waitcnt lgkmcnt(0)
	s_setprio 1
	s_waitcnt lgkmcnt(0)
	v_mfma_f32_16x16x32_bf16 v[92:95], v[220:223], v[188:191], v[92:95]
	v_mfma_f32_16x16x32_bf16 v[88:91], v[228:231], v[188:191], v[88:91]
	v_mfma_f32_16x16x32_bf16 v[84:87], v[220:223], v[196:199], v[84:87]
	v_mfma_f32_16x16x32_bf16 v[80:83], v[228:231], v[196:199], v[80:83]
	v_mfma_f32_16x16x32_bf16 v[76:79], v[220:223], v[204:207], v[76:79]
	v_mfma_f32_16x16x32_bf16 v[72:75], v[228:231], v[204:207], v[72:75]
	v_mfma_f32_16x16x32_bf16 v[68:71], v[220:223], v[212:215], v[68:71]
	v_mfma_f32_16x16x32_bf16 v[64:67], v[228:231], v[212:215], v[64:67]
	v_mfma_f32_16x16x32_bf16 v[92:95], v[224:227], v[192:195], v[92:95]
	v_mfma_f32_16x16x32_bf16 v[88:91], v[232:235], v[192:195], v[88:91]
	v_mfma_f32_16x16x32_bf16 v[84:87], v[224:227], v[200:203], v[84:87]
	v_mfma_f32_16x16x32_bf16 v[80:83], v[232:235], v[200:203], v[80:83]
	v_mfma_f32_16x16x32_bf16 v[76:79], v[224:227], v[208:211], v[76:79]
	v_mfma_f32_16x16x32_bf16 v[72:75], v[232:235], v[208:211], v[72:75]
	v_mfma_f32_16x16x32_bf16 v[68:71], v[224:227], v[216:219], v[68:71]
	v_mfma_f32_16x16x32_bf16 v[64:67], v[232:235], v[216:219], v[64:67]
	s_setprio 0
	v_readfirstlane_b32 s43, v157
	v_lshl_add_u64 v[236:237], v[236:237], 0, s[26:27]
	s_mov_b32 m0, s43
	v_readfirstlane_b32 s43, v158
	s_barrier
; #define STAGE(P, BASE, LD, br, kt) do { const char* _g = (const char*)((BASE) + (size_t)(br) * (LD) + (size_t)(kt) * 64); \
;     for (int _i = 0; _i < 2; ++_i) { int _b = tidx * 16 + _i * 8192; int _r, _c; stage_rc(_b, _r, _c); \
;       __builtin_amdgcn_global_load_lds((const unsigned*)(_g + (unsigned)((_r * (LD) + _c) * 2)), (unsigned*)((char*)(P) + _b), 16, 0, 0); } } while (0)
; #define LDA(dst, b, h) for (int m = 0; m < 4; ++m) for (int k = 0; k < 2; ++k) \
;     dst[m][k] = *reinterpret_cast<const bf16x8*>((char*)SA(b, h) + lds_byte(wr * 64 + m * 16 + fr, k * 32 + fq * 8))
; #define LDB(dst, b, h) for (int n = 0; n < 2; ++n) for (int k = 0; k < 2; ++k) \
;     dst[n][k] = *reinterpret_cast<const bf16x8*>((char*)SB(b, h) + lds_byte(wc * 32 + n * 16 + fr, k * 32 + fq * 8))
; #define MMA(ai, bj, At_, Bt_) do { __builtin_amdgcn_s_setprio(1); \
;     for (int k = 0; k < 2; ++k) for (int m = 0; m < 4; ++m) for (int n = 0; n < 2; ++n) \
;       acc[ai][bj][m][n] = __builtin_amdgcn_mfma_f32_16x16x32_bf16(At_[m][k], Bt_[n][k], acc[ai][bj][m][n], 0, 0, 0); \
;     __builtin_amdgcn_s_setprio(0); } while (0)
; #define WAIT_V(n) asm volatile("s_waitcnt vmcnt(" #n ")" ::: "memory")
; #define WAIT_L(n) asm volatile("s_waitcnt lgkmcnt(" #n ")" ::: "memory")
; #define BAR __builtin_amdgcn_s_barrier()
; #define SCHED __builtin_amdgcn_sched_barrier(0)
; template <int EPI, int lda, int ldb, int N, int K>
; __device__ __forceinline__ void gemm_phase(const u16* __restrict__ A, const u16* __restrict__ Bt, const GemmEpi ep, int wv) {
;     ...
;       LDA(At, 1, 1); STAGE(SA(1, 0), Ab, lda, brow, t + 3);
;       BAR; WAIT_L(0); MMA(1, 0, At, B0); BAR; SCHED;
;       STAGE(SB(1, 1), Bt, ldb, bcol + HALF, t + 3);
;       WAIT_V(6); BAR; MMA(1, 1, At, B1); BAR;
;     }
;     { LDB(B0, 0, 0); LDA(At, 0, 0); STAGE(SA(1, 1), Ab, lda, brow + HALF, nt - 1);
;       BAR; WAIT_L(0); MMA(0, 0, At, B0); BAR;
;       LDB(B1, 0, 1); BAR; WAIT_L(0); MMA(0, 1, At, B1); BAR;
	ds_read_b128 v[188:191], v152 offset:49152
	ds_read_b128 v[192:195], v152 offset:50176
	ds_read_b128 v[196:199], v151 offset:49152
	ds_read_b128 v[200:203], v151 offset:50176
	ds_read_b128 v[204:207], v150 offset:49152
	ds_read_b128 v[208:211], v150 offset:50176
	ds_read_b128 v[212:215], v149 offset:49152
	ds_read_b128 v[216:219], v149 offset:50176
	global_load_lds_dwordx4 v[236:237], off
	v_lshl_add_u64 v[236:237], v[238:239], 0, s[26:27]
	s_mov_b32 m0, s43
	s_nop 0
	global_load_lds_dwordx4 v[236:237], off
	s_barrier
	s_waitcnt lgkmcnt(0)
	s_setprio 1
	s_waitcnt lgkmcnt(0)
	v_mfma_f32_16x16x32_bf16 v[60:63], v[172:175], v[188:191], v[60:63]
	v_mfma_f32_16x16x32_bf16 v[56:59], v[180:183], v[188:191], v[56:59]
	v_mfma_f32_16x16x32_bf16 v[52:55], v[172:175], v[196:199], v[52:55]
	v_mfma_f32_16x16x32_bf16 v[48:51], v[180:183], v[196:199], v[48:51]
	v_mfma_f32_16x16x32_bf16 v[44:47], v[172:175], v[204:207], v[44:47]
	v_mfma_f32_16x16x32_bf16 v[40:43], v[180:183], v[204:207], v[40:43]
	v_mfma_f32_16x16x32_bf16 v[36:39], v[172:175], v[212:215], v[36:39]
	v_mfma_f32_16x16x32_bf16 v[32:35], v[180:183], v[212:215], v[32:35]
	v_mfma_f32_16x16x32_bf16 v[60:63], v[176:179], v[192:195], v[60:63]
	v_mfma_f32_16x16x32_bf16 v[56:59], v[184:187], v[192:195], v[56:59]
	v_mfma_f32_16x16x32_bf16 v[52:55], v[176:179], v[200:203], v[52:55]
	v_mfma_f32_16x16x32_bf16 v[48:51], v[184:187], v[200:203], v[48:51]
	v_mfma_f32_16x16x32_bf16 v[44:47], v[176:179], v[208:211], v[44:47]
	v_mfma_f32_16x16x32_bf16 v[40:43], v[184:187], v[208:211], v[40:43]
	v_mfma_f32_16x16x32_bf16 v[36:39], v[176:179], v[216:219], v[36:39]
	v_mfma_f32_16x16x32_bf16 v[32:35], v[184:187], v[216:219], v[32:35]
	s_setprio 0
	s_barrier
	v_readfirstlane_b32 s43, v159
	v_add_u32_e32 v171, 0x2000, v159
	v_lshl_add_u64 v[172:173], v[240:241], 0, s[34:35]
	s_mov_b32 m0, s43
	v_readfirstlane_b32 s43, v171
	global_load_lds_dwordx4 v[172:173], off
	v_lshl_add_u64 v[172:173], v[242:243], 0, s[34:35]
	s_mov_b32 m0, s43
	s_nop 0
	global_load_lds_dwordx4 v[172:173], off
	s_waitcnt vmcnt(6)
	s_barrier
	s_setprio 1
	v_mfma_f32_16x16x32_bf16 v[28:31], v[220:223], v[188:191], v[28:31]
	v_mfma_f32_16x16x32_bf16 v[24:27], v[228:231], v[188:191], v[24:27]
	v_mfma_f32_16x16x32_bf16 v[20:23], v[220:223], v[196:199], v[20:23]
	v_mfma_f32_16x16x32_bf16 v[16:19], v[228:231], v[196:199], v[16:19]
	v_mfma_f32_16x16x32_bf16 v[12:15], v[220:223], v[204:207], v[12:15]
	v_mfma_f32_16x16x32_bf16 v[8:11], v[228:231], v[204:207], v[8:11]
	v_mfma_f32_16x16x32_bf16 v[4:7], v[220:223], v[212:215], v[4:7]
	v_mfma_f32_16x16x32_bf16 v[0:3], v[228:231], v[212:215], v[0:3]
	v_mfma_f32_16x16x32_bf16 v[28:31], v[224:227], v[192:195], v[28:31]
	v_mfma_f32_16x16x32_bf16 v[24:27], v[232:235], v[192:195], v[24:27]
	v_mfma_f32_16x16x32_bf16 v[20:23], v[224:227], v[200:203], v[20:23]
	v_mfma_f32_16x16x32_bf16 v[16:19], v[232:235], v[200:203], v[16:19]
	v_mfma_f32_16x16x32_bf16 v[12:15], v[224:227], v[208:211], v[12:15]
	v_mfma_f32_16x16x32_bf16 v[8:11], v[232:235], v[208:211], v[8:11]
	v_mfma_f32_16x16x32_bf16 v[4:7], v[224:227], v[216:219], v[4:7]
	v_mfma_f32_16x16x32_bf16 v[0:3], v[232:235], v[216:219], v[0:3]
	s_setprio 0
	s_add_i32 s42, s42, 2
	s_add_u32 s40, s40, 0x100
	s_addc_u32 s41, s41, 0
	s_cmp_gt_u32 s42, 27
	s_barrier
	s_cbranch_scc0 .LBB0_1564
	s_add_i32 s40, s38, 0x80
	s_mul_hi_i32 s41, s40, 0x1080
	s_mulk_i32 s40, 0x1080
	s_add_u32 s40, s49, s40
	s_addc_u32 s41, s50, s41
	v_lshl_add_u64 v[158:159], s[40:41], 0, v[128:129]
	v_readfirstlane_b32 s42, v169
	v_lshl_add_u64 v[158:159], v[158:159], 0, s[36:37]
	s_mov_b32 m0, s42
	ds_read_b128 v[134:137], v161
	ds_read_b128 v[138:141], v161 offset:1024
	ds_read_b128 v[172:175], v161 offset:2048
	ds_read_b128 v[176:179], v161 offset:3072
	ds_read_b128 v[180:183], v152
	ds_read_b128 v[184:187], v152 offset:1024
	ds_read_b128 v[188:191], v151
	ds_read_b128 v[192:195], v151 offset:1024
	ds_read_b128 v[196:199], v150
	ds_read_b128 v[200:203], v150 offset:1024
	ds_read_b128 v[204:207], v149
	ds_read_b128 v[208:211], v149 offset:1024
	global_load_lds_dwordx4 v[158:159], off
	v_lshl_add_u64 v[158:159], s[40:41], 0, v[132:133]
	v_readfirstlane_b32 s40, v170
	v_lshl_add_u64 v[158:159], v[158:159], 0, s[36:37]
	s_mov_b32 m0, s40
	s_nop 0
	global_load_lds_dwordx4 v[158:159], off
	s_barrier
	s_waitcnt lgkmcnt(0)
	s_setprio 1
	s_waitcnt lgkmcnt(0)
	v_mfma_f32_16x16x32_bf16 v[124:127], v[134:137], v[180:183], v[124:127]
	v_mfma_f32_16x16x32_bf16 v[120:123], v[172:175], v[180:183], v[120:123]
	v_mfma_f32_16x16x32_bf16 v[116:119], v[134:137], v[188:191], v[116:119]
	v_mfma_f32_16x16x32_bf16 v[112:115], v[172:175], v[188:191], v[112:115]
	v_mfma_f32_16x16x32_bf16 v[108:111], v[134:137], v[196:199], v[108:111]
	v_mfma_f32_16x16x32_bf16 v[104:107], v[172:175], v[196:199], v[104:107]
	v_mfma_f32_16x16x32_bf16 v[100:103], v[134:137], v[204:207], v[100:103]
	v_mfma_f32_16x16x32_bf16 v[96:99], v[172:175], v[204:207], v[96:99]
	v_mfma_f32_16x16x32_bf16 v[124:127], v[138:141], v[184:187], v[124:127]
	v_mfma_f32_16x16x32_bf16 v[120:123], v[176:179], v[184:187], v[120:123]
	v_mfma_f32_16x16x32_bf16 v[116:119], v[138:141], v[192:195], v[116:119]
	v_mfma_f32_16x16x32_bf16 v[112:115], v[176:179], v[192:195], v[112:115]
	v_mfma_f32_16x16x32_bf16 v[108:111], v[138:141], v[200:203], v[108:111]
	v_mfma_f32_16x16x32_bf16 v[104:107], v[176:179], v[200:203], v[104:107]
	v_mfma_f32_16x16x32_bf16 v[100:103], v[138:141], v[208:211], v[100:103]
	v_mfma_f32_16x16x32_bf16 v[96:99], v[176:179], v[208:211], v[96:99]
	s_setprio 0
	s_barrier
	ds_read_b128 v[212:215], v160
	ds_read_b128 v[216:219], v160 offset:1024
	ds_read_b128 v[220:223], v160 offset:2048
	ds_read_b128 v[158:161], v160 offset:3072
	s_barrier
; #define LDA(dst, b, h) for (int m = 0; m < 4; ++m) for (int k = 0; k < 2; ++k) \
;     dst[m][k] = *reinterpret_cast<const bf16x8*>((char*)SA(b, h) + lds_byte(wr * 64 + m * 16 + fr, k * 32 + fq * 8))
; #define LDB(dst, b, h) for (int n = 0; n < 2; ++n) for (int k = 0; k < 2; ++k) \
;     dst[n][k] = *reinterpret_cast<const bf16x8*>((char*)SB(b, h) + lds_byte(wc * 32 + n * 16 + fr, k * 32 + fq * 8))
; #define MMA(ai, bj, At_, Bt_) do { __builtin_amdgcn_s_setprio(1); \
;     for (int k = 0; k < 2; ++k) for (int m = 0; m < 4; ++m) for (int n = 0; n < 2; ++n) \
;       acc[ai][bj][m][n] = __builtin_amdgcn_mfma_f32_16x16x32_bf16(At_[m][k], Bt_[n][k], acc[ai][bj][m][n], 0, 0, 0); \
;     __builtin_amdgcn_s_setprio(0); } while (0)
; #define WAIT_V(n) asm volatile("s_waitcnt vmcnt(" #n ")" ::: "memory")
; #define WAIT_L(n) asm volatile("s_waitcnt lgkmcnt(" #n ")" ::: "memory")
; #define BAR __builtin_amdgcn_s_barrier()
; template <int EPI, int lda, int ldb, int N, int K>
; __device__ __forceinline__ void gemm_phase(const u16* __restrict__ A, const u16* __restrict__ Bt, const GemmEpi ep, int wv) {
;     ...
;       BAR; WAIT_L(0); MMA(0, 0, At, B0); BAR;
;       LDB(B1, 0, 1); BAR; WAIT_L(0); MMA(0, 1, At, B1); BAR;
;       LDA(At, 0, 1); WAIT_V(4); BAR; WAIT_L(0); MMA(1, 0, At, B0); MMA(1, 1, At, B1); BAR; }
;     { LDB(B0, 1, 0); LDA(At, 1, 0); WAIT_V(2); BAR; WAIT_L(0); MMA(0, 0, At, B0); BAR;
;       LDB(B1, 1, 1); WAIT_V(0); BAR; WAIT_L(0); MMA(0, 1, At, B1); BAR;
	s_waitcnt lgkmcnt(0)
	s_setprio 1
	s_waitcnt lgkmcnt(0)
	v_mfma_f32_16x16x32_bf16 v[92:95], v[212:215], v[180:183], v[92:95]
	v_mfma_f32_16x16x32_bf16 v[88:91], v[220:223], v[180:183], v[88:91]
	v_mfma_f32_16x16x32_bf16 v[76:79], v[212:215], v[196:199], v[76:79]
	v_mfma_f32_16x16x32_bf16 v[72:75], v[220:223], v[196:199], v[72:75]
	v_mfma_f32_16x16x32_bf16 v[84:87], v[212:215], v[188:191], v[84:87]
	v_mfma_f32_16x16x32_bf16 v[80:83], v[220:223], v[188:191], v[80:83]
	v_mfma_f32_16x16x32_bf16 v[68:71], v[212:215], v[204:207], v[68:71]
	v_mfma_f32_16x16x32_bf16 v[64:67], v[220:223], v[204:207], v[64:67]
	v_mfma_f32_16x16x32_bf16 v[92:95], v[216:219], v[184:187], v[92:95]
	v_mfma_f32_16x16x32_bf16 v[88:91], v[158:161], v[184:187], v[88:91]
	v_mfma_f32_16x16x32_bf16 v[76:79], v[216:219], v[200:203], v[76:79]
	v_mfma_f32_16x16x32_bf16 v[72:75], v[158:161], v[200:203], v[72:75]
	v_mfma_f32_16x16x32_bf16 v[180:183], v[216:219], v[192:195], v[84:87]
	v_mfma_f32_16x16x32_bf16 v[184:187], v[158:161], v[192:195], v[80:83]
	v_mfma_f32_16x16x32_bf16 v[188:191], v[216:219], v[208:211], v[68:71]
	v_mfma_f32_16x16x32_bf16 v[192:195], v[158:161], v[208:211], v[64:67]
	s_setprio 0
	s_barrier
	s_nop 0
	ds_read_b128 v[64:67], v152 offset:16384
	ds_read_b128 v[68:71], v152 offset:17408
	ds_read_b128 v[80:83], v151 offset:16384
	ds_read_b128 v[84:87], v151 offset:17408
	ds_read_b128 v[196:199], v150 offset:16384
	ds_read_b128 v[200:203], v150 offset:17408
	ds_read_b128 v[204:207], v149 offset:16384
	ds_read_b128 v[208:211], v149 offset:17408
	s_waitcnt vmcnt(4)
	s_barrier
	s_waitcnt lgkmcnt(0)
	s_setprio 1
	s_waitcnt lgkmcnt(0)
	v_mfma_f32_16x16x32_bf16 v[60:63], v[134:137], v[64:67], v[60:63]
	v_mfma_f32_16x16x32_bf16 v[56:59], v[172:175], v[64:67], v[56:59]
	v_mfma_f32_16x16x32_bf16 v[52:55], v[134:137], v[80:83], v[52:55]
	v_mfma_f32_16x16x32_bf16 v[48:51], v[172:175], v[80:83], v[48:51]
	v_mfma_f32_16x16x32_bf16 v[44:47], v[134:137], v[196:199], v[44:47]
	v_mfma_f32_16x16x32_bf16 v[40:43], v[172:175], v[196:199], v[40:43]
	v_mfma_f32_16x16x32_bf16 v[36:39], v[134:137], v[204:207], v[36:39]
	v_mfma_f32_16x16x32_bf16 v[32:35], v[172:175], v[204:207], v[32:35]
	v_mfma_f32_16x16x32_bf16 v[60:63], v[138:141], v[68:71], v[60:63]
	v_mfma_f32_16x16x32_bf16 v[56:59], v[176:179], v[68:71], v[56:59]
	v_mfma_f32_16x16x32_bf16 v[52:55], v[138:141], v[84:87], v[52:55]
	v_mfma_f32_16x16x32_bf16 v[48:51], v[176:179], v[84:87], v[48:51]
	v_mfma_f32_16x16x32_bf16 v[44:47], v[138:141], v[200:203], v[44:47]
	v_mfma_f32_16x16x32_bf16 v[40:43], v[176:179], v[200:203], v[40:43]
	v_mfma_f32_16x16x32_bf16 v[36:39], v[138:141], v[208:211], v[36:39]
	v_mfma_f32_16x16x32_bf16 v[32:35], v[176:179], v[208:211], v[32:35]
	s_setprio 0
	s_setprio 1
	v_mfma_f32_16x16x32_bf16 v[28:31], v[212:215], v[64:67], v[28:31]
	v_mfma_f32_16x16x32_bf16 v[24:27], v[220:223], v[64:67], v[24:27]
	v_mfma_f32_16x16x32_bf16 v[12:15], v[212:215], v[196:199], v[12:15]
	v_mfma_f32_16x16x32_bf16 v[8:11], v[220:223], v[196:199], v[8:11]
	v_mfma_f32_16x16x32_bf16 v[20:23], v[212:215], v[80:83], v[20:23]
	v_mfma_f32_16x16x32_bf16 v[16:19], v[220:223], v[80:83], v[16:19]
	v_mfma_f32_16x16x32_bf16 v[4:7], v[212:215], v[204:207], v[4:7]
	v_mfma_f32_16x16x32_bf16 v[0:3], v[220:223], v[204:207], v[0:3]
	v_mfma_f32_16x16x32_bf16 v[28:31], v[216:219], v[68:71], v[28:31]
	v_mfma_f32_16x16x32_bf16 v[24:27], v[158:161], v[68:71], v[24:27]
	v_mfma_f32_16x16x32_bf16 v[12:15], v[216:219], v[200:203], v[12:15]
	v_mfma_f32_16x16x32_bf16 v[8:11], v[158:161], v[200:203], v[8:11]
	v_mfma_f32_16x16x32_bf16 v[134:137], v[216:219], v[84:87], v[20:23]
	v_mfma_f32_16x16x32_bf16 v[138:141], v[158:161], v[84:87], v[16:19]
	v_mfma_f32_16x16x32_bf16 v[170:173], v[216:219], v[208:211], v[4:7]
	v_mfma_f32_16x16x32_bf16 v[158:161], v[158:161], v[208:211], v[0:3]
	s_setprio 0
	s_barrier
	s_nop 0
	ds_read_b128 v[0:3], v156
	ds_read_b128 v[4:7], v156 offset:1024
	ds_read_b128 v[16:19], v156 offset:2048
	ds_read_b128 v[174:177], v156 offset:3072
	ds_read_b128 v[20:23], v152 offset:32768
	ds_read_b128 v[196:199], v152 offset:33792
	ds_read_b128 v[200:203], v151 offset:32768
	ds_read_b128 v[204:207], v151 offset:33792
	ds_read_b128 v[208:211], v150 offset:32768
	ds_read_b128 v[212:215], v150 offset:33792
	ds_read_b128 v[216:219], v149 offset:32768
	ds_read_b128 v[220:223], v149 offset:33792
	s_waitcnt vmcnt(2)
	s_barrier
; #define LDA(dst, b, h) for (int m = 0; m < 4; ++m) for (int k = 0; k < 2; ++k) \
;     dst[m][k] = *reinterpret_cast<const bf16x8*>((char*)SA(b, h) + lds_byte(wr * 64 + m * 16 + fr, k * 32 + fq * 8))
; #define LDB(dst, b, h) for (int n = 0; n < 2; ++n) for (int k = 0; k < 2; ++k) \
;     dst[n][k] = *reinterpret_cast<const bf16x8*>((char*)SB(b, h) + lds_byte(wc * 32 + n * 16 + fr, k * 32 + fq * 8))
; #define MMA(ai, bj, At_, Bt_) do { __builtin_amdgcn_s_setprio(1); \
;     for (int k = 0; k < 2; ++k) for (int m = 0; m < 4; ++m) for (int n = 0; n < 2; ++n) \
;       acc[ai][bj][m][n] = __builtin_amdgcn_mfma_f32_16x16x32_bf16(At_[m][k], Bt_[n][k], acc[ai][bj][m][n], 0, 0, 0); \
;     __builtin_amdgcn_s_setprio(0); } while (0)
; #define WAIT_V(n) asm volatile("s_waitcnt vmcnt(" #n ")" ::: "memory")
; #define WAIT_L(n) asm volatile("s_waitcnt lgkmcnt(" #n ")" ::: "memory")
; #define BAR __builtin_amdgcn_s_barrier()
; template <int EPI, int lda, int ldb, int N, int K>
; __device__ __forceinline__ void gemm_phase(const u16* __restrict__ A, const u16* __restrict__ Bt, const GemmEpi ep, int wv) {
;     ...
;       LDA(At, 0, 1); WAIT_V(4); BAR; WAIT_L(0); MMA(1, 0, At, B0); MMA(1, 1, At, B1); BAR; }
;     { LDB(B0, 1, 0); LDA(At, 1, 0); WAIT_V(2); BAR; WAIT_L(0); MMA(0, 0, At, B0); BAR;
;       LDB(B1, 1, 1); WAIT_V(0); BAR; WAIT_L(0); MMA(0, 1, At, B1); BAR;
;       LDA(At, 1, 1); BAR; WAIT_L(0); MMA(1, 0, At, B0); MMA(1, 1, At, B1); BAR; }
;     if (wr == 0) BAR;
	s_waitcnt lgkmcnt(0)
	s_setprio 1
	s_waitcnt lgkmcnt(0)
	v_mfma_f32_16x16x32_bf16 v[64:67], v[0:3], v[20:23], v[124:127]
	v_mfma_f32_16x16x32_bf16 v[68:71], v[16:19], v[20:23], v[120:123]
	v_mfma_f32_16x16x32_bf16 v[80:83], v[0:3], v[200:203], v[116:119]
	v_mfma_f32_16x16x32_bf16 v[84:87], v[16:19], v[200:203], v[112:115]
	v_mfma_f32_16x16x32_bf16 v[108:111], v[0:3], v[208:211], v[108:111]
	v_mfma_f32_16x16x32_bf16 v[104:107], v[16:19], v[208:211], v[104:107]
	v_mfma_f32_16x16x32_bf16 v[120:123], v[0:3], v[216:219], v[100:103]
	v_mfma_f32_16x16x32_bf16 v[124:127], v[16:19], v[216:219], v[96:99]
	v_mfma_f32_16x16x32_bf16 v[116:119], v[4:7], v[196:199], v[64:67]
	v_mfma_f32_16x16x32_bf16 v[112:115], v[174:177], v[196:199], v[68:71]
	v_mfma_f32_16x16x32_bf16 v[100:103], v[4:7], v[204:207], v[80:83]
	v_mfma_f32_16x16x32_bf16 v[96:99], v[174:177], v[204:207], v[84:87]
	v_mfma_f32_16x16x32_bf16 v[84:87], v[4:7], v[212:215], v[108:111]
	v_mfma_f32_16x16x32_bf16 v[80:83], v[174:177], v[212:215], v[104:107]
	v_mfma_f32_16x16x32_bf16 v[68:71], v[4:7], v[220:223], v[120:123]
	v_mfma_f32_16x16x32_bf16 v[64:67], v[174:177], v[220:223], v[124:127]
	s_setprio 0
	s_barrier
	ds_read_b128 v[224:227], v154
	ds_read_b128 v[228:231], v154 offset:1024
	ds_read_b128 v[232:235], v154 offset:2048
	ds_read_b128 v[154:157], v154 offset:3072
	s_waitcnt vmcnt(0)
	s_barrier
	s_waitcnt lgkmcnt(0)
	s_setprio 1
	s_waitcnt lgkmcnt(0)
	v_mfma_f32_16x16x32_bf16 v[92:95], v[224:227], v[20:23], v[92:95]
	v_mfma_f32_16x16x32_bf16 v[20:23], v[232:235], v[20:23], v[88:91]
	v_mfma_f32_16x16x32_bf16 v[88:91], v[224:227], v[200:203], v[180:183]
	v_mfma_f32_16x16x32_bf16 v[104:107], v[232:235], v[200:203], v[184:187]
	v_mfma_f32_16x16x32_bf16 v[76:79], v[224:227], v[208:211], v[76:79]
	v_mfma_f32_16x16x32_bf16 v[72:75], v[232:235], v[208:211], v[72:75]
	v_mfma_f32_16x16x32_bf16 v[178:181], v[224:227], v[216:219], v[188:191]
	v_mfma_f32_16x16x32_bf16 v[182:185], v[232:235], v[216:219], v[192:195]
	v_mfma_f32_16x16x32_bf16 v[124:127], v[228:231], v[196:199], v[92:95]
	v_mfma_f32_16x16x32_bf16 v[120:123], v[154:157], v[196:199], v[20:23]
	v_mfma_f32_16x16x32_bf16 v[108:111], v[228:231], v[204:207], v[88:91]
	v_mfma_f32_16x16x32_bf16 v[104:107], v[154:157], v[204:207], v[104:107]
	v_mfma_f32_16x16x32_bf16 v[92:95], v[228:231], v[212:215], v[76:79]
	v_mfma_f32_16x16x32_bf16 v[88:91], v[154:157], v[212:215], v[72:75]
	v_mfma_f32_16x16x32_bf16 v[76:79], v[228:231], v[220:223], v[178:181]
	v_mfma_f32_16x16x32_bf16 v[72:75], v[154:157], v[220:223], v[182:185]
	s_setprio 0
	s_barrier
	ds_read_b128 v[178:181], v152 offset:49152
	ds_read_b128 v[182:185], v152 offset:50176
	ds_read_b128 v[186:189], v151 offset:49152
	ds_read_b128 v[190:193], v151 offset:50176
	ds_read_b128 v[194:197], v150 offset:49152
	ds_read_b128 v[150:153], v150 offset:50176
	ds_read_b128 v[198:201], v149 offset:49152
	ds_read_b128 v[202:205], v149 offset:50176
	s_barrier
	s_waitcnt lgkmcnt(0)
	s_setprio 1
	s_waitcnt lgkmcnt(0)
	v_mfma_f32_16x16x32_bf16 v[20:23], v[0:3], v[178:181], v[60:63]
	v_mfma_f32_16x16x32_bf16 v[56:59], v[16:19], v[178:181], v[56:59]
	v_mfma_f32_16x16x32_bf16 v[60:63], v[0:3], v[186:189], v[52:55]
	v_mfma_f32_16x16x32_bf16 v[206:209], v[16:19], v[186:189], v[48:51]
	v_mfma_f32_16x16x32_bf16 v[44:47], v[0:3], v[194:197], v[44:47]
	v_mfma_f32_16x16x32_bf16 v[40:43], v[16:19], v[194:197], v[40:43]
	v_mfma_f32_16x16x32_bf16 v[0:3], v[0:3], v[198:201], v[36:39]
	v_mfma_f32_16x16x32_bf16 v[210:213], v[16:19], v[198:201], v[32:35]
	v_mfma_f32_16x16x32_bf16 v[52:55], v[4:7], v[182:185], v[20:23]
	v_mfma_f32_16x16x32_bf16 v[48:51], v[174:177], v[182:185], v[56:59]
	v_mfma_f32_16x16x32_bf16 v[36:39], v[4:7], v[190:193], v[60:63]
	v_mfma_f32_16x16x32_bf16 v[32:35], v[174:177], v[190:193], v[206:209]
	v_mfma_f32_16x16x32_bf16 v[20:23], v[4:7], v[150:153], v[44:47]
	v_mfma_f32_16x16x32_bf16 v[16:19], v[174:177], v[150:153], v[40:43]
	v_mfma_f32_16x16x32_bf16 v[4:7], v[4:7], v[202:205], v[0:3]
	v_mfma_f32_16x16x32_bf16 v[0:3], v[174:177], v[202:205], v[210:213]
	s_setprio 0
	s_setprio 1
	v_mfma_f32_16x16x32_bf16 v[28:31], v[224:227], v[178:181], v[28:31]
	v_mfma_f32_16x16x32_bf16 v[24:27], v[232:235], v[178:181], v[24:27]
	v_mfma_f32_16x16x32_bf16 v[40:43], v[224:227], v[186:189], v[134:137]
	v_mfma_f32_16x16x32_bf16 v[134:137], v[232:235], v[186:189], v[138:141]
	v_mfma_f32_16x16x32_bf16 v[12:15], v[224:227], v[194:197], v[12:15]
	v_mfma_f32_16x16x32_bf16 v[8:11], v[232:235], v[194:197], v[8:11]
	v_mfma_f32_16x16x32_bf16 v[138:141], v[224:227], v[198:201], v[170:173]
	v_mfma_f32_16x16x32_bf16 v[158:161], v[232:235], v[198:201], v[158:161]
	v_mfma_f32_16x16x32_bf16 v[60:63], v[228:231], v[182:185], v[28:31]
	v_mfma_f32_16x16x32_bf16 v[56:59], v[154:157], v[182:185], v[24:27]
	v_mfma_f32_16x16x32_bf16 v[44:47], v[228:231], v[190:193], v[40:43]
	v_mfma_f32_16x16x32_bf16 v[40:43], v[154:157], v[190:193], v[134:137]
	v_mfma_f32_16x16x32_bf16 v[28:31], v[228:231], v[150:153], v[12:15]
	v_mfma_f32_16x16x32_bf16 v[24:27], v[154:157], v[150:153], v[8:11]
	v_mfma_f32_16x16x32_bf16 v[12:15], v[228:231], v[202:205], v[138:141]
	v_mfma_f32_16x16x32_bf16 v[8:11], v[154:157], v[202:205], v[158:161]
	s_setprio 0
	v_cmp_gt_u32_e32 vcc, s54, v130
	s_barrier
	s_and_saveexec_b64 s[40:41], vcc
	s_cbranch_execz .LBB0_1567
	s_barrier

; __device__ __forceinline__ u16 f2bf(float x) { return (u16)(cvtpk(x, x) & 0xffffu); }
; #define UNR _Pragma("unroll")
; template <int EPI, int lda, int ldb, int N, int K>
; __device__ __forceinline__ void gemm_phase(const u16* __restrict__ A, const u16* __restrict__ Bt, const GemmEpi ep, int wv) {
;     ...
;     if constexpr (EPI == EPI_SWIGLU) {
;       u16* out = reinterpret_cast<u16*>(ep.out0);
;       UNR for (int ai = 0; ai < 2; ++ai) UNR for (int m = 0; m < 4; ++m) {
;         const int rl0 = ai * HALF + wr * 64 + m * 16 + fq * 4;
;         const f32x4 r4 = *reinterpret_cast<const f32x4*>(lrs + rl0);
;         UNR for (int j = 0; j < 4; ++j) {
;           const int row = brow + rl0 + j;
;           const float rs = r4[j], ce = -1.4426950408889634f * rs, r2 = rs * rs;
;           UNR for (int n = 0; n < 2; ++n) {
;             const int col = (bcol >> 1) + wc * 32 + n * 16 + fr;
;             const float g = acc[ai][0][m][n][j], u = acc[ai][1][m][n][j];
;             const float sg = __builtin_amdgcn_rcpf(1.f + __builtin_amdgcn_exp2f(ce * g));
;             out[(size_t)row * ep.ldc + col] = f2bf((g * u) * (r2 * sg));
;           }
;         }
;       }
.LBB0_1571:
	s_or_b64 exec, exec, s[46:47]
	v_and_b32_e32 v135, 15, v130
	v_lshrrev_b32_e32 v149, 8, v130
	v_lshl_add_u32 v135, v149, 6, v135
	v_lshlrev_b32_e32 v133, 2, v135
	v_add_u32_e32 v133, 0x20000, v133
	ds_read_b32 v150, v133 offset:0
	ds_read_b32 v151, v133 offset:64
	ds_read_b32 v152, v133 offset:128
	ds_read_b32 v153, v133 offset:192
	v_add_u32_e32 v135, s38, v135
	v_mul_u32_u24_e32 v132, 0x2b00, v135
	v_bfe_u32 v149, v130, 6, 2
	v_lshlrev_b32_e32 v149, 5, v149
	v_bfe_u32 v135, v130, 4, 1
	v_lshl_add_u32 v149, v135, 4, v149
	v_bfe_u32 v135, v130, 5, 1
	v_lshl_add_u32 v149, v135, 3, v149
	v_lshrrev_b32_e64 v135, 1, s39
	v_add_u32_e32 v149, v135, v149
	v_lshl_add_u32 v132, v149, 1, v132
	s_waitcnt lgkmcnt(0)
	v_mul_f32_e32 v135, 0xbfb8aa3b, v150
	v_mul_f32_e32 v149, v150, v150
	ds_read_b32 v150, v133 offset:512
	v_mul_f32_e32 v124, v116, v124
	v_mul_f32_e32 v125, v117, v125
	v_mul_f32_e32 v116, v135, v116
	v_mul_f32_e32 v117, v135, v117
	v_exp_f32_e32 v116, v116
	v_exp_f32_e32 v117, v117
	v_add_f32_e32 v116, 1.0, v116
	v_add_f32_e32 v117, 1.0, v117
	v_rcp_f32_e32 v116, v116
	v_rcp_f32_e32 v117, v117
	v_mul_f32_e32 v116, v149, v116
	v_mul_f32_e32 v117, v149, v117
	v_mul_f32_e32 v124, v124, v116
	v_mul_f32_e32 v125, v125, v117
	v_cvt_pk_bf16_f32 v116, v124, v125
	v_mul_f32_e32 v126, v118, v126
	v_mul_f32_e32 v127, v119, v127
	v_mul_f32_e32 v118, v135, v118
	v_mul_f32_e32 v119, v135, v119
	v_exp_f32_e32 v118, v118
	v_exp_f32_e32 v119, v119
	v_add_f32_e32 v118, 1.0, v118
	v_add_f32_e32 v119, 1.0, v119
	v_rcp_f32_e32 v118, v118
	v_rcp_f32_e32 v119, v119
	v_mul_f32_e32 v118, v149, v118
	v_mul_f32_e32 v119, v149, v119
	v_mul_f32_e32 v126, v126, v118
	v_mul_f32_e32 v127, v127, v119
	v_cvt_pk_bf16_f32 v117, v126, v127
	v_mul_f32_e32 v120, v112, v120
	v_mul_f32_e32 v121, v113, v121
	v_mul_f32_e32 v112, v135, v112
	v_mul_f32_e32 v113, v135, v113
	v_exp_f32_e32 v112, v112
	v_exp_f32_e32 v113, v113
	v_add_f32_e32 v112, 1.0, v112
	v_add_f32_e32 v113, 1.0, v113
	v_rcp_f32_e32 v112, v112
	v_rcp_f32_e32 v113, v113
	v_mul_f32_e32 v112, v149, v112
	v_mul_f32_e32 v113, v149, v113
	v_mul_f32_e32 v120, v120, v112
	v_mul_f32_e32 v121, v121, v113
	v_cvt_pk_bf16_f32 v118, v120, v121
	v_mul_f32_e32 v122, v114, v122
	v_mul_f32_e32 v123, v115, v123
	v_mul_f32_e32 v114, v135, v114
	v_mul_f32_e32 v115, v135, v115
	v_exp_f32_e32 v114, v114
	v_exp_f32_e32 v115, v115
	v_add_f32_e32 v114, 1.0, v114
	v_add_f32_e32 v115, 1.0, v115
	v_rcp_f32_e32 v114, v114
	v_rcp_f32_e32 v115, v115
	v_mul_f32_e32 v114, v149, v114
	v_mul_f32_e32 v115, v149, v115
	v_mul_f32_e32 v122, v122, v114
	v_mul_f32_e32 v123, v123, v115
	v_cvt_pk_bf16_f32 v119, v122, v123
	s_nop 1
	v_permlane16_swap_b32_e32 v116, v118
	v_permlane16_swap_b32_e32 v117, v119
	global_store_dwordx4 v132, v[116:119], s[10:11]
	v_add_u32_e32 v134, 0x2b000, v132
	v_mul_f32_e32 v135, 0xbfb8aa3b, v151
	v_mul_f32_e32 v149, v151, v151
	ds_read_b32 v151, v133 offset:576
	v_mul_f32_e32 v108, v100, v108
	v_mul_f32_e32 v109, v101, v109
	v_mul_f32_e32 v100, v135, v100
	v_mul_f32_e32 v101, v135, v101
	v_exp_f32_e32 v100, v100
	v_exp_f32_e32 v101, v101
	v_add_f32_e32 v100, 1.0, v100
	v_add_f32_e32 v101, 1.0, v101
	v_rcp_f32_e32 v100, v100
	v_rcp_f32_e32 v101, v101
	v_mul_f32_e32 v100, v149, v100
	v_mul_f32_e32 v101, v149, v101
	v_mul_f32_e32 v108, v108, v100
	v_mul_f32_e32 v109, v109, v101
	v_cvt_pk_bf16_f32 v100, v108, v109
	v_mul_f32_e32 v110, v102, v110
	v_mul_f32_e32 v111, v103, v111
	v_mul_f32_e32 v102, v135, v102
	v_mul_f32_e32 v103, v135, v103
	v_exp_f32_e32 v102, v102
	v_exp_f32_e32 v103, v103
	v_add_f32_e32 v102, 1.0, v102
	v_add_f32_e32 v103, 1.0, v103
	v_rcp_f32_e32 v102, v102
	v_rcp_f32_e32 v103, v103
	v_mul_f32_e32 v102, v149, v102
	v_mul_f32_e32 v103, v149, v103
	v_mul_f32_e32 v110, v110, v102
	v_mul_f32_e32 v111, v111, v103
	v_cvt_pk_bf16_f32 v101, v110, v111
	v_mul_f32_e32 v104, v96, v104
	v_mul_f32_e32 v105, v97, v105
	v_mul_f32_e32 v96, v135, v96
	v_mul_f32_e32 v97, v135, v97
	v_exp_f32_e32 v96, v96
	v_exp_f32_e32 v97, v97
	v_add_f32_e32 v96, 1.0, v96
	v_add_f32_e32 v97, 1.0, v97
	v_rcp_f32_e32 v96, v96
	v_rcp_f32_e32 v97, v97
	v_mul_f32_e32 v96, v149, v96
	v_mul_f32_e32 v97, v149, v97
	v_mul_f32_e32 v104, v104, v96
	v_mul_f32_e32 v105, v105, v97
	v_cvt_pk_bf16_f32 v102, v104, v105
	v_mul_f32_e32 v106, v98, v106
	v_mul_f32_e32 v107, v99, v107
	v_mul_f32_e32 v98, v135, v98
	v_mul_f32_e32 v99, v135, v99
	v_exp_f32_e32 v98, v98
	v_exp_f32_e32 v99, v99
	v_add_f32_e32 v98, 1.0, v98
	v_add_f32_e32 v99, 1.0, v99
	v_rcp_f32_e32 v98, v98
	v_rcp_f32_e32 v99, v99
	v_mul_f32_e32 v98, v149, v98
	v_mul_f32_e32 v99, v149, v99
	v_mul_f32_e32 v106, v106, v98
	v_mul_f32_e32 v107, v107, v99
	v_cvt_pk_bf16_f32 v103, v106, v107
	s_nop 1
	v_permlane16_swap_b32_e32 v100, v102
	v_permlane16_swap_b32_e32 v101, v103
	global_store_dwordx4 v134, v[100:103], s[10:11]
	v_add_u32_e32 v134, 0x56000, v132
	v_mul_f32_e32 v135, 0xbfb8aa3b, v152
	v_mul_f32_e32 v149, v152, v152
	ds_read_b32 v152, v133 offset:640
	v_mul_f32_e32 v92, v84, v92
	v_mul_f32_e32 v93, v85, v93
	v_mul_f32_e32 v84, v135, v84
	v_mul_f32_e32 v85, v135, v85
	v_exp_f32_e32 v84, v84
	v_exp_f32_e32 v85, v85
	v_add_f32_e32 v84, 1.0, v84
	v_add_f32_e32 v85, 1.0, v85
	v_rcp_f32_e32 v84, v84
	v_rcp_f32_e32 v85, v85
	v_mul_f32_e32 v84, v149, v84
	v_mul_f32_e32 v85, v149, v85
	v_mul_f32_e32 v92, v92, v84
	v_mul_f32_e32 v93, v93, v85
	v_cvt_pk_bf16_f32 v84, v92, v93
	v_mul_f32_e32 v94, v86, v94
	v_mul_f32_e32 v95, v87, v95
	v_mul_f32_e32 v86, v135, v86
	v_mul_f32_e32 v87, v135, v87
	v_exp_f32_e32 v86, v86
	v_exp_f32_e32 v87, v87
	v_add_f32_e32 v86, 1.0, v86
	v_add_f32_e32 v87, 1.0, v87
; __device__ __forceinline__ u16 f2bf(float x) { return (u16)(cvtpk(x, x) & 0xffffu); }
; #define UNR _Pragma("unroll")
; template <int EPI, int lda, int ldb, int N, int K>
; __device__ __forceinline__ void gemm_phase(const u16* __restrict__ A, const u16* __restrict__ Bt, const GemmEpi ep, int wv) {
;     ...
;     if constexpr (EPI == EPI_SWIGLU) {
;       u16* out = reinterpret_cast<u16*>(ep.out0);
;       UNR for (int ai = 0; ai < 2; ++ai) UNR for (int m = 0; m < 4; ++m) {
;         const int rl0 = ai * HALF + wr * 64 + m * 16 + fq * 4;
;         const f32x4 r4 = *reinterpret_cast<const f32x4*>(lrs + rl0);
;         UNR for (int j = 0; j < 4; ++j) {
;           const int row = brow + rl0 + j;
;           const float rs = r4[j], ce = -1.4426950408889634f * rs, r2 = rs * rs;
;           UNR for (int n = 0; n < 2; ++n) {
;             const int col = (bcol >> 1) + wc * 32 + n * 16 + fr;
;             const float g = acc[ai][0][m][n][j], u = acc[ai][1][m][n][j];
;             const float sg = __builtin_amdgcn_rcpf(1.f + __builtin_amdgcn_exp2f(ce * g));
;             out[(size_t)row * ep.ldc + col] = f2bf((g * u) * (r2 * sg));
;           }
;         }
;       }
	v_rcp_f32_e32 v86, v86
	v_rcp_f32_e32 v87, v87
	v_mul_f32_e32 v86, v149, v86
	v_mul_f32_e32 v87, v149, v87
	v_mul_f32_e32 v94, v94, v86
	v_mul_f32_e32 v95, v95, v87
	v_cvt_pk_bf16_f32 v85, v94, v95
	v_mul_f32_e32 v88, v80, v88
	v_mul_f32_e32 v89, v81, v89
	v_mul_f32_e32 v80, v135, v80
	v_mul_f32_e32 v81, v135, v81
	v_exp_f32_e32 v80, v80
	v_exp_f32_e32 v81, v81
	v_add_f32_e32 v80, 1.0, v80
	v_add_f32_e32 v81, 1.0, v81
	v_rcp_f32_e32 v80, v80
	v_rcp_f32_e32 v81, v81
	v_mul_f32_e32 v80, v149, v80
	v_mul_f32_e32 v81, v149, v81
	v_mul_f32_e32 v88, v88, v80
	v_mul_f32_e32 v89, v89, v81
	v_cvt_pk_bf16_f32 v86, v88, v89
	v_mul_f32_e32 v90, v82, v90
	v_mul_f32_e32 v91, v83, v91
	v_mul_f32_e32 v82, v135, v82
	v_mul_f32_e32 v83, v135, v83
	v_exp_f32_e32 v82, v82
	v_exp_f32_e32 v83, v83
	v_add_f32_e32 v82, 1.0, v82
	v_add_f32_e32 v83, 1.0, v83
	v_rcp_f32_e32 v82, v82
	v_rcp_f32_e32 v83, v83
	v_mul_f32_e32 v82, v149, v82
	v_mul_f32_e32 v83, v149, v83
	v_mul_f32_e32 v90, v90, v82
	v_mul_f32_e32 v91, v91, v83
	v_cvt_pk_bf16_f32 v87, v90, v91
	s_nop 1
	v_permlane16_swap_b32_e32 v84, v86
	v_permlane16_swap_b32_e32 v85, v87
	global_store_dwordx4 v134, v[84:87], s[10:11]
	v_add_u32_e32 v134, 0x81000, v132
	v_mul_f32_e32 v135, 0xbfb8aa3b, v153
	v_mul_f32_e32 v149, v153, v153
	ds_read_b32 v153, v133 offset:704
	v_mul_f32_e32 v76, v68, v76
	v_mul_f32_e32 v77, v69, v77
	v_mul_f32_e32 v68, v135, v68
	v_mul_f32_e32 v69, v135, v69
	v_exp_f32_e32 v68, v68
	v_exp_f32_e32 v69, v69
	v_add_f32_e32 v68, 1.0, v68
	v_add_f32_e32 v69, 1.0, v69
	v_rcp_f32_e32 v68, v68
	v_rcp_f32_e32 v69, v69
	v_mul_f32_e32 v68, v149, v68
	v_mul_f32_e32 v69, v149, v69
	v_mul_f32_e32 v76, v76, v68
	v_mul_f32_e32 v77, v77, v69
	v_cvt_pk_bf16_f32 v68, v76, v77
	v_mul_f32_e32 v78, v70, v78
	v_mul_f32_e32 v79, v71, v79
	v_mul_f32_e32 v70, v135, v70
	v_mul_f32_e32 v71, v135, v71
	v_exp_f32_e32 v70, v70
	v_exp_f32_e32 v71, v71
	v_add_f32_e32 v70, 1.0, v70
	v_add_f32_e32 v71, 1.0, v71
	v_rcp_f32_e32 v70, v70
	v_rcp_f32_e32 v71, v71
	v_mul_f32_e32 v70, v149, v70
	v_mul_f32_e32 v71, v149, v71
	v_mul_f32_e32 v78, v78, v70
	v_mul_f32_e32 v79, v79, v71
	v_cvt_pk_bf16_f32 v69, v78, v79
	v_mul_f32_e32 v72, v64, v72
	v_mul_f32_e32 v73, v65, v73
	v_mul_f32_e32 v64, v135, v64
	v_mul_f32_e32 v65, v135, v65
	v_exp_f32_e32 v64, v64
	v_exp_f32_e32 v65, v65
	v_add_f32_e32 v64, 1.0, v64
	v_add_f32_e32 v65, 1.0, v65
	v_rcp_f32_e32 v64, v64
	v_rcp_f32_e32 v65, v65
	v_mul_f32_e32 v64, v149, v64
	v_mul_f32_e32 v65, v149, v65
	v_mul_f32_e32 v72, v72, v64
	v_mul_f32_e32 v73, v73, v65
	v_cvt_pk_bf16_f32 v70, v72, v73
	v_mul_f32_e32 v74, v66, v74
	v_mul_f32_e32 v75, v67, v75
	v_mul_f32_e32 v66, v135, v66
	v_mul_f32_e32 v67, v135, v67
	v_exp_f32_e32 v66, v66
	v_exp_f32_e32 v67, v67
	v_add_f32_e32 v66, 1.0, v66
	v_add_f32_e32 v67, 1.0, v67
	v_rcp_f32_e32 v66, v66
	v_rcp_f32_e32 v67, v67
	v_mul_f32_e32 v66, v149, v66
	v_mul_f32_e32 v67, v149, v67
	v_mul_f32_e32 v74, v74, v66
	v_mul_f32_e32 v75, v75, v67
	v_cvt_pk_bf16_f32 v71, v74, v75
	s_nop 1
	v_permlane16_swap_b32_e32 v68, v70
	v_permlane16_swap_b32_e32 v69, v71
	global_store_dwordx4 v134, v[68:71], s[10:11]
	s_waitcnt lgkmcnt(0)
	v_add_u32_e32 v134, 0x158000, v132
	v_mul_f32_e32 v135, 0xbfb8aa3b, v150
	v_mul_f32_e32 v149, v150, v150
	v_mul_f32_e32 v60, v52, v60
	v_mul_f32_e32 v61, v53, v61
	v_mul_f32_e32 v52, v135, v52
	v_mul_f32_e32 v53, v135, v53
	v_exp_f32_e32 v52, v52
	v_exp_f32_e32 v53, v53
	v_add_f32_e32 v52, 1.0, v52
	v_add_f32_e32 v53, 1.0, v53
	v_rcp_f32_e32 v52, v52
	v_rcp_f32_e32 v53, v53
	v_mul_f32_e32 v52, v149, v52
	v_mul_f32_e32 v53, v149, v53
	v_mul_f32_e32 v60, v60, v52
	v_mul_f32_e32 v61, v61, v53
	v_cvt_pk_bf16_f32 v52, v60, v61
	v_mul_f32_e32 v62, v54, v62
	v_mul_f32_e32 v63, v55, v63
	v_mul_f32_e32 v54, v135, v54
	v_mul_f32_e32 v55, v135, v55
	v_exp_f32_e32 v54, v54
	v_exp_f32_e32 v55, v55
	v_add_f32_e32 v54, 1.0, v54
	v_add_f32_e32 v55, 1.0, v55
	v_rcp_f32_e32 v54, v54
	v_rcp_f32_e32 v55, v55
	v_mul_f32_e32 v54, v149, v54
	v_mul_f32_e32 v55, v149, v55
	v_mul_f32_e32 v62, v62, v54
	v_mul_f32_e32 v63, v63, v55
	v_cvt_pk_bf16_f32 v53, v62, v63
	v_mul_f32_e32 v56, v48, v56
	v_mul_f32_e32 v57, v49, v57
	v_mul_f32_e32 v48, v135, v48
	v_mul_f32_e32 v49, v135, v49
	v_exp_f32_e32 v48, v48
	v_exp_f32_e32 v49, v49
	v_add_f32_e32 v48, 1.0, v48
	v_add_f32_e32 v49, 1.0, v49
	v_rcp_f32_e32 v48, v48
	v_rcp_f32_e32 v49, v49
	v_mul_f32_e32 v48, v149, v48
	v_mul_f32_e32 v49, v149, v49
	v_mul_f32_e32 v56, v56, v48
	v_mul_f32_e32 v57, v57, v49
	v_cvt_pk_bf16_f32 v54, v56, v57
	v_mul_f32_e32 v58, v50, v58
	v_mul_f32_e32 v59, v51, v59
	v_mul_f32_e32 v50, v135, v50
	v_mul_f32_e32 v51, v135, v51
	v_exp_f32_e32 v50, v50
	v_exp_f32_e32 v51, v51
	v_add_f32_e32 v50, 1.0, v50
	v_add_f32_e32 v51, 1.0, v51
	v_rcp_f32_e32 v50, v50
	v_rcp_f32_e32 v51, v51
	v_mul_f32_e32 v50, v149, v50
	v_mul_f32_e32 v51, v149, v51
	v_mul_f32_e32 v58, v58, v50
	v_mul_f32_e32 v59, v59, v51
	v_cvt_pk_bf16_f32 v55, v58, v59
	s_nop 1
	v_permlane16_swap_b32_e32 v52, v54
	v_permlane16_swap_b32_e32 v53, v55
	global_store_dwordx4 v134, v[52:55], s[10:11]
	v_add_u32_e32 v134, 0x183000, v132
	v_mul_f32_e32 v135, 0xbfb8aa3b, v151
	v_mul_f32_e32 v149, v151, v151
	v_mul_f32_e32 v44, v36, v44
	v_mul_f32_e32 v45, v37, v45
	v_mul_f32_e32 v36, v135, v36
	v_mul_f32_e32 v37, v135, v37
	v_exp_f32_e32 v36, v36
	v_exp_f32_e32 v37, v37
	v_add_f32_e32 v36, 1.0, v36
	v_add_f32_e32 v37, 1.0, v37
	v_rcp_f32_e32 v36, v36
	v_rcp_f32_e32 v37, v37
	v_mul_f32_e32 v36, v149, v36
	v_mul_f32_e32 v37, v149, v37
	v_mul_f32_e32 v44, v44, v36
	v_mul_f32_e32 v45, v45, v37
	v_cvt_pk_bf16_f32 v36, v44, v45
	v_mul_f32_e32 v46, v38, v46
; __device__ __forceinline__ u16 f2bf(float x) { return (u16)(cvtpk(x, x) & 0xffffu); }
; #define UNR _Pragma("unroll")
; #define WAIT_V(n) asm volatile("s_waitcnt vmcnt(" #n ")" ::: "memory")
; template <int EPI, int lda, int ldb, int N, int K>
; __device__ __forceinline__ void gemm_phase(const u16* __restrict__ A, const u16* __restrict__ Bt, const GemmEpi ep, int wv) {
;     ...
;     if constexpr (EPI == EPI_SWIGLU) {
;       u16* out = reinterpret_cast<u16*>(ep.out0);
;       UNR for (int ai = 0; ai < 2; ++ai) UNR for (int m = 0; m < 4; ++m) {
;         const int rl0 = ai * HALF + wr * 64 + m * 16 + fq * 4;
;         const f32x4 r4 = *reinterpret_cast<const f32x4*>(lrs + rl0);
;         UNR for (int j = 0; j < 4; ++j) {
;           const int row = brow + rl0 + j;
;           const float rs = r4[j], ce = -1.4426950408889634f * rs, r2 = rs * rs;
;           UNR for (int n = 0; n < 2; ++n) {
;             const int col = (bcol >> 1) + wc * 32 + n * 16 + fr;
;             const float g = acc[ai][0][m][n][j], u = acc[ai][1][m][n][j];
;             const float sg = __builtin_amdgcn_rcpf(1.f + __builtin_amdgcn_exp2f(ce * g));
;             out[(size_t)row * ep.ldc + col] = f2bf((g * u) * (r2 * sg));
;           }
;         }
;       }
;     ...
;     if constexpr (PF) {
;       WAIT_V(0);
;       __syncthreads();
;       if constexpr (CONS) { if (more && tidx < 256) { float sq = 0.f; UNR for (int pp = 0; pp < 8; ++pp) sq += nss[pp];
;         lrs[tidx] = rsqrtf(sq * (1.f / DM) + 1e-6f); } }
;       if (!more) break;
	v_mul_f32_e32 v47, v39, v47
	v_mul_f32_e32 v38, v135, v38
	v_mul_f32_e32 v39, v135, v39
	v_exp_f32_e32 v38, v38
	v_exp_f32_e32 v39, v39
	v_add_f32_e32 v38, 1.0, v38
	v_add_f32_e32 v39, 1.0, v39
	v_rcp_f32_e32 v38, v38
	v_rcp_f32_e32 v39, v39
	v_mul_f32_e32 v38, v149, v38
	v_mul_f32_e32 v39, v149, v39
	v_mul_f32_e32 v46, v46, v38
	v_mul_f32_e32 v47, v47, v39
	v_cvt_pk_bf16_f32 v37, v46, v47
	v_mul_f32_e32 v40, v32, v40
	v_mul_f32_e32 v41, v33, v41
	v_mul_f32_e32 v32, v135, v32
	v_mul_f32_e32 v33, v135, v33
	v_exp_f32_e32 v32, v32
	v_exp_f32_e32 v33, v33
	v_add_f32_e32 v32, 1.0, v32
	v_add_f32_e32 v33, 1.0, v33
	v_rcp_f32_e32 v32, v32
	v_rcp_f32_e32 v33, v33
	v_mul_f32_e32 v32, v149, v32
	v_mul_f32_e32 v33, v149, v33
	v_mul_f32_e32 v40, v40, v32
	v_mul_f32_e32 v41, v41, v33
	v_cvt_pk_bf16_f32 v38, v40, v41
	v_mul_f32_e32 v42, v34, v42
	v_mul_f32_e32 v43, v35, v43
	v_mul_f32_e32 v34, v135, v34
	v_mul_f32_e32 v35, v135, v35
	v_exp_f32_e32 v34, v34
	v_exp_f32_e32 v35, v35
	v_add_f32_e32 v34, 1.0, v34
	v_add_f32_e32 v35, 1.0, v35
	v_rcp_f32_e32 v34, v34
	v_rcp_f32_e32 v35, v35
	v_mul_f32_e32 v34, v149, v34
	v_mul_f32_e32 v35, v149, v35
	v_mul_f32_e32 v42, v42, v34
	v_mul_f32_e32 v43, v43, v35
	v_cvt_pk_bf16_f32 v39, v42, v43
	s_nop 1
	v_permlane16_swap_b32_e32 v36, v38
	v_permlane16_swap_b32_e32 v37, v39
	global_store_dwordx4 v134, v[36:39], s[10:11]
	v_add_u32_e32 v134, 0x1ae000, v132
	v_mul_f32_e32 v135, 0xbfb8aa3b, v152
	v_mul_f32_e32 v149, v152, v152
	v_mul_f32_e32 v28, v20, v28
	v_mul_f32_e32 v29, v21, v29
	v_mul_f32_e32 v20, v135, v20
	v_mul_f32_e32 v21, v135, v21
	v_exp_f32_e32 v20, v20
	v_exp_f32_e32 v21, v21
	v_add_f32_e32 v20, 1.0, v20
	v_add_f32_e32 v21, 1.0, v21
	v_rcp_f32_e32 v20, v20
	v_rcp_f32_e32 v21, v21
	v_mul_f32_e32 v20, v149, v20
	v_mul_f32_e32 v21, v149, v21
	v_mul_f32_e32 v28, v28, v20
	v_mul_f32_e32 v29, v29, v21
	v_cvt_pk_bf16_f32 v20, v28, v29
	v_mul_f32_e32 v30, v22, v30
	v_mul_f32_e32 v31, v23, v31
	v_mul_f32_e32 v22, v135, v22
	v_mul_f32_e32 v23, v135, v23
	v_exp_f32_e32 v22, v22
	v_exp_f32_e32 v23, v23
	v_add_f32_e32 v22, 1.0, v22
	v_add_f32_e32 v23, 1.0, v23
	v_rcp_f32_e32 v22, v22
	v_rcp_f32_e32 v23, v23
	v_mul_f32_e32 v22, v149, v22
	v_mul_f32_e32 v23, v149, v23
	v_mul_f32_e32 v30, v30, v22
	v_mul_f32_e32 v31, v31, v23
	v_cvt_pk_bf16_f32 v21, v30, v31
	v_mul_f32_e32 v24, v16, v24
	v_mul_f32_e32 v25, v17, v25
	v_mul_f32_e32 v16, v135, v16
	v_mul_f32_e32 v17, v135, v17
	v_exp_f32_e32 v16, v16
	v_exp_f32_e32 v17, v17
	v_add_f32_e32 v16, 1.0, v16
	v_add_f32_e32 v17, 1.0, v17
	v_rcp_f32_e32 v16, v16
	v_rcp_f32_e32 v17, v17
	v_mul_f32_e32 v16, v149, v16
	v_mul_f32_e32 v17, v149, v17
	v_mul_f32_e32 v24, v24, v16
	v_mul_f32_e32 v25, v25, v17
	v_cvt_pk_bf16_f32 v22, v24, v25
	v_mul_f32_e32 v26, v18, v26
	v_mul_f32_e32 v27, v19, v27
	v_mul_f32_e32 v18, v135, v18
	v_mul_f32_e32 v19, v135, v19
	v_exp_f32_e32 v18, v18
	v_exp_f32_e32 v19, v19
	v_add_f32_e32 v18, 1.0, v18
	v_add_f32_e32 v19, 1.0, v19
	v_rcp_f32_e32 v18, v18
	v_rcp_f32_e32 v19, v19
	v_mul_f32_e32 v18, v149, v18
	v_mul_f32_e32 v19, v149, v19
	v_mul_f32_e32 v26, v26, v18
	v_mul_f32_e32 v27, v27, v19
	v_cvt_pk_bf16_f32 v23, v26, v27
	s_nop 1
	v_permlane16_swap_b32_e32 v20, v22
	v_permlane16_swap_b32_e32 v21, v23
	global_store_dwordx4 v134, v[20:23], s[10:11]
	v_add_u32_e32 v134, 0x1d9000, v132
	v_mul_f32_e32 v135, 0xbfb8aa3b, v153
	v_mul_f32_e32 v149, v153, v153
	v_mul_f32_e32 v12, v4, v12
	v_mul_f32_e32 v13, v5, v13
	v_mul_f32_e32 v4, v135, v4
	v_mul_f32_e32 v5, v135, v5
	v_exp_f32_e32 v4, v4
	v_exp_f32_e32 v5, v5
	v_add_f32_e32 v4, 1.0, v4
	v_add_f32_e32 v5, 1.0, v5
	v_rcp_f32_e32 v4, v4
	v_rcp_f32_e32 v5, v5
	v_mul_f32_e32 v4, v149, v4
	v_mul_f32_e32 v5, v149, v5
	v_mul_f32_e32 v12, v12, v4
	v_mul_f32_e32 v13, v13, v5
	v_cvt_pk_bf16_f32 v4, v12, v13
	v_mul_f32_e32 v14, v6, v14
	v_mul_f32_e32 v15, v7, v15
	v_mul_f32_e32 v6, v135, v6
	v_mul_f32_e32 v7, v135, v7
	v_exp_f32_e32 v6, v6
	v_exp_f32_e32 v7, v7
	v_add_f32_e32 v6, 1.0, v6
	v_add_f32_e32 v7, 1.0, v7
	v_rcp_f32_e32 v6, v6
	v_rcp_f32_e32 v7, v7
	v_mul_f32_e32 v6, v149, v6
	v_mul_f32_e32 v7, v149, v7
	v_mul_f32_e32 v14, v14, v6
	v_mul_f32_e32 v15, v15, v7
	v_cvt_pk_bf16_f32 v5, v14, v15
	v_mul_f32_e32 v8, v0, v8
	v_mul_f32_e32 v9, v1, v9
	v_mul_f32_e32 v0, v135, v0
	v_mul_f32_e32 v1, v135, v1
	v_exp_f32_e32 v0, v0
	v_exp_f32_e32 v1, v1
	v_add_f32_e32 v0, 1.0, v0
	v_add_f32_e32 v1, 1.0, v1
	v_rcp_f32_e32 v0, v0
	v_rcp_f32_e32 v1, v1
	v_mul_f32_e32 v0, v149, v0
	v_mul_f32_e32 v1, v149, v1
	v_mul_f32_e32 v8, v8, v0
	v_mul_f32_e32 v9, v9, v1
	v_cvt_pk_bf16_f32 v6, v8, v9
	v_mul_f32_e32 v10, v2, v10
	v_mul_f32_e32 v11, v3, v11
	v_mul_f32_e32 v2, v135, v2
	v_mul_f32_e32 v3, v135, v3
	v_exp_f32_e32 v2, v2
	v_exp_f32_e32 v3, v3
	v_add_f32_e32 v2, 1.0, v2
	v_add_f32_e32 v3, 1.0, v3
	v_rcp_f32_e32 v2, v2
	v_rcp_f32_e32 v3, v3
	v_mul_f32_e32 v2, v149, v2
	v_mul_f32_e32 v3, v149, v3
	v_mul_f32_e32 v10, v10, v2
	v_mul_f32_e32 v11, v11, v3
	v_cvt_pk_bf16_f32 v7, v10, v11
	s_nop 1
	v_permlane16_swap_b32_e32 v4, v6
	v_permlane16_swap_b32_e32 v5, v7
	global_store_dwordx4 v134, v[4:7], s[10:11]
	s_waitcnt vmcnt(0)
	s_waitcnt vmcnt(0)
	v_add_f32_e32 v148, 0, v131
	s_barrier
	s_and_saveexec_b64 s[38:39], s[44:45]
	s_cbranch_execz .LBB0_1560
	v_add_f32_e32 v0, v141, v148
	v_add_f32_e32 v0, v140, v0
	v_add_f32_e32 v0, v139, v0
	v_add_f32_e32 v0, v138, v0
	v_add_f32_e32 v0, v137, v0
	v_add_f32_e32 v0, v136, v0
	v_add_f32_e32 v0, v128, v0
	v_fmamk_f32 v0, v0, 0x3a000000, v143
	v_mul_f32_e32 v1, 0x4b800000, v0
	v_cmp_gt_f32_e32 vcc, s61, v0
	s_nop 1
	v_cndmask_b32_e32 v0, v0, v1, vcc
	v_rsq_f32_e32 v0, v0
	v_lshl_add_u32 v1, v130, 2, 0
	v_add_u32_e32 v1, 0x20000, v1
	v_mul_f32_e32 v2, 0x45800000, v0
	v_cndmask_b32_e32 v0, v0, v2, vcc
	ds_write_b32 v1, v0
	s_branch .LBB0_1560
